# strategy 7.4: one static s_setprio 1 for waves 4-7 before each GEMM K-loop, per-cluster flips deleted, reset after the loop
# speedup vs baseline: 1.0009x; 1.0009x over previous
; #define PG8_STAGE(bufoff, gbase, voff) do { _Pragma("unroll") for (int _i = 0; _i < 2; ++_i) \
;         __builtin_amdgcn_global_load_lds((const unsigned*)((const char*)(gbase) + (voff)[_i]), (LAS unsigned*)(lds + (bufoff) + ldsw + _i * 8192), 16, 0, 0); } while (0)
; #define PG8_LDA(dst, b, h) do { _Pragma("unroll") for (int m = 0; m < 4; ++m) _Pragma("unroll") for (int k = 0; k < 2; ++k) dst[m][k] = *(const LAS h16x8*)(lds + PG8_SA(b, h) + aoff + m * 2048 + k * 1024); } while (0)
; #define PG8_LDB(dst, b, h) do { _Pragma("unroll") for (int n = 0; n < 2; ++n) _Pragma("unroll") for (int k = 0; k < 2; ++k) dst[n][k] = *(const LAS h16x8*)(lds + PG8_SB(b, h) + boff + n * 2048 + k * 1024); } while (0)
; #define PG8_MMA(ai, bj, At, Bt) do { __builtin_amdgcn_s_setprio(1); _Pragma("unroll") for (int m = 0; m < 4; ++m) _Pragma("unroll") for (int n = 0; n < 2; ++n) _Pragma("unroll") for (int k = 0; k < 2; ++k) \
;         acc[ai][bj][m][n] = __builtin_amdgcn_mfma_f32_16x16x32_f16(Bt[n][k], At[m][k], acc[ai][bj][m][n], 0, 0, 0); __builtin_amdgcn_s_setprio(0); } while (0)
; #define PG8_WAIT_V(n) asm volatile("s_waitcnt vmcnt(" #n ")" ::: "memory")
; #define PG8_WAIT_L(n) asm volatile("s_waitcnt lgkmcnt(" #n ")" ::: "memory")
; #define PG8_BAR __builtin_amdgcn_s_barrier()
; template <class Epi>
; __device__ __forceinline__ void gemm_phase(LAS unsigned char* lds, const Gemm g, const StaticOrder& S, const Epi& E) {
;     ...
;         for (int t = 0; t < nt; t += 2) {
;             const bool last = (t == nt - 2);
;             const char* a1 = cA + (size_t)(t + 1) * kstep;
;             const char* a2 = last ? nA : cA + (size_t)(t + 2) * kstep; const char* b2 = last ? nB : cB + (size_t)(t + 2) * kstep;
;             const char* a3 = a2 + kstep; const char* b3 = b2 + kstep;
;             PG8_LDB(B0, 0, 0); PG8_LDB(B1, 0, 1); PG8_SCHED; PG8_LDA(At, 0, 0); PG8_STAGE(PG8_SA(1, 1), a1 + hstepA, voffA);
;             PG8_WAIT_V(8); PG8_WAIT_L(0); PG8_BAR; PG8_MMA(0, 0, At, B0); PG8_MMA(0, 1, At, B1); PG8_BAR; PG8_SCHED;
;     ...
; #pragma unroll
;         for (int a = 0; a < 2; ++a)
; #pragma unroll
;             for (int b = 0; b < 2; ++b)
; #pragma unroll
;                 for (int m = 0; m < 4; ++m)
; #pragma unroll
;                     for (int n = 0; n < 2; ++n) acc[a][b][m][n] = (f32x4){0.f, 0.f, 0.f, 0.f};
;         cur = nxt; cA = nA; cB = nB; ++ui;
.LBB0_139:
	s_add_u32 s93, s6, 0x100
	s_addc_u32 s94, s7, 0
	v_readlane_b32 s36, v254, 43
	s_add_u32 s6, s22, 0x80
	v_mov_b32_e32 v0, 0
	v_readlane_b32 s44, v254, 51
	v_readlane_b32 s45, v254, 52
	s_addc_u32 s7, s23, 0
	s_mov_b32 s22, 0
	v_mov_b32_e32 v1, v0
	v_mov_b32_e32 v2, v0
	v_mov_b32_e32 v3, v0
	v_mov_b32_e32 v4, v0
	v_mov_b32_e32 v5, v0
	v_mov_b32_e32 v6, v0
	v_mov_b32_e32 v7, v0
	v_mov_b32_e32 v16, v0
	v_mov_b32_e32 v17, v0
	v_mov_b32_e32 v18, v0
	v_mov_b32_e32 v19, v0
	v_mov_b32_e32 v20, v0
	v_mov_b32_e32 v21, v0
	v_mov_b32_e32 v22, v0
	v_mov_b32_e32 v23, v0
	v_mov_b32_e32 v34, v0
	v_mov_b32_e32 v35, v0
	v_mov_b32_e32 v36, v0
	v_mov_b32_e32 v37, v0
	v_mov_b32_e32 v38, v0
	v_mov_b32_e32 v39, v0
	v_mov_b32_e32 v40, v0
	v_mov_b32_e32 v41, v0
	v_mov_b32_e32 v50, v0
	v_mov_b32_e32 v51, v0
	v_mov_b32_e32 v52, v0
	v_mov_b32_e32 v53, v0
	v_mov_b32_e32 v54, v0
	v_mov_b32_e32 v55, v0
	v_mov_b32_e32 v56, v0
	v_mov_b32_e32 v57, v0
	v_mov_b32_e32 v8, v0
	v_mov_b32_e32 v9, v0
	v_mov_b32_e32 v10, v0
	v_mov_b32_e32 v11, v0
	v_mov_b32_e32 v12, v0
	v_mov_b32_e32 v13, v0
	v_mov_b32_e32 v14, v0
	v_mov_b32_e32 v15, v0
	v_mov_b32_e32 v24, v0
	v_mov_b32_e32 v25, v0
	v_mov_b32_e32 v26, v0
	v_mov_b32_e32 v27, v0
	v_mov_b32_e32 v28, v0
	v_mov_b32_e32 v29, v0
	v_mov_b32_e32 v30, v0
	v_mov_b32_e32 v31, v0
	v_mov_b32_e32 v42, v0
	v_mov_b32_e32 v43, v0
	v_mov_b32_e32 v44, v0
	v_mov_b32_e32 v45, v0
	v_mov_b32_e32 v46, v0
	v_mov_b32_e32 v47, v0
	v_mov_b32_e32 v48, v0
	v_mov_b32_e32 v49, v0
	v_mov_b32_e32 v58, v0
	v_mov_b32_e32 v59, v0
	v_mov_b32_e32 v60, v0
	v_mov_b32_e32 v61, v0
	v_mov_b32_e32 v62, v0
	v_mov_b32_e32 v63, v0
	v_mov_b32_e32 v64, v0
	v_mov_b32_e32 v65, v0
	v_mov_b32_e32 v66, v0
	v_mov_b32_e32 v67, v0
	v_mov_b32_e32 v68, v0
	v_mov_b32_e32 v69, v0
	v_mov_b32_e32 v70, v0
	v_mov_b32_e32 v71, v0
	v_mov_b32_e32 v72, v0
	v_mov_b32_e32 v73, v0
	v_mov_b32_e32 v82, v0
	v_mov_b32_e32 v83, v0
	v_mov_b32_e32 v84, v0
	v_mov_b32_e32 v85, v0
	v_mov_b32_e32 v86, v0
	v_mov_b32_e32 v87, v0
	v_mov_b32_e32 v88, v0
	v_mov_b32_e32 v89, v0
	v_mov_b32_e32 v98, v0
	v_mov_b32_e32 v99, v0
	v_mov_b32_e32 v100, v0
	v_mov_b32_e32 v101, v0
	v_mov_b32_e32 v102, v0
	v_mov_b32_e32 v103, v0
	v_mov_b32_e32 v104, v0
	v_mov_b32_e32 v105, v0
	v_mov_b32_e32 v114, v0
	v_mov_b32_e32 v115, v0
	v_mov_b32_e32 v116, v0
	v_mov_b32_e32 v117, v0
	v_mov_b32_e32 v118, v0
	v_mov_b32_e32 v119, v0
	v_mov_b32_e32 v120, v0
	v_mov_b32_e32 v121, v0
	v_mov_b32_e32 v74, v0
	v_mov_b32_e32 v75, v0
	v_mov_b32_e32 v76, v0
	v_mov_b32_e32 v77, v0
	v_mov_b32_e32 v78, v0
	v_mov_b32_e32 v79, v0
	v_mov_b32_e32 v80, v0
	v_mov_b32_e32 v81, v0
	v_mov_b32_e32 v90, v0
	v_mov_b32_e32 v91, v0
	v_mov_b32_e32 v92, v0
	v_mov_b32_e32 v93, v0
	v_mov_b32_e32 v94, v0
	v_mov_b32_e32 v95, v0
	v_mov_b32_e32 v96, v0
	v_mov_b32_e32 v97, v0
	v_mov_b32_e32 v106, v0
	v_mov_b32_e32 v107, v0
	v_mov_b32_e32 v108, v0
	v_mov_b32_e32 v109, v0
	v_mov_b32_e32 v110, v0
	v_mov_b32_e32 v111, v0
	v_mov_b32_e32 v112, v0
	v_mov_b32_e32 v113, v0
	v_mov_b32_e32 v122, v0
	v_mov_b32_e32 v123, v0
	v_mov_b32_e32 v124, v0
	v_mov_b32_e32 v125, v0
	v_mov_b32_e32 v126, v0
	v_mov_b32_e32 v127, v0
	v_mov_b32_e32 v128, v0
	v_mov_b32_e32 v129, v0
	s_mov_b64 s[24:25], s[44:45]
	v_readlane_b32 s37, v254, 44
	v_readlane_b32 s38, v254, 45
	v_readlane_b32 s39, v254, 46
	v_readlane_b32 s40, v254, 47
	v_readlane_b32 s41, v254, 48
	v_readlane_b32 s42, v254, 49
	v_readlane_b32 s43, v254, 50
	v_readlane_b32 s46, v254, 53
	v_readlane_b32 s47, v254, 54
	v_readlane_b32 s48, v254, 55
	v_readlane_b32 s49, v254, 56
	v_readlane_b32 s50, v254, 57
	v_readlane_b32 s51, v254, 58
	s_cmp_eq_u64 s[18:19], 0
	s_cbranch_scc0 .Lprio_140
	s_setprio 1
.Lprio_140:
.LBB0_140:
	s_add_i32 s95, s22, 2
	s_add_u32 s96, s6, 0x80
	s_addc_u32 s23, s7, 0
	s_add_i32 vcc_lo, 0, 0x10000
	s_cmp_eq_u32 s79, s22
	s_cselect_b32 s23, s1, s23
	s_cselect_b32 s22, s0, s96
	v_add_u32_e32 v32, vcc_lo, v156
	s_cselect_b32 s97, s21, s94
	s_cselect_b32 s96, s20, s93
	s_add_i32 vcc_hi, 0, 0x14000
	ds_read_b128 v[130:133], v32
	ds_read_b128 v[134:137], v32 offset:1024
	ds_read_b128 v[150:153], v32 offset:2048
	ds_read_b128 v[160:163], v32 offset:3072
	v_add_u32_e32 v32, vcc_hi, v156
	ds_read_b128 v[164:167], v32
	ds_read_b128 v[168:171], v32 offset:1024
	ds_read_b128 v[172:175], v32 offset:2048
	ds_read_b128 v[176:179], v32 offset:3072
	v_lshl_add_u64 v[154:155], s[6:7], 0, v[148:149]
	s_add_i32 m0, s71, 0xc000
	ds_read_b128 v[196:199], v159
	ds_read_b128 v[204:207], v159 offset:1024
	ds_read_b128 v[208:211], v159 offset:2048
	ds_read_b128 v[212:215], v159 offset:3072
	ds_read_b128 v[216:219], v159 offset:4096
	ds_read_b128 v[220:223], v159 offset:5120
	ds_read_b128 v[224:227], v159 offset:6144
	ds_read_b128 v[228:231], v159 offset:7168
	global_load_lds_dwordx4 v[154:155], off
	v_lshl_add_u64 v[154:155], s[6:7], 0, v[146:147]
	s_add_i32 m0, s71, 0xe000
	s_nop 0
	global_load_lds_dwordx4 v[154:155], off
	s_waitcnt vmcnt(8)
	s_waitcnt lgkmcnt(0)
	s_barrier
; #define PG8_STAGE(bufoff, gbase, voff) do { _Pragma("unroll") for (int _i = 0; _i < 2; ++_i) \
;         __builtin_amdgcn_global_load_lds((const unsigned*)((const char*)(gbase) + (voff)[_i]), (LAS unsigned*)(lds + (bufoff) + ldsw + _i * 8192), 16, 0, 0); } while (0)
; #define PG8_LDA(dst, b, h) do { _Pragma("unroll") for (int m = 0; m < 4; ++m) _Pragma("unroll") for (int k = 0; k < 2; ++k) dst[m][k] = *(const LAS h16x8*)(lds + PG8_SA(b, h) + aoff + m * 2048 + k * 1024); } while (0)
; #define PG8_MMA(ai, bj, At, Bt) do { __builtin_amdgcn_s_setprio(1); _Pragma("unroll") for (int m = 0; m < 4; ++m) _Pragma("unroll") for (int n = 0; n < 2; ++n) _Pragma("unroll") for (int k = 0; k < 2; ++k) \
;         acc[ai][bj][m][n] = __builtin_amdgcn_mfma_f32_16x16x32_f16(Bt[n][k], At[m][k], acc[ai][bj][m][n], 0, 0, 0); __builtin_amdgcn_s_setprio(0); } while (0)
; #define PG8_WAIT_V(n) asm volatile("s_waitcnt vmcnt(" #n ")" ::: "memory")
; #define PG8_WAIT_L(n) asm volatile("s_waitcnt lgkmcnt(" #n ")" ::: "memory")
; #define PG8_BAR __builtin_amdgcn_s_barrier()
; #define PG8_SCHED __builtin_amdgcn_sched_barrier(0)
; template <class Epi>
; __device__ __forceinline__ void gemm_phase(LAS unsigned char* lds, const Gemm g, const StaticOrder& S, const Epi& E) {
;     ...
;             PG8_WAIT_V(8); PG8_WAIT_L(0); PG8_BAR; PG8_MMA(0, 0, At, B0); PG8_MMA(0, 1, At, B1); PG8_BAR; PG8_SCHED;
;             PG8_LDA(At, 0, 1); PG8_STAGE(PG8_SB(0, 0), b2, voffB); PG8_STAGE(PG8_SB(0, 1), b2 + hstepB, voffB); PG8_STAGE(PG8_SA(0, 0), a2, voffA);
;             PG8_WAIT_V(8); PG8_WAIT_L(0); PG8_BAR; PG8_MMA(1, 0, At, B0); PG8_MMA(1, 1, At, B1); PG8_BAR; PG8_SCHED;
	s_waitcnt lgkmcnt(0)
	v_mfma_f32_16x16x32_f16 v[126:129], v[130:133], v[196:199], v[126:129]
	v_mfma_f32_16x16x32_f16 v[122:125], v[150:153], v[196:199], v[122:125]
	v_mfma_f32_16x16x32_f16 v[110:113], v[130:133], v[208:211], v[110:113]
	v_mfma_f32_16x16x32_f16 v[106:109], v[150:153], v[208:211], v[106:109]
	v_mfma_f32_16x16x32_f16 v[94:97], v[130:133], v[216:219], v[94:97]
	v_mfma_f32_16x16x32_f16 v[90:93], v[150:153], v[216:219], v[90:93]
	v_mfma_f32_16x16x32_f16 v[78:81], v[130:133], v[224:227], v[78:81]
	v_mfma_f32_16x16x32_f16 v[74:77], v[150:153], v[224:227], v[74:77]
	v_mfma_f32_16x16x32_f16 v[126:129], v[134:137], v[204:207], v[126:129]
	v_mfma_f32_16x16x32_f16 v[122:125], v[160:163], v[204:207], v[122:125]
	v_mfma_f32_16x16x32_f16 v[110:113], v[134:137], v[212:215], v[110:113]
	v_mfma_f32_16x16x32_f16 v[106:109], v[160:163], v[212:215], v[106:109]
	v_mfma_f32_16x16x32_f16 v[94:97], v[134:137], v[220:223], v[94:97]
	v_mfma_f32_16x16x32_f16 v[90:93], v[160:163], v[220:223], v[90:93]
	v_mfma_f32_16x16x32_f16 v[78:81], v[134:137], v[228:231], v[78:81]
	v_mfma_f32_16x16x32_f16 v[74:77], v[160:163], v[228:231], v[74:77]
	v_mfma_f32_16x16x32_f16 v[118:121], v[164:167], v[196:199], v[118:121]
	v_mfma_f32_16x16x32_f16 v[114:117], v[172:175], v[196:199], v[114:117]
	v_mfma_f32_16x16x32_f16 v[102:105], v[164:167], v[208:211], v[102:105]
	v_mfma_f32_16x16x32_f16 v[98:101], v[172:175], v[208:211], v[98:101]
	v_mfma_f32_16x16x32_f16 v[86:89], v[164:167], v[216:219], v[86:89]
	v_mfma_f32_16x16x32_f16 v[82:85], v[172:175], v[216:219], v[82:85]
	v_mfma_f32_16x16x32_f16 v[70:73], v[164:167], v[224:227], v[70:73]
	v_mfma_f32_16x16x32_f16 v[66:69], v[172:175], v[224:227], v[66:69]
	v_mfma_f32_16x16x32_f16 v[118:121], v[168:171], v[204:207], v[118:121]
	v_mfma_f32_16x16x32_f16 v[114:117], v[176:179], v[204:207], v[114:117]
	v_mfma_f32_16x16x32_f16 v[102:105], v[168:171], v[212:215], v[102:105]
	v_mfma_f32_16x16x32_f16 v[98:101], v[176:179], v[212:215], v[98:101]
	v_mfma_f32_16x16x32_f16 v[86:89], v[168:171], v[220:223], v[86:89]
	v_mfma_f32_16x16x32_f16 v[82:85], v[176:179], v[220:223], v[82:85]
	v_mfma_f32_16x16x32_f16 v[70:73], v[168:171], v[228:231], v[70:73]
	v_mfma_f32_16x16x32_f16 v[66:69], v[176:179], v[228:231], v[66:69]
	s_barrier
	s_add_i32 vcc_lo, vcc_lo, s70
	v_lshl_add_u64 v[154:155], s[96:97], 0, v[142:143]
	s_mov_b32 m0, vcc_lo
	ds_read_b128 v[196:199], v159 offset:16384
	ds_read_b128 v[204:207], v159 offset:17408
	ds_read_b128 v[208:211], v159 offset:18432
	ds_read_b128 v[212:215], v159 offset:19456
	ds_read_b128 v[216:219], v159 offset:20480
	ds_read_b128 v[220:223], v159 offset:21504
	ds_read_b128 v[224:227], v159 offset:22528
	ds_read_b128 v[228:231], v159 offset:23552
	global_load_lds_dwordx4 v[154:155], off
	s_add_i32 m0, vcc_lo, 0x2000
	v_lshl_add_u64 v[180:181], s[96:97], 0, v[138:139]
	s_add_u32 s96, s96, s55
	s_addc_u32 s97, s97, 0
	s_add_i32 vcc_lo, vcc_hi, s70
	global_load_lds_dwordx4 v[180:181], off
	v_lshl_add_u64 v[190:191], s[96:97], 0, v[142:143]
	s_mov_b32 m0, vcc_lo
	v_lshl_add_u64 v[232:233], s[96:97], 0, v[138:139]
	global_load_lds_dwordx4 v[190:191], off
	s_add_i32 m0, vcc_lo, 0x2000
	v_lshl_add_u64 v[234:235], s[22:23], 0, v[144:145]
	global_load_lds_dwordx4 v[232:233], off
	s_mov_b32 m0, s71
	v_lshl_add_u64 v[236:237], s[22:23], 0, v[140:141]
	global_load_lds_dwordx4 v[234:235], off
	s_mov_b32 m0, s72
	s_nop 0
	global_load_lds_dwordx4 v[236:237], off
	s_waitcnt vmcnt(8)
	s_waitcnt lgkmcnt(0)
	s_barrier
	s_waitcnt lgkmcnt(0)
	v_mfma_f32_16x16x32_f16 v[62:65], v[130:133], v[196:199], v[62:65]
	v_mfma_f32_16x16x32_f16 v[58:61], v[150:153], v[196:199], v[58:61]
	v_mfma_f32_16x16x32_f16 v[46:49], v[130:133], v[208:211], v[46:49]
	v_mfma_f32_16x16x32_f16 v[42:45], v[150:153], v[208:211], v[42:45]
	v_mfma_f32_16x16x32_f16 v[28:31], v[130:133], v[216:219], v[28:31]
	v_mfma_f32_16x16x32_f16 v[24:27], v[150:153], v[216:219], v[24:27]
	v_mfma_f32_16x16x32_f16 v[12:15], v[130:133], v[224:227], v[12:15]
	v_mfma_f32_16x16x32_f16 v[8:11], v[150:153], v[224:227], v[8:11]
	v_mfma_f32_16x16x32_f16 v[62:65], v[134:137], v[204:207], v[62:65]
	v_mfma_f32_16x16x32_f16 v[58:61], v[160:163], v[204:207], v[58:61]
	v_mfma_f32_16x16x32_f16 v[46:49], v[134:137], v[212:215], v[46:49]
	v_mfma_f32_16x16x32_f16 v[42:45], v[160:163], v[212:215], v[42:45]
	v_mfma_f32_16x16x32_f16 v[28:31], v[134:137], v[220:223], v[28:31]
	v_mfma_f32_16x16x32_f16 v[24:27], v[160:163], v[220:223], v[24:27]
	v_mfma_f32_16x16x32_f16 v[12:15], v[134:137], v[228:231], v[12:15]
	v_mfma_f32_16x16x32_f16 v[8:11], v[160:163], v[228:231], v[8:11]
	v_mfma_f32_16x16x32_f16 v[54:57], v[164:167], v[196:199], v[54:57]
	v_mfma_f32_16x16x32_f16 v[50:53], v[172:175], v[196:199], v[50:53]
	v_mfma_f32_16x16x32_f16 v[38:41], v[164:167], v[208:211], v[38:41]
	v_mfma_f32_16x16x32_f16 v[34:37], v[172:175], v[208:211], v[34:37]
	v_mfma_f32_16x16x32_f16 v[20:23], v[164:167], v[216:219], v[20:23]
	v_mfma_f32_16x16x32_f16 v[16:19], v[172:175], v[216:219], v[16:19]
	v_mfma_f32_16x16x32_f16 v[4:7], v[164:167], v[224:227], v[4:7]
	v_mfma_f32_16x16x32_f16 v[0:3], v[172:175], v[224:227], v[0:3]
	v_mfma_f32_16x16x32_f16 v[54:57], v[168:171], v[204:207], v[54:57]
	v_mfma_f32_16x16x32_f16 v[50:53], v[176:179], v[204:207], v[50:53]
	v_mfma_f32_16x16x32_f16 v[38:41], v[168:171], v[212:215], v[38:41]
	v_mfma_f32_16x16x32_f16 v[34:37], v[176:179], v[212:215], v[34:37]
	v_mfma_f32_16x16x32_f16 v[20:23], v[168:171], v[220:223], v[20:23]
	v_mfma_f32_16x16x32_f16 v[16:19], v[176:179], v[220:223], v[16:19]
	v_mfma_f32_16x16x32_f16 v[4:7], v[168:171], v[228:231], v[4:7]
	v_mfma_f32_16x16x32_f16 v[0:3], v[176:179], v[228:231], v[0:3]
	s_barrier
; #define PG8_STAGE(bufoff, gbase, voff) do { _Pragma("unroll") for (int _i = 0; _i < 2; ++_i) \
;         __builtin_amdgcn_global_load_lds((const unsigned*)((const char*)(gbase) + (voff)[_i]), (LAS unsigned*)(lds + (bufoff) + ldsw + _i * 8192), 16, 0, 0); } while (0)
; #define PG8_LDA(dst, b, h) do { _Pragma("unroll") for (int m = 0; m < 4; ++m) _Pragma("unroll") for (int k = 0; k < 2; ++k) dst[m][k] = *(const LAS h16x8*)(lds + PG8_SA(b, h) + aoff + m * 2048 + k * 1024); } while (0)
; #define PG8_LDB(dst, b, h) do { _Pragma("unroll") for (int n = 0; n < 2; ++n) _Pragma("unroll") for (int k = 0; k < 2; ++k) dst[n][k] = *(const LAS h16x8*)(lds + PG8_SB(b, h) + boff + n * 2048 + k * 1024); } while (0)
; #define PG8_MMA(ai, bj, At, Bt) do { __builtin_amdgcn_s_setprio(1); _Pragma("unroll") for (int m = 0; m < 4; ++m) _Pragma("unroll") for (int n = 0; n < 2; ++n) _Pragma("unroll") for (int k = 0; k < 2; ++k) \
;         acc[ai][bj][m][n] = __builtin_amdgcn_mfma_f32_16x16x32_f16(Bt[n][k], At[m][k], acc[ai][bj][m][n], 0, 0, 0); __builtin_amdgcn_s_setprio(0); } while (0)
; #define PG8_WAIT_V(n) asm volatile("s_waitcnt vmcnt(" #n ")" ::: "memory")
; #define PG8_WAIT_L(n) asm volatile("s_waitcnt lgkmcnt(" #n ")" ::: "memory")
; #define PG8_BAR __builtin_amdgcn_s_barrier()
; #define PG8_SCHED __builtin_amdgcn_sched_barrier(0)
; template <class Epi>
; __device__ __forceinline__ void gemm_phase(LAS unsigned char* lds, const Gemm g, const StaticOrder& S, const Epi& E) {
;     ...
;             PG8_LDB(B0, 1, 0); PG8_LDB(B1, 1, 1); PG8_SCHED; PG8_LDA(At, 1, 0); PG8_STAGE(PG8_SA(0, 1), a2 + hstepA, voffA);
;             PG8_WAIT_V(8); PG8_WAIT_L(0); PG8_BAR; PG8_MMA(0, 0, At, B0); PG8_MMA(0, 1, At, B1); PG8_BAR; PG8_SCHED;
;             PG8_LDA(At, 1, 1); PG8_STAGE(PG8_SB(1, 0), b3, voffB); PG8_STAGE(PG8_SB(1, 1), b3 + hstepB, voffB); PG8_STAGE(PG8_SA(1, 0), a3, voffA);
;             PG8_WAIT_V(8); PG8_WAIT_L(0); PG8_BAR; PG8_MMA(1, 0, At, B0); PG8_MMA(1, 1, At, B1); PG8_BAR; PG8_SCHED;
;         }
;         if (wr == 0) PG8_BAR;
	s_add_i32 s96, 0, 0x18000
	v_add_u32_e32 v32, s96, v156
	s_add_i32 s97, 0, 0x1c000
	ds_read_b128 v[130:133], v32
	ds_read_b128 v[134:137], v32 offset:1024
	ds_read_b128 v[150:153], v32 offset:2048
	ds_read_b128 v[160:163], v32 offset:3072
	v_add_u32_e32 v32, s97, v156
	ds_read_b128 v[164:167], v32
	ds_read_b128 v[168:171], v32 offset:1024
	ds_read_b128 v[172:175], v32 offset:2048
	ds_read_b128 v[176:179], v32 offset:3072
	s_add_u32 s22, s22, s24
	s_addc_u32 s23, s23, 0
	s_mov_b32 m0, s73
	v_lshl_add_u64 v[238:239], s[22:23], 0, v[144:145]
	ds_read_b128 v[196:199], v159 offset:32768
	ds_read_b128 v[204:207], v159 offset:33792
	ds_read_b128 v[208:211], v159 offset:34816
	ds_read_b128 v[212:215], v159 offset:35840
	ds_read_b128 v[216:219], v159 offset:36864
	ds_read_b128 v[220:223], v159 offset:37888
	ds_read_b128 v[224:227], v159 offset:38912
	ds_read_b128 v[228:231], v159 offset:39936
	global_load_lds_dwordx4 v[238:239], off
	v_lshl_add_u64 v[238:239], s[22:23], 0, v[140:141]
	s_mov_b32 m0, s75
	s_nop 0
	global_load_lds_dwordx4 v[238:239], off
	s_waitcnt vmcnt(8)
	s_waitcnt lgkmcnt(0)
	s_barrier
	s_waitcnt lgkmcnt(0)
	v_mfma_f32_16x16x32_f16 v[126:129], v[130:133], v[196:199], v[126:129]
	v_mfma_f32_16x16x32_f16 v[122:125], v[150:153], v[196:199], v[122:125]
	v_mfma_f32_16x16x32_f16 v[110:113], v[130:133], v[208:211], v[110:113]
	v_mfma_f32_16x16x32_f16 v[106:109], v[150:153], v[208:211], v[106:109]
	v_mfma_f32_16x16x32_f16 v[94:97], v[130:133], v[216:219], v[94:97]
	v_mfma_f32_16x16x32_f16 v[90:93], v[150:153], v[216:219], v[90:93]
	v_mfma_f32_16x16x32_f16 v[78:81], v[130:133], v[224:227], v[78:81]
	v_mfma_f32_16x16x32_f16 v[74:77], v[150:153], v[224:227], v[74:77]
	v_mfma_f32_16x16x32_f16 v[126:129], v[134:137], v[204:207], v[126:129]
	v_mfma_f32_16x16x32_f16 v[122:125], v[160:163], v[204:207], v[122:125]
	v_mfma_f32_16x16x32_f16 v[110:113], v[134:137], v[212:215], v[110:113]
	v_mfma_f32_16x16x32_f16 v[106:109], v[160:163], v[212:215], v[106:109]
	v_mfma_f32_16x16x32_f16 v[94:97], v[134:137], v[220:223], v[94:97]
	v_mfma_f32_16x16x32_f16 v[90:93], v[160:163], v[220:223], v[90:93]
	v_mfma_f32_16x16x32_f16 v[78:81], v[134:137], v[228:231], v[78:81]
	v_mfma_f32_16x16x32_f16 v[74:77], v[160:163], v[228:231], v[74:77]
	v_mfma_f32_16x16x32_f16 v[118:121], v[164:167], v[196:199], v[118:121]
	v_mfma_f32_16x16x32_f16 v[114:117], v[172:175], v[196:199], v[114:117]
	v_mfma_f32_16x16x32_f16 v[102:105], v[164:167], v[208:211], v[102:105]
	v_mfma_f32_16x16x32_f16 v[98:101], v[172:175], v[208:211], v[98:101]
	v_mfma_f32_16x16x32_f16 v[86:89], v[164:167], v[216:219], v[86:89]
	v_mfma_f32_16x16x32_f16 v[82:85], v[172:175], v[216:219], v[82:85]
	v_mfma_f32_16x16x32_f16 v[70:73], v[164:167], v[224:227], v[70:73]
	v_mfma_f32_16x16x32_f16 v[66:69], v[172:175], v[224:227], v[66:69]
	v_mfma_f32_16x16x32_f16 v[118:121], v[168:171], v[204:207], v[118:121]
	v_mfma_f32_16x16x32_f16 v[114:117], v[176:179], v[204:207], v[114:117]
	v_mfma_f32_16x16x32_f16 v[102:105], v[168:171], v[212:215], v[102:105]
	v_mfma_f32_16x16x32_f16 v[98:101], v[176:179], v[212:215], v[98:101]
	v_mfma_f32_16x16x32_f16 v[86:89], v[168:171], v[220:223], v[86:89]
	v_mfma_f32_16x16x32_f16 v[82:85], v[176:179], v[220:223], v[82:85]
	v_mfma_f32_16x16x32_f16 v[70:73], v[168:171], v[228:231], v[70:73]
	v_mfma_f32_16x16x32_f16 v[66:69], v[176:179], v[228:231], v[66:69]
	s_barrier
	s_add_i32 s22, s96, s70
	v_lshl_add_u64 v[154:155], v[154:155], 0, s[90:91]
	s_mov_b32 m0, s22
	ds_read_b128 v[196:199], v159 offset:49152
	ds_read_b128 v[204:207], v159 offset:50176
	ds_read_b128 v[208:211], v159 offset:51200
	ds_read_b128 v[212:215], v159 offset:52224
	ds_read_b128 v[216:219], v159 offset:53248
	ds_read_b128 v[220:223], v159 offset:54272
	ds_read_b128 v[224:227], v159 offset:55296
	ds_read_b128 v[228:231], v159 offset:56320
	global_load_lds_dwordx4 v[154:155], off
	v_lshl_add_u64 v[154:155], v[180:181], 0, s[90:91]
	s_add_i32 m0, s22, 0x2000
	s_add_i32 s22, s97, s70
	global_load_lds_dwordx4 v[154:155], off
	v_lshl_add_u64 v[154:155], v[190:191], 0, s[90:91]
	s_mov_b32 m0, s22
	s_nop 0
	global_load_lds_dwordx4 v[154:155], off
	v_lshl_add_u64 v[154:155], v[232:233], 0, s[90:91]
	s_add_i32 m0, s22, 0x2000
	s_nop 0
	global_load_lds_dwordx4 v[154:155], off
	v_lshl_add_u64 v[154:155], v[234:235], 0, s[90:91]
	s_mov_b32 m0, s77
	s_nop 0
	global_load_lds_dwordx4 v[154:155], off
	v_lshl_add_u64 v[154:155], v[236:237], 0, s[90:91]
	s_mov_b32 m0, s78
	s_nop 0
	global_load_lds_dwordx4 v[154:155], off
	s_waitcnt vmcnt(8)
	s_waitcnt lgkmcnt(0)
	s_barrier
	s_waitcnt lgkmcnt(0)
	v_mfma_f32_16x16x32_f16 v[62:65], v[130:133], v[196:199], v[62:65]
	v_mfma_f32_16x16x32_f16 v[58:61], v[150:153], v[196:199], v[58:61]
	v_mfma_f32_16x16x32_f16 v[46:49], v[130:133], v[208:211], v[46:49]
	v_mfma_f32_16x16x32_f16 v[42:45], v[150:153], v[208:211], v[42:45]
	v_mfma_f32_16x16x32_f16 v[28:31], v[130:133], v[216:219], v[28:31]
	v_mfma_f32_16x16x32_f16 v[24:27], v[150:153], v[216:219], v[24:27]
	v_mfma_f32_16x16x32_f16 v[12:15], v[130:133], v[224:227], v[12:15]
	v_mfma_f32_16x16x32_f16 v[8:11], v[150:153], v[224:227], v[8:11]
	v_mfma_f32_16x16x32_f16 v[62:65], v[134:137], v[204:207], v[62:65]
	v_mfma_f32_16x16x32_f16 v[58:61], v[160:163], v[204:207], v[58:61]
	v_mfma_f32_16x16x32_f16 v[46:49], v[134:137], v[212:215], v[46:49]
	v_mfma_f32_16x16x32_f16 v[42:45], v[160:163], v[212:215], v[42:45]
	v_mfma_f32_16x16x32_f16 v[28:31], v[134:137], v[220:223], v[28:31]
	v_mfma_f32_16x16x32_f16 v[24:27], v[160:163], v[220:223], v[24:27]
	v_mfma_f32_16x16x32_f16 v[12:15], v[134:137], v[228:231], v[12:15]
	v_mfma_f32_16x16x32_f16 v[8:11], v[160:163], v[228:231], v[8:11]
	v_mfma_f32_16x16x32_f16 v[54:57], v[164:167], v[196:199], v[54:57]
	v_mfma_f32_16x16x32_f16 v[50:53], v[172:175], v[196:199], v[50:53]
	v_mfma_f32_16x16x32_f16 v[38:41], v[164:167], v[208:211], v[38:41]
	v_mfma_f32_16x16x32_f16 v[34:37], v[172:175], v[208:211], v[34:37]
	v_mfma_f32_16x16x32_f16 v[20:23], v[164:167], v[216:219], v[20:23]
	v_mfma_f32_16x16x32_f16 v[16:19], v[172:175], v[216:219], v[16:19]
	v_mfma_f32_16x16x32_f16 v[4:7], v[164:167], v[224:227], v[4:7]
	v_mfma_f32_16x16x32_f16 v[0:3], v[172:175], v[224:227], v[0:3]
	v_mfma_f32_16x16x32_f16 v[54:57], v[168:171], v[204:207], v[54:57]
	v_mfma_f32_16x16x32_f16 v[50:53], v[176:179], v[204:207], v[50:53]
	v_mfma_f32_16x16x32_f16 v[38:41], v[168:171], v[212:215], v[38:41]
	v_mfma_f32_16x16x32_f16 v[34:37], v[176:179], v[212:215], v[34:37]
	v_mfma_f32_16x16x32_f16 v[20:23], v[168:171], v[220:223], v[20:23]
	v_mfma_f32_16x16x32_f16 v[16:19], v[176:179], v[220:223], v[16:19]
	v_mfma_f32_16x16x32_f16 v[4:7], v[168:171], v[228:231], v[4:7]
	v_mfma_f32_16x16x32_f16 v[0:3], v[176:179], v[228:231], v[0:3]
	s_barrier
	s_add_u32 s93, s93, 0x100
	s_addc_u32 s94, s94, 0
	s_add_u32 s6, s6, 0x100
	s_addc_u32 s7, s7, 0
	s_cmp_ge_u32 s95, s76
	s_mov_b32 s22, s95
	s_cbranch_scc0 .LBB0_140
	s_setprio 0
	s_and_b64 vcc, exec, s[18:19]
	s_cbranch_vccz .LBB0_143
	s_barrier

; #define PG8_STAGE(bufoff, gbase, voff) do { _Pragma("unroll") for (int _i = 0; _i < 2; ++_i) \
;         __builtin_amdgcn_global_load_lds((const unsigned*)((const char*)(gbase) + (voff)[_i]), (LAS unsigned*)(lds + (bufoff) + ldsw + _i * 8192), 16, 0, 0); } while (0)
; #define PG8_LDA(dst, b, h) do { _Pragma("unroll") for (int m = 0; m < 4; ++m) _Pragma("unroll") for (int k = 0; k < 2; ++k) dst[m][k] = *(const LAS h16x8*)(lds + PG8_SA(b, h) + aoff + m * 2048 + k * 1024); } while (0)
; #define PG8_LDB(dst, b, h) do { _Pragma("unroll") for (int n = 0; n < 2; ++n) _Pragma("unroll") for (int k = 0; k < 2; ++k) dst[n][k] = *(const LAS h16x8*)(lds + PG8_SB(b, h) + boff + n * 2048 + k * 1024); } while (0)
; #define PG8_MMA(ai, bj, At, Bt) do { __builtin_amdgcn_s_setprio(1); _Pragma("unroll") for (int m = 0; m < 4; ++m) _Pragma("unroll") for (int n = 0; n < 2; ++n) _Pragma("unroll") for (int k = 0; k < 2; ++k) \
;         acc[ai][bj][m][n] = __builtin_amdgcn_mfma_f32_16x16x32_f16(Bt[n][k], At[m][k], acc[ai][bj][m][n], 0, 0, 0); __builtin_amdgcn_s_setprio(0); } while (0)
; #define PG8_BAR __builtin_amdgcn_s_barrier()
; template <class Epi>
; __device__ __forceinline__ void gemm_phase(LAS unsigned char* lds, const Gemm g, const StaticOrder& S, const Epi& E) {
;     ...
;         const char* nA = has_next ? (const char*)g.A + (size_t)nxt.pm * tstepA : cA; const char* nB = has_next ? (const char*)g.Bt + (size_t)nxt.pn * tstepB : cB;
;         for (int t = 0; t < nt; t += 2) {
;             const bool last = (t == nt - 2);
;             const char* a1 = cA + (size_t)(t + 1) * kstep;
;             const char* a2 = last ? nA : cA + (size_t)(t + 2) * kstep; const char* b2 = last ? nB : cB + (size_t)(t + 2) * kstep;
;             const char* a3 = a2 + kstep; const char* b3 = b2 + kstep;
;             PG8_LDB(B0, 0, 0); PG8_LDB(B1, 0, 1); PG8_SCHED; PG8_LDA(At, 0, 0); PG8_STAGE(PG8_SA(1, 1), a1 + hstepA, voffA);
;             PG8_WAIT_V(8); PG8_WAIT_L(0); PG8_BAR; PG8_MMA(0, 0, At, B0); PG8_MMA(0, 1, At, B1); PG8_BAR; PG8_SCHED;
;     ...
; #pragma unroll
;         for (int a = 0; a < 2; ++a)
; #pragma unroll
;             for (int b = 0; b < 2; ++b)
; #pragma unroll
;                 for (int m = 0; m < 4; ++m)
; #pragma unroll
;                     for (int n = 0; n < 2; ++n) acc[a][b][m][n] = (f32x4){0.f, 0.f, 0.f, 0.f};
;         cur = nxt; cA = nA; cB = nB; ++ui;
.LBB0_213:
	s_ashr_i32 s13, s12, 31
	s_lshl_b64 s[14:15], s[12:13], 19
	s_add_u32 s14, s84, s14
	s_addc_u32 s15, s85, s15
	s_and_b64 s[16:17], s[4:5], exec
	s_cselect_b32 s13, s15, s21
	s_cselect_b32 s70, s14, s20
	s_ashr_i32 s11, s10, 31
	s_lshl_b64 s[16:17], s[10:11], 19
	v_readlane_b32 s22, v255, 5
	v_readlane_b32 s23, v255, 6
	s_add_u32 s16, s22, s16
	s_addc_u32 s17, s23, s17
	s_and_b64 s[22:23], s[4:5], exec
	s_cselect_b32 s11, s17, s19
	s_cselect_b32 s71, s16, s18
	s_add_u32 s72, s18, 0x100
	s_addc_u32 s73, s19, 0
	s_add_u32 s18, s20, 0x40080
	v_mov_b32_e32 v0, 0
	s_addc_u32 s19, s21, 0
	s_mov_b32 s75, -2
	v_mov_b32_e32 v1, v0
	v_mov_b32_e32 v2, v0
	v_mov_b32_e32 v3, v0
	v_mov_b32_e32 v4, v0
	v_mov_b32_e32 v5, v0
	v_mov_b32_e32 v6, v0
	v_mov_b32_e32 v7, v0
	v_mov_b32_e32 v16, v0
	v_mov_b32_e32 v17, v0
	v_mov_b32_e32 v18, v0
	v_mov_b32_e32 v19, v0
	v_mov_b32_e32 v20, v0
	v_mov_b32_e32 v21, v0
	v_mov_b32_e32 v22, v0
	v_mov_b32_e32 v23, v0
	v_mov_b32_e32 v34, v0
	v_mov_b32_e32 v35, v0
	v_mov_b32_e32 v36, v0
	v_mov_b32_e32 v37, v0
	v_mov_b32_e32 v38, v0
	v_mov_b32_e32 v39, v0
	v_mov_b32_e32 v40, v0
	v_mov_b32_e32 v41, v0
	v_mov_b32_e32 v50, v0
	v_mov_b32_e32 v51, v0
	v_mov_b32_e32 v52, v0
	v_mov_b32_e32 v53, v0
	v_mov_b32_e32 v54, v0
	v_mov_b32_e32 v55, v0
	v_mov_b32_e32 v56, v0
	v_mov_b32_e32 v57, v0
	v_mov_b32_e32 v8, v0
	v_mov_b32_e32 v9, v0
	v_mov_b32_e32 v10, v0
	v_mov_b32_e32 v11, v0
	v_mov_b32_e32 v12, v0
	v_mov_b32_e32 v13, v0
	v_mov_b32_e32 v14, v0
	v_mov_b32_e32 v15, v0
	v_mov_b32_e32 v24, v0
	v_mov_b32_e32 v25, v0
	v_mov_b32_e32 v26, v0
	v_mov_b32_e32 v27, v0
	v_mov_b32_e32 v28, v0
	v_mov_b32_e32 v29, v0
	v_mov_b32_e32 v30, v0
	v_mov_b32_e32 v31, v0
	v_mov_b32_e32 v42, v0
	v_mov_b32_e32 v43, v0
	v_mov_b32_e32 v44, v0
	v_mov_b32_e32 v45, v0
	v_mov_b32_e32 v46, v0
	v_mov_b32_e32 v47, v0
	v_mov_b32_e32 v48, v0
	v_mov_b32_e32 v49, v0
	v_mov_b32_e32 v58, v0
	v_mov_b32_e32 v59, v0
	v_mov_b32_e32 v60, v0
	v_mov_b32_e32 v61, v0
	v_mov_b32_e32 v62, v0
	v_mov_b32_e32 v63, v0
	v_mov_b32_e32 v64, v0
	v_mov_b32_e32 v65, v0
	v_mov_b32_e32 v66, v0
	v_mov_b32_e32 v67, v0
	v_mov_b32_e32 v68, v0
	v_mov_b32_e32 v69, v0
	v_mov_b32_e32 v70, v0
	v_mov_b32_e32 v71, v0
	v_mov_b32_e32 v72, v0
	v_mov_b32_e32 v73, v0
	v_mov_b32_e32 v82, v0
	v_mov_b32_e32 v83, v0
	v_mov_b32_e32 v84, v0
	v_mov_b32_e32 v85, v0
	v_mov_b32_e32 v86, v0
	v_mov_b32_e32 v87, v0
	v_mov_b32_e32 v88, v0
	v_mov_b32_e32 v89, v0
	v_mov_b32_e32 v98, v0
	v_mov_b32_e32 v99, v0
	v_mov_b32_e32 v100, v0
	v_mov_b32_e32 v101, v0
	v_mov_b32_e32 v102, v0
	v_mov_b32_e32 v103, v0
	v_mov_b32_e32 v104, v0
	v_mov_b32_e32 v105, v0
	v_mov_b32_e32 v114, v0
	v_mov_b32_e32 v115, v0
	v_mov_b32_e32 v116, v0
	v_mov_b32_e32 v117, v0
	v_mov_b32_e32 v118, v0
	v_mov_b32_e32 v119, v0
	v_mov_b32_e32 v120, v0
	v_mov_b32_e32 v121, v0
	v_mov_b32_e32 v74, v0
	v_mov_b32_e32 v75, v0
	v_mov_b32_e32 v76, v0
	v_mov_b32_e32 v77, v0
	v_mov_b32_e32 v78, v0
	v_mov_b32_e32 v79, v0
	v_mov_b32_e32 v80, v0
	v_mov_b32_e32 v81, v0
	v_mov_b32_e32 v90, v0
	v_mov_b32_e32 v91, v0
	v_mov_b32_e32 v92, v0
	v_mov_b32_e32 v93, v0
	v_mov_b32_e32 v94, v0
	v_mov_b32_e32 v95, v0
	v_mov_b32_e32 v96, v0
	v_mov_b32_e32 v97, v0
	v_mov_b32_e32 v106, v0
	v_mov_b32_e32 v107, v0
	v_mov_b32_e32 v108, v0
	v_mov_b32_e32 v109, v0
	v_mov_b32_e32 v110, v0
	v_mov_b32_e32 v111, v0
	v_mov_b32_e32 v112, v0
	v_mov_b32_e32 v113, v0
	v_mov_b32_e32 v122, v0
	v_mov_b32_e32 v123, v0
	v_mov_b32_e32 v124, v0
	v_mov_b32_e32 v125, v0
	v_mov_b32_e32 v126, v0
	v_mov_b32_e32 v127, v0
	v_mov_b32_e32 v128, v0
	v_mov_b32_e32 v129, v0
	s_cmp_eq_u64 s[6:7], 0
	s_cbranch_scc0 .Lprio_214
	s_setprio 1
.Lprio_214:
.LBB0_214:
	s_add_u32 s20, s18, 0xfffc0080
	s_addc_u32 s21, s19, -1
	s_add_i32 s76, 0, 0x10000
	s_cmp_eq_u32 s75, 12
	s_cselect_b32 s23, s13, s21
	s_cselect_b32 s22, s70, s20
	v_add_u32_e32 v32, s76, v145
	s_cselect_b32 s21, s11, s73
	s_cselect_b32 s20, s71, s72
	s_add_i32 s78, 0, 0x14000
	ds_read_b128 v[148:151], v32
	ds_read_b128 v[152:155], v32 offset:1024
	ds_read_b128 v[156:159], v32 offset:2048
	ds_read_b128 v[160:163], v32 offset:3072
	v_add_u32_e32 v32, s78, v145
	ds_read_b128 v[164:167], v32
	ds_read_b128 v[168:171], v32 offset:1024
	ds_read_b128 v[172:175], v32 offset:2048
	ds_read_b128 v[176:179], v32 offset:3072
	v_lshl_add_u64 v[180:181], s[18:19], 0, v[142:143]
	s_add_i32 m0, s28, 0xc000
	ds_read_b128 v[196:199], v147
	ds_read_b128 v[204:207], v147 offset:1024
	ds_read_b128 v[208:211], v147 offset:2048
	ds_read_b128 v[212:215], v147 offset:3072
	ds_read_b128 v[216:219], v147 offset:4096
	ds_read_b128 v[220:223], v147 offset:5120
	ds_read_b128 v[224:227], v147 offset:6144
	ds_read_b128 v[228:231], v147 offset:7168
	global_load_lds_dwordx4 v[180:181], off
	v_lshl_add_u64 v[180:181], s[18:19], 0, v[140:141]
	s_add_i32 m0, s28, 0xe000
	s_nop 0
	global_load_lds_dwordx4 v[180:181], off
	s_waitcnt vmcnt(8)
	s_waitcnt lgkmcnt(0)
	s_barrier
; #define PG8_STAGE(bufoff, gbase, voff) do { _Pragma("unroll") for (int _i = 0; _i < 2; ++_i) \
;         __builtin_amdgcn_global_load_lds((const unsigned*)((const char*)(gbase) + (voff)[_i]), (LAS unsigned*)(lds + (bufoff) + ldsw + _i * 8192), 16, 0, 0); } while (0)
; #define PG8_LDA(dst, b, h) do { _Pragma("unroll") for (int m = 0; m < 4; ++m) _Pragma("unroll") for (int k = 0; k < 2; ++k) dst[m][k] = *(const LAS h16x8*)(lds + PG8_SA(b, h) + aoff + m * 2048 + k * 1024); } while (0)
; #define PG8_MMA(ai, bj, At, Bt) do { __builtin_amdgcn_s_setprio(1); _Pragma("unroll") for (int m = 0; m < 4; ++m) _Pragma("unroll") for (int n = 0; n < 2; ++n) _Pragma("unroll") for (int k = 0; k < 2; ++k) \
;         acc[ai][bj][m][n] = __builtin_amdgcn_mfma_f32_16x16x32_f16(Bt[n][k], At[m][k], acc[ai][bj][m][n], 0, 0, 0); __builtin_amdgcn_s_setprio(0); } while (0)
; #define PG8_WAIT_V(n) asm volatile("s_waitcnt vmcnt(" #n ")" ::: "memory")
; #define PG8_WAIT_L(n) asm volatile("s_waitcnt lgkmcnt(" #n ")" ::: "memory")
; #define PG8_BAR __builtin_amdgcn_s_barrier()
; #define PG8_SCHED __builtin_amdgcn_sched_barrier(0)
; template <class Epi>
; __device__ __forceinline__ void gemm_phase(LAS unsigned char* lds, const Gemm g, const StaticOrder& S, const Epi& E) {
;     ...
;             PG8_WAIT_V(8); PG8_WAIT_L(0); PG8_BAR; PG8_MMA(0, 0, At, B0); PG8_MMA(0, 1, At, B1); PG8_BAR; PG8_SCHED;
;             PG8_LDA(At, 0, 1); PG8_STAGE(PG8_SB(0, 0), b2, voffB); PG8_STAGE(PG8_SB(0, 1), b2 + hstepB, voffB); PG8_STAGE(PG8_SA(0, 0), a2, voffA);
;             PG8_WAIT_V(8); PG8_WAIT_L(0); PG8_BAR; PG8_MMA(1, 0, At, B0); PG8_MMA(1, 1, At, B1); PG8_BAR; PG8_SCHED;
	s_waitcnt lgkmcnt(0)
	v_mfma_f32_16x16x32_f16 v[126:129], v[148:151], v[196:199], v[126:129]
	v_mfma_f32_16x16x32_f16 v[122:125], v[156:159], v[196:199], v[122:125]
	v_mfma_f32_16x16x32_f16 v[110:113], v[148:151], v[208:211], v[110:113]
	v_mfma_f32_16x16x32_f16 v[106:109], v[156:159], v[208:211], v[106:109]
	v_mfma_f32_16x16x32_f16 v[94:97], v[148:151], v[216:219], v[94:97]
	v_mfma_f32_16x16x32_f16 v[90:93], v[156:159], v[216:219], v[90:93]
	v_mfma_f32_16x16x32_f16 v[78:81], v[148:151], v[224:227], v[78:81]
	v_mfma_f32_16x16x32_f16 v[74:77], v[156:159], v[224:227], v[74:77]
	v_mfma_f32_16x16x32_f16 v[126:129], v[152:155], v[204:207], v[126:129]
	v_mfma_f32_16x16x32_f16 v[122:125], v[160:163], v[204:207], v[122:125]
	v_mfma_f32_16x16x32_f16 v[110:113], v[152:155], v[212:215], v[110:113]
	v_mfma_f32_16x16x32_f16 v[106:109], v[160:163], v[212:215], v[106:109]
	v_mfma_f32_16x16x32_f16 v[94:97], v[152:155], v[220:223], v[94:97]
	v_mfma_f32_16x16x32_f16 v[90:93], v[160:163], v[220:223], v[90:93]
	v_mfma_f32_16x16x32_f16 v[78:81], v[152:155], v[228:231], v[78:81]
	v_mfma_f32_16x16x32_f16 v[74:77], v[160:163], v[228:231], v[74:77]
	v_mfma_f32_16x16x32_f16 v[118:121], v[164:167], v[196:199], v[118:121]
	v_mfma_f32_16x16x32_f16 v[114:117], v[172:175], v[196:199], v[114:117]
	v_mfma_f32_16x16x32_f16 v[102:105], v[164:167], v[208:211], v[102:105]
	v_mfma_f32_16x16x32_f16 v[98:101], v[172:175], v[208:211], v[98:101]
	v_mfma_f32_16x16x32_f16 v[86:89], v[164:167], v[216:219], v[86:89]
	v_mfma_f32_16x16x32_f16 v[82:85], v[172:175], v[216:219], v[82:85]
	v_mfma_f32_16x16x32_f16 v[70:73], v[164:167], v[224:227], v[70:73]
	v_mfma_f32_16x16x32_f16 v[66:69], v[172:175], v[224:227], v[66:69]
	v_mfma_f32_16x16x32_f16 v[118:121], v[168:171], v[204:207], v[118:121]
	v_mfma_f32_16x16x32_f16 v[114:117], v[176:179], v[204:207], v[114:117]
	v_mfma_f32_16x16x32_f16 v[102:105], v[168:171], v[212:215], v[102:105]
	v_mfma_f32_16x16x32_f16 v[98:101], v[176:179], v[212:215], v[98:101]
	v_mfma_f32_16x16x32_f16 v[86:89], v[168:171], v[220:223], v[86:89]
	v_mfma_f32_16x16x32_f16 v[82:85], v[176:179], v[220:223], v[82:85]
	v_mfma_f32_16x16x32_f16 v[70:73], v[168:171], v[228:231], v[70:73]
	v_mfma_f32_16x16x32_f16 v[66:69], v[176:179], v[228:231], v[66:69]
	s_barrier
	s_add_i32 s76, s76, s24
	v_lshl_add_u64 v[180:181], s[20:21], 0, v[134:135]
	s_mov_b32 m0, s76
	ds_read_b128 v[196:199], v147 offset:16384
	ds_read_b128 v[204:207], v147 offset:17408
	ds_read_b128 v[208:211], v147 offset:18432
	ds_read_b128 v[212:215], v147 offset:19456
	ds_read_b128 v[216:219], v147 offset:20480
	ds_read_b128 v[220:223], v147 offset:21504
	ds_read_b128 v[224:227], v147 offset:22528
	ds_read_b128 v[228:231], v147 offset:23552
	global_load_lds_dwordx4 v[180:181], off
	s_add_i32 m0, s76, 0x2000
	s_add_u32 s76, s20, 0x40000
	v_lshl_add_u64 v[190:191], s[20:21], 0, v[130:131]
	s_addc_u32 s77, s21, 0
	s_add_i32 s78, s78, s24
	global_load_lds_dwordx4 v[190:191], off
	v_lshl_add_u64 v[232:233], s[76:77], 0, v[134:135]
	s_mov_b32 m0, s78
	v_lshl_add_u64 v[234:235], s[22:23], 0, v[132:133]
	global_load_lds_dwordx4 v[232:233], off
	v_lshl_add_u64 v[232:233], s[76:77], 0, v[130:131]
	s_add_i32 m0, s78, 0x2000
	s_nop 0
	global_load_lds_dwordx4 v[232:233], off
	v_lshl_add_u64 v[232:233], s[22:23], 0, v[136:137]
	s_mov_b32 m0, s28
	s_nop 0
	global_load_lds_dwordx4 v[232:233], off
	s_mov_b32 m0, s29
	s_nop 0
	global_load_lds_dwordx4 v[234:235], off
	s_waitcnt vmcnt(8)
	s_waitcnt lgkmcnt(0)
	s_barrier
	s_waitcnt lgkmcnt(0)
	v_mfma_f32_16x16x32_f16 v[62:65], v[148:151], v[196:199], v[62:65]
	v_mfma_f32_16x16x32_f16 v[58:61], v[156:159], v[196:199], v[58:61]
	v_mfma_f32_16x16x32_f16 v[46:49], v[148:151], v[208:211], v[46:49]
	v_mfma_f32_16x16x32_f16 v[42:45], v[156:159], v[208:211], v[42:45]
	v_mfma_f32_16x16x32_f16 v[28:31], v[148:151], v[216:219], v[28:31]
	v_mfma_f32_16x16x32_f16 v[24:27], v[156:159], v[216:219], v[24:27]
	v_mfma_f32_16x16x32_f16 v[12:15], v[148:151], v[224:227], v[12:15]
	v_mfma_f32_16x16x32_f16 v[8:11], v[156:159], v[224:227], v[8:11]
	v_mfma_f32_16x16x32_f16 v[62:65], v[152:155], v[204:207], v[62:65]
	v_mfma_f32_16x16x32_f16 v[58:61], v[160:163], v[204:207], v[58:61]
	v_mfma_f32_16x16x32_f16 v[46:49], v[152:155], v[212:215], v[46:49]
	v_mfma_f32_16x16x32_f16 v[42:45], v[160:163], v[212:215], v[42:45]
	v_mfma_f32_16x16x32_f16 v[28:31], v[152:155], v[220:223], v[28:31]
	v_mfma_f32_16x16x32_f16 v[24:27], v[160:163], v[220:223], v[24:27]
	v_mfma_f32_16x16x32_f16 v[12:15], v[152:155], v[228:231], v[12:15]
	v_mfma_f32_16x16x32_f16 v[8:11], v[160:163], v[228:231], v[8:11]
	v_mfma_f32_16x16x32_f16 v[54:57], v[164:167], v[196:199], v[54:57]
	v_mfma_f32_16x16x32_f16 v[50:53], v[172:175], v[196:199], v[50:53]
	v_mfma_f32_16x16x32_f16 v[38:41], v[164:167], v[208:211], v[38:41]
	v_mfma_f32_16x16x32_f16 v[34:37], v[172:175], v[208:211], v[34:37]
	v_mfma_f32_16x16x32_f16 v[20:23], v[164:167], v[216:219], v[20:23]
	v_mfma_f32_16x16x32_f16 v[16:19], v[172:175], v[216:219], v[16:19]
	v_mfma_f32_16x16x32_f16 v[4:7], v[164:167], v[224:227], v[4:7]
	v_mfma_f32_16x16x32_f16 v[0:3], v[172:175], v[224:227], v[0:3]
	v_mfma_f32_16x16x32_f16 v[54:57], v[168:171], v[204:207], v[54:57]
	v_mfma_f32_16x16x32_f16 v[50:53], v[176:179], v[204:207], v[50:53]
	v_mfma_f32_16x16x32_f16 v[38:41], v[168:171], v[212:215], v[38:41]
	v_mfma_f32_16x16x32_f16 v[34:37], v[176:179], v[212:215], v[34:37]
	v_mfma_f32_16x16x32_f16 v[20:23], v[168:171], v[220:223], v[20:23]
	v_mfma_f32_16x16x32_f16 v[16:19], v[176:179], v[220:223], v[16:19]
	v_mfma_f32_16x16x32_f16 v[4:7], v[168:171], v[228:231], v[4:7]
	v_mfma_f32_16x16x32_f16 v[0:3], v[176:179], v[228:231], v[0:3]
	s_barrier
; #define PG8_STAGE(bufoff, gbase, voff) do { _Pragma("unroll") for (int _i = 0; _i < 2; ++_i) \
;         __builtin_amdgcn_global_load_lds((const unsigned*)((const char*)(gbase) + (voff)[_i]), (LAS unsigned*)(lds + (bufoff) + ldsw + _i * 8192), 16, 0, 0); } while (0)
; #define PG8_LDA(dst, b, h) do { _Pragma("unroll") for (int m = 0; m < 4; ++m) _Pragma("unroll") for (int k = 0; k < 2; ++k) dst[m][k] = *(const LAS h16x8*)(lds + PG8_SA(b, h) + aoff + m * 2048 + k * 1024); } while (0)
; #define PG8_LDB(dst, b, h) do { _Pragma("unroll") for (int n = 0; n < 2; ++n) _Pragma("unroll") for (int k = 0; k < 2; ++k) dst[n][k] = *(const LAS h16x8*)(lds + PG8_SB(b, h) + boff + n * 2048 + k * 1024); } while (0)
; #define PG8_MMA(ai, bj, At, Bt) do { __builtin_amdgcn_s_setprio(1); _Pragma("unroll") for (int m = 0; m < 4; ++m) _Pragma("unroll") for (int n = 0; n < 2; ++n) _Pragma("unroll") for (int k = 0; k < 2; ++k) \
;         acc[ai][bj][m][n] = __builtin_amdgcn_mfma_f32_16x16x32_f16(Bt[n][k], At[m][k], acc[ai][bj][m][n], 0, 0, 0); __builtin_amdgcn_s_setprio(0); } while (0)
; #define PG8_WAIT_V(n) asm volatile("s_waitcnt vmcnt(" #n ")" ::: "memory")
; #define PG8_WAIT_L(n) asm volatile("s_waitcnt lgkmcnt(" #n ")" ::: "memory")
; #define PG8_BAR __builtin_amdgcn_s_barrier()
; #define PG8_SCHED __builtin_amdgcn_sched_barrier(0)
; template <class Epi>
; __device__ __forceinline__ void gemm_phase(LAS unsigned char* lds, const Gemm g, const StaticOrder& S, const Epi& E) {
;     ...
;             PG8_LDB(B0, 1, 0); PG8_LDB(B1, 1, 1); PG8_SCHED; PG8_LDA(At, 1, 0); PG8_STAGE(PG8_SA(0, 1), a2 + hstepA, voffA);
;             PG8_WAIT_V(8); PG8_WAIT_L(0); PG8_BAR; PG8_MMA(0, 0, At, B0); PG8_MMA(0, 1, At, B1); PG8_BAR; PG8_SCHED;
	s_add_i32 s76, 0, 0x18000
	v_add_u32_e32 v32, s76, v145
	s_add_i32 s77, 0, 0x1c000
	ds_read_b128 v[148:151], v32
	ds_read_b128 v[152:155], v32 offset:1024
	ds_read_b128 v[156:159], v32 offset:2048
	ds_read_b128 v[160:163], v32 offset:3072
	v_add_u32_e32 v32, s77, v145
	ds_read_b128 v[164:167], v32
	ds_read_b128 v[168:171], v32 offset:1024
	ds_read_b128 v[172:175], v32 offset:2048
	ds_read_b128 v[176:179], v32 offset:3072
	s_add_u32 s22, s22, 0x40000
	s_addc_u32 s23, s23, 0
	s_mov_b32 m0, s30
	v_lshl_add_u64 v[236:237], s[22:23], 0, v[136:137]
	ds_read_b128 v[196:199], v147 offset:32768
	ds_read_b128 v[204:207], v147 offset:33792
	ds_read_b128 v[208:211], v147 offset:34816
	ds_read_b128 v[212:215], v147 offset:35840
	ds_read_b128 v[216:219], v147 offset:36864
	ds_read_b128 v[220:223], v147 offset:37888
	ds_read_b128 v[224:227], v147 offset:38912
	ds_read_b128 v[228:231], v147 offset:39936
	global_load_lds_dwordx4 v[236:237], off
	v_lshl_add_u64 v[236:237], s[22:23], 0, v[132:133]
	s_mov_b32 m0, s31
	s_nop 0
	global_load_lds_dwordx4 v[236:237], off
	s_waitcnt vmcnt(8)
	s_waitcnt lgkmcnt(0)
	s_barrier
	s_waitcnt lgkmcnt(0)
	v_mfma_f32_16x16x32_f16 v[126:129], v[148:151], v[196:199], v[126:129]
	v_mfma_f32_16x16x32_f16 v[122:125], v[156:159], v[196:199], v[122:125]
	v_mfma_f32_16x16x32_f16 v[110:113], v[148:151], v[208:211], v[110:113]
	v_mfma_f32_16x16x32_f16 v[106:109], v[156:159], v[208:211], v[106:109]
	v_mfma_f32_16x16x32_f16 v[94:97], v[148:151], v[216:219], v[94:97]
	v_mfma_f32_16x16x32_f16 v[90:93], v[156:159], v[216:219], v[90:93]
	v_mfma_f32_16x16x32_f16 v[78:81], v[148:151], v[224:227], v[78:81]
	v_mfma_f32_16x16x32_f16 v[74:77], v[156:159], v[224:227], v[74:77]
	v_mfma_f32_16x16x32_f16 v[126:129], v[152:155], v[204:207], v[126:129]
	v_mfma_f32_16x16x32_f16 v[122:125], v[160:163], v[204:207], v[122:125]
	v_mfma_f32_16x16x32_f16 v[110:113], v[152:155], v[212:215], v[110:113]
	v_mfma_f32_16x16x32_f16 v[106:109], v[160:163], v[212:215], v[106:109]
	v_mfma_f32_16x16x32_f16 v[94:97], v[152:155], v[220:223], v[94:97]
	v_mfma_f32_16x16x32_f16 v[90:93], v[160:163], v[220:223], v[90:93]
	v_mfma_f32_16x16x32_f16 v[78:81], v[152:155], v[228:231], v[78:81]
	v_mfma_f32_16x16x32_f16 v[74:77], v[160:163], v[228:231], v[74:77]
	v_mfma_f32_16x16x32_f16 v[118:121], v[164:167], v[196:199], v[118:121]
	v_mfma_f32_16x16x32_f16 v[114:117], v[172:175], v[196:199], v[114:117]
	v_mfma_f32_16x16x32_f16 v[102:105], v[164:167], v[208:211], v[102:105]
	v_mfma_f32_16x16x32_f16 v[98:101], v[172:175], v[208:211], v[98:101]
	v_mfma_f32_16x16x32_f16 v[86:89], v[164:167], v[216:219], v[86:89]
	v_mfma_f32_16x16x32_f16 v[82:85], v[172:175], v[216:219], v[82:85]
	v_mfma_f32_16x16x32_f16 v[70:73], v[164:167], v[224:227], v[70:73]
	v_mfma_f32_16x16x32_f16 v[66:69], v[172:175], v[224:227], v[66:69]
	v_mfma_f32_16x16x32_f16 v[118:121], v[168:171], v[204:207], v[118:121]
	v_mfma_f32_16x16x32_f16 v[114:117], v[176:179], v[204:207], v[114:117]
	v_mfma_f32_16x16x32_f16 v[102:105], v[168:171], v[212:215], v[102:105]
	v_mfma_f32_16x16x32_f16 v[98:101], v[176:179], v[212:215], v[98:101]
	v_mfma_f32_16x16x32_f16 v[86:89], v[168:171], v[220:223], v[86:89]
	v_mfma_f32_16x16x32_f16 v[82:85], v[176:179], v[220:223], v[82:85]
	v_mfma_f32_16x16x32_f16 v[70:73], v[168:171], v[228:231], v[70:73]
	v_mfma_f32_16x16x32_f16 v[66:69], v[176:179], v[228:231], v[66:69]
	s_barrier
; #define PG8_STAGE(bufoff, gbase, voff) do { _Pragma("unroll") for (int _i = 0; _i < 2; ++_i) \
;         __builtin_amdgcn_global_load_lds((const unsigned*)((const char*)(gbase) + (voff)[_i]), (LAS unsigned*)(lds + (bufoff) + ldsw + _i * 8192), 16, 0, 0); } while (0)
; #define PG8_LDA(dst, b, h) do { _Pragma("unroll") for (int m = 0; m < 4; ++m) _Pragma("unroll") for (int k = 0; k < 2; ++k) dst[m][k] = *(const LAS h16x8*)(lds + PG8_SA(b, h) + aoff + m * 2048 + k * 1024); } while (0)
; #define PG8_MMA(ai, bj, At, Bt) do { __builtin_amdgcn_s_setprio(1); _Pragma("unroll") for (int m = 0; m < 4; ++m) _Pragma("unroll") for (int n = 0; n < 2; ++n) _Pragma("unroll") for (int k = 0; k < 2; ++k) \
;         acc[ai][bj][m][n] = __builtin_amdgcn_mfma_f32_16x16x32_f16(Bt[n][k], At[m][k], acc[ai][bj][m][n], 0, 0, 0); __builtin_amdgcn_s_setprio(0); } while (0)
; #define PG8_WAIT_V(n) asm volatile("s_waitcnt vmcnt(" #n ")" ::: "memory")
; #define PG8_WAIT_L(n) asm volatile("s_waitcnt lgkmcnt(" #n ")" ::: "memory")
; #define PG8_BAR __builtin_amdgcn_s_barrier()
; #define PG8_SCHED __builtin_amdgcn_sched_barrier(0)
; template <class Epi>
; __device__ __forceinline__ void gemm_phase(LAS unsigned char* lds, const Gemm g, const StaticOrder& S, const Epi& E) {
;     ...
;             PG8_LDA(At, 1, 1); PG8_STAGE(PG8_SB(1, 0), b3, voffB); PG8_STAGE(PG8_SB(1, 1), b3 + hstepB, voffB); PG8_STAGE(PG8_SA(1, 0), a3, voffA);
;             PG8_WAIT_V(8); PG8_WAIT_L(0); PG8_BAR; PG8_MMA(1, 0, At, B0); PG8_MMA(1, 1, At, B1); PG8_BAR; PG8_SCHED;
;         }
;         if (wr == 0) PG8_BAR;
	s_add_i32 s22, s76, s24
	v_lshl_add_u64 v[180:181], v[180:181], 0, s[90:91]
	s_mov_b32 m0, s22
	ds_read_b128 v[196:199], v147 offset:49152
	ds_read_b128 v[204:207], v147 offset:50176
	ds_read_b128 v[208:211], v147 offset:51200
	ds_read_b128 v[212:215], v147 offset:52224
	ds_read_b128 v[216:219], v147 offset:53248
	ds_read_b128 v[220:223], v147 offset:54272
	ds_read_b128 v[224:227], v147 offset:55296
	ds_read_b128 v[228:231], v147 offset:56320
	global_load_lds_dwordx4 v[180:181], off
	s_add_i32 m0, s22, 0x2000
	s_add_u32 s20, s20, 0x40080
	v_lshl_add_u64 v[180:181], v[190:191], 0, s[90:91]
	s_addc_u32 s21, s21, 0
	s_add_i32 s22, s77, s24
	global_load_lds_dwordx4 v[180:181], off
	v_lshl_add_u64 v[180:181], s[20:21], 0, v[134:135]
	s_mov_b32 m0, s22
	s_nop 0
	global_load_lds_dwordx4 v[180:181], off
	v_lshl_add_u64 v[180:181], s[20:21], 0, v[130:131]
	s_add_i32 m0, s22, 0x2000
	s_nop 0
	global_load_lds_dwordx4 v[180:181], off
	v_lshl_add_u64 v[180:181], v[232:233], 0, s[90:91]
	s_mov_b32 m0, s35
	s_nop 0
	global_load_lds_dwordx4 v[180:181], off
	v_lshl_add_u64 v[180:181], v[234:235], 0, s[90:91]
	s_mov_b32 m0, s54
	s_nop 0
	global_load_lds_dwordx4 v[180:181], off
	s_waitcnt vmcnt(8)
	s_waitcnt lgkmcnt(0)
	s_barrier
	s_waitcnt lgkmcnt(0)
	v_mfma_f32_16x16x32_f16 v[62:65], v[148:151], v[196:199], v[62:65]
	v_mfma_f32_16x16x32_f16 v[58:61], v[156:159], v[196:199], v[58:61]
	v_mfma_f32_16x16x32_f16 v[46:49], v[148:151], v[208:211], v[46:49]
	v_mfma_f32_16x16x32_f16 v[42:45], v[156:159], v[208:211], v[42:45]
	v_mfma_f32_16x16x32_f16 v[28:31], v[148:151], v[216:219], v[28:31]
	v_mfma_f32_16x16x32_f16 v[24:27], v[156:159], v[216:219], v[24:27]
	v_mfma_f32_16x16x32_f16 v[12:15], v[148:151], v[224:227], v[12:15]
	v_mfma_f32_16x16x32_f16 v[8:11], v[156:159], v[224:227], v[8:11]
	v_mfma_f32_16x16x32_f16 v[62:65], v[152:155], v[204:207], v[62:65]
	v_mfma_f32_16x16x32_f16 v[58:61], v[160:163], v[204:207], v[58:61]
	v_mfma_f32_16x16x32_f16 v[46:49], v[152:155], v[212:215], v[46:49]
	v_mfma_f32_16x16x32_f16 v[42:45], v[160:163], v[212:215], v[42:45]
	v_mfma_f32_16x16x32_f16 v[28:31], v[152:155], v[220:223], v[28:31]
	v_mfma_f32_16x16x32_f16 v[24:27], v[160:163], v[220:223], v[24:27]
	v_mfma_f32_16x16x32_f16 v[12:15], v[152:155], v[228:231], v[12:15]
	v_mfma_f32_16x16x32_f16 v[8:11], v[160:163], v[228:231], v[8:11]
	v_mfma_f32_16x16x32_f16 v[54:57], v[164:167], v[196:199], v[54:57]
	v_mfma_f32_16x16x32_f16 v[50:53], v[172:175], v[196:199], v[50:53]
	v_mfma_f32_16x16x32_f16 v[38:41], v[164:167], v[208:211], v[38:41]
	v_mfma_f32_16x16x32_f16 v[34:37], v[172:175], v[208:211], v[34:37]
	v_mfma_f32_16x16x32_f16 v[20:23], v[164:167], v[216:219], v[20:23]
	v_mfma_f32_16x16x32_f16 v[16:19], v[172:175], v[216:219], v[16:19]
	v_mfma_f32_16x16x32_f16 v[4:7], v[164:167], v[224:227], v[4:7]
	v_mfma_f32_16x16x32_f16 v[0:3], v[172:175], v[224:227], v[0:3]
	v_mfma_f32_16x16x32_f16 v[54:57], v[168:171], v[204:207], v[54:57]
	v_mfma_f32_16x16x32_f16 v[50:53], v[176:179], v[204:207], v[50:53]
	v_mfma_f32_16x16x32_f16 v[38:41], v[168:171], v[212:215], v[38:41]
	v_mfma_f32_16x16x32_f16 v[34:37], v[176:179], v[212:215], v[34:37]
	v_mfma_f32_16x16x32_f16 v[20:23], v[168:171], v[220:223], v[20:23]
	v_mfma_f32_16x16x32_f16 v[16:19], v[176:179], v[220:223], v[16:19]
	v_mfma_f32_16x16x32_f16 v[4:7], v[168:171], v[228:231], v[4:7]
	v_mfma_f32_16x16x32_f16 v[0:3], v[176:179], v[228:231], v[0:3]
	s_barrier
	s_add_i32 s75, s75, 2
	s_add_u32 s72, s72, 0x100
	s_addc_u32 s73, s73, 0
	s_add_u32 s18, s18, 0x100
	s_addc_u32 s19, s19, 0
	s_cmp_gt_u32 s75, 13
	s_cbranch_scc0 .LBB0_214
	s_setprio 0
	s_and_b64 vcc, exec, s[6:7]
	s_cbranch_vccnz .LBB0_219
	v_lshl_add_u32 v148, s68, 8, v144
	s_cmp_gt_i32 s69, 3
	s_mov_b64 s[18:19], -1
	s_cbranch_scc1 .LBB0_220

; #define PG8_STAGE(bufoff, gbase, voff) do { _Pragma("unroll") for (int _i = 0; _i < 2; ++_i) \
;         __builtin_amdgcn_global_load_lds((const unsigned*)((const char*)(gbase) + (voff)[_i]), (LAS unsigned*)(lds + (bufoff) + ldsw + _i * 8192), 16, 0, 0); } while (0)
; #define PG8_LDA(dst, b, h) do { _Pragma("unroll") for (int m = 0; m < 4; ++m) _Pragma("unroll") for (int k = 0; k < 2; ++k) dst[m][k] = *(const LAS h16x8*)(lds + PG8_SA(b, h) + aoff + m * 2048 + k * 1024); } while (0)
; #define PG8_LDB(dst, b, h) do { _Pragma("unroll") for (int n = 0; n < 2; ++n) _Pragma("unroll") for (int k = 0; k < 2; ++k) dst[n][k] = *(const LAS h16x8*)(lds + PG8_SB(b, h) + boff + n * 2048 + k * 1024); } while (0)
; #define PG8_MMA(ai, bj, At, Bt) do { __builtin_amdgcn_s_setprio(1); _Pragma("unroll") for (int m = 0; m < 4; ++m) _Pragma("unroll") for (int n = 0; n < 2; ++n) _Pragma("unroll") for (int k = 0; k < 2; ++k) \
;         acc[ai][bj][m][n] = __builtin_amdgcn_mfma_f32_16x16x32_f16(Bt[n][k], At[m][k], acc[ai][bj][m][n], 0, 0, 0); __builtin_amdgcn_s_setprio(0); } while (0)
; #define PG8_WAIT_V(n) asm volatile("s_waitcnt vmcnt(" #n ")" ::: "memory")
; #define PG8_WAIT_L(n) asm volatile("s_waitcnt lgkmcnt(" #n ")" ::: "memory")
; #define PG8_BAR __builtin_amdgcn_s_barrier()
; template <class Epi>
; __device__ __forceinline__ void gemm_phase(LAS unsigned char* lds, const Gemm g, const StaticOrder& S, const Epi& E) {
;     ...
;         for (int t = 0; t < nt; t += 2) {
;             const bool last = (t == nt - 2);
;             const char* a1 = cA + (size_t)(t + 1) * kstep;
;             const char* a2 = last ? nA : cA + (size_t)(t + 2) * kstep; const char* b2 = last ? nB : cB + (size_t)(t + 2) * kstep;
;             const char* a3 = a2 + kstep; const char* b3 = b2 + kstep;
;             PG8_LDB(B0, 0, 0); PG8_LDB(B1, 0, 1); PG8_SCHED; PG8_LDA(At, 0, 0); PG8_STAGE(PG8_SA(1, 1), a1 + hstepA, voffA);
;             PG8_WAIT_V(8); PG8_WAIT_L(0); PG8_BAR; PG8_MMA(0, 0, At, B0); PG8_MMA(0, 1, At, B1); PG8_BAR; PG8_SCHED;
;     ...
; #pragma unroll
;         for (int a = 0; a < 2; ++a)
; #pragma unroll
;             for (int b = 0; b < 2; ++b)
; #pragma unroll
;                 for (int m = 0; m < 4; ++m)
; #pragma unroll
;                     for (int n = 0; n < 2; ++n) acc[a][b][m][n] = (f32x4){0.f, 0.f, 0.f, 0.f};
;         cur = nxt; cA = nA; cB = nB; ++ui;
.LBB0_563:
	s_add_u32 s30, s26, 0x100
	s_addc_u32 s31, s27, 0
	s_add_u32 s26, s28, 0x80
	v_mov_b32_e32 v0, 0
	s_addc_u32 s27, s29, 0
	s_mov_b32 s28, 0
	v_mov_b32_e32 v1, v0
	v_mov_b32_e32 v2, v0
	v_mov_b32_e32 v3, v0
	v_mov_b32_e32 v4, v0
	v_mov_b32_e32 v5, v0
	v_mov_b32_e32 v6, v0
	v_mov_b32_e32 v7, v0
	v_mov_b32_e32 v16, v0
	v_mov_b32_e32 v17, v0
	v_mov_b32_e32 v18, v0
	v_mov_b32_e32 v19, v0
	v_mov_b32_e32 v20, v0
	v_mov_b32_e32 v21, v0
	v_mov_b32_e32 v22, v0
	v_mov_b32_e32 v23, v0
	v_mov_b32_e32 v34, v0
	v_mov_b32_e32 v35, v0
	v_mov_b32_e32 v36, v0
	v_mov_b32_e32 v37, v0
	v_mov_b32_e32 v38, v0
	v_mov_b32_e32 v39, v0
	v_mov_b32_e32 v40, v0
	v_mov_b32_e32 v41, v0
	v_mov_b32_e32 v50, v0
	v_mov_b32_e32 v51, v0
	v_mov_b32_e32 v52, v0
	v_mov_b32_e32 v53, v0
	v_mov_b32_e32 v54, v0
	v_mov_b32_e32 v55, v0
	v_mov_b32_e32 v56, v0
	v_mov_b32_e32 v57, v0
	v_mov_b32_e32 v8, v0
	v_mov_b32_e32 v9, v0
	v_mov_b32_e32 v10, v0
	v_mov_b32_e32 v11, v0
	v_mov_b32_e32 v12, v0
	v_mov_b32_e32 v13, v0
	v_mov_b32_e32 v14, v0
	v_mov_b32_e32 v15, v0
	v_mov_b32_e32 v24, v0
	v_mov_b32_e32 v25, v0
	v_mov_b32_e32 v26, v0
	v_mov_b32_e32 v27, v0
	v_mov_b32_e32 v28, v0
	v_mov_b32_e32 v29, v0
	v_mov_b32_e32 v30, v0
	v_mov_b32_e32 v31, v0
	v_mov_b32_e32 v42, v0
	v_mov_b32_e32 v43, v0
	v_mov_b32_e32 v44, v0
	v_mov_b32_e32 v45, v0
	v_mov_b32_e32 v46, v0
	v_mov_b32_e32 v47, v0
	v_mov_b32_e32 v48, v0
	v_mov_b32_e32 v49, v0
	v_mov_b32_e32 v58, v0
	v_mov_b32_e32 v59, v0
	v_mov_b32_e32 v60, v0
	v_mov_b32_e32 v61, v0
	v_mov_b32_e32 v62, v0
	v_mov_b32_e32 v63, v0
	v_mov_b32_e32 v64, v0
	v_mov_b32_e32 v65, v0
	v_mov_b32_e32 v66, v0
	v_mov_b32_e32 v67, v0
	v_mov_b32_e32 v68, v0
	v_mov_b32_e32 v69, v0
	v_mov_b32_e32 v70, v0
	v_mov_b32_e32 v71, v0
	v_mov_b32_e32 v72, v0
	v_mov_b32_e32 v73, v0
	v_mov_b32_e32 v82, v0
	v_mov_b32_e32 v83, v0
	v_mov_b32_e32 v84, v0
	v_mov_b32_e32 v85, v0
	v_mov_b32_e32 v86, v0
	v_mov_b32_e32 v87, v0
	v_mov_b32_e32 v88, v0
	v_mov_b32_e32 v89, v0
	v_mov_b32_e32 v98, v0
	v_mov_b32_e32 v99, v0
	v_mov_b32_e32 v100, v0
	v_mov_b32_e32 v101, v0
	v_mov_b32_e32 v102, v0
	v_mov_b32_e32 v103, v0
	v_mov_b32_e32 v104, v0
	v_mov_b32_e32 v105, v0
	v_mov_b32_e32 v114, v0
	v_mov_b32_e32 v115, v0
	v_mov_b32_e32 v116, v0
	v_mov_b32_e32 v117, v0
	v_mov_b32_e32 v118, v0
	v_mov_b32_e32 v119, v0
	v_mov_b32_e32 v120, v0
	v_mov_b32_e32 v121, v0
	v_mov_b32_e32 v74, v0
	v_mov_b32_e32 v75, v0
	v_mov_b32_e32 v76, v0
	v_mov_b32_e32 v77, v0
	v_mov_b32_e32 v78, v0
	v_mov_b32_e32 v79, v0
	v_mov_b32_e32 v80, v0
	v_mov_b32_e32 v81, v0
	v_mov_b32_e32 v90, v0
	v_mov_b32_e32 v91, v0
	v_mov_b32_e32 v92, v0
	v_mov_b32_e32 v93, v0
	v_mov_b32_e32 v94, v0
	v_mov_b32_e32 v95, v0
	v_mov_b32_e32 v96, v0
	v_mov_b32_e32 v97, v0
	v_mov_b32_e32 v106, v0
	v_mov_b32_e32 v107, v0
	v_mov_b32_e32 v108, v0
	v_mov_b32_e32 v109, v0
	v_mov_b32_e32 v110, v0
	v_mov_b32_e32 v111, v0
	v_mov_b32_e32 v112, v0
	v_mov_b32_e32 v113, v0
	v_mov_b32_e32 v122, v0
	v_mov_b32_e32 v123, v0
	v_mov_b32_e32 v124, v0
	v_mov_b32_e32 v125, v0
	v_mov_b32_e32 v126, v0
	v_mov_b32_e32 v127, v0
	v_mov_b32_e32 v128, v0
	v_mov_b32_e32 v129, v0
	s_cmp_eq_u64 s[20:21], 0
	s_cbranch_scc0 .Lprio_564
	s_setprio 1
.Lprio_564:
.LBB0_564:
	s_add_i32 s68, s28, 2
	s_add_u32 s69, s26, 0x80
	s_addc_u32 s29, s27, 0
	s_add_i32 vcc_lo, 0, 0x10000
	s_cmp_eq_u32 s79, s28
	s_cselect_b32 s29, s1, s29
	s_cselect_b32 s28, s0, s69
	v_add_u32_e32 v32, vcc_lo, v178
	s_cselect_b32 s71, s23, s31
	s_cselect_b32 s70, s22, s30
	s_add_i32 s69, 0, 0x14000
	ds_read_b128 v[148:151], v32
	ds_read_b128 v[152:155], v32 offset:1024
	ds_read_b128 v[156:159], v32 offset:2048
	ds_read_b128 v[160:163], v32 offset:3072
	v_add_u32_e32 v32, s69, v178
	ds_read_b128 v[164:167], v32
	ds_read_b128 v[168:171], v32 offset:1024
	ds_read_b128 v[172:175], v32 offset:2048
	ds_read_b128 v[208:211], v32 offset:3072
	v_lshl_add_u64 v[176:177], s[26:27], 0, v[146:147]
	s_add_i32 m0, s88, 0xc000
	ds_read_b128 v[212:215], v206
	ds_read_b128 v[216:219], v206 offset:1024
	ds_read_b128 v[220:223], v206 offset:2048
	ds_read_b128 v[224:227], v206 offset:3072
	ds_read_b128 v[228:231], v206 offset:4096
	ds_read_b128 v[232:235], v206 offset:5120
	ds_read_b128 v[236:239], v206 offset:6144
	ds_read_b128 v[240:243], v206 offset:7168
	global_load_lds_dwordx4 v[176:177], off
	v_lshl_add_u64 v[176:177], s[26:27], 0, v[144:145]
	s_add_i32 m0, s88, 0xe000
	s_nop 0
	global_load_lds_dwordx4 v[176:177], off
	s_waitcnt vmcnt(8)
	s_waitcnt lgkmcnt(0)
	s_barrier
	s_waitcnt lgkmcnt(0)
	v_mfma_f32_16x16x32_f16 v[126:129], v[148:151], v[212:215], v[126:129]
	v_mfma_f32_16x16x32_f16 v[122:125], v[156:159], v[212:215], v[122:125]
	v_mfma_f32_16x16x32_f16 v[110:113], v[148:151], v[220:223], v[110:113]
	v_mfma_f32_16x16x32_f16 v[106:109], v[156:159], v[220:223], v[106:109]
	v_mfma_f32_16x16x32_f16 v[94:97], v[148:151], v[228:231], v[94:97]
	v_mfma_f32_16x16x32_f16 v[90:93], v[156:159], v[228:231], v[90:93]
	v_mfma_f32_16x16x32_f16 v[78:81], v[148:151], v[236:239], v[78:81]
	v_mfma_f32_16x16x32_f16 v[74:77], v[156:159], v[236:239], v[74:77]
	v_mfma_f32_16x16x32_f16 v[126:129], v[152:155], v[216:219], v[126:129]
	v_mfma_f32_16x16x32_f16 v[122:125], v[160:163], v[216:219], v[122:125]
	v_mfma_f32_16x16x32_f16 v[110:113], v[152:155], v[224:227], v[110:113]
	v_mfma_f32_16x16x32_f16 v[106:109], v[160:163], v[224:227], v[106:109]
	v_mfma_f32_16x16x32_f16 v[94:97], v[152:155], v[232:235], v[94:97]
	v_mfma_f32_16x16x32_f16 v[90:93], v[160:163], v[232:235], v[90:93]
	v_mfma_f32_16x16x32_f16 v[78:81], v[152:155], v[240:243], v[78:81]
	v_mfma_f32_16x16x32_f16 v[74:77], v[160:163], v[240:243], v[74:77]
	v_mfma_f32_16x16x32_f16 v[118:121], v[164:167], v[212:215], v[118:121]
	v_mfma_f32_16x16x32_f16 v[114:117], v[172:175], v[212:215], v[114:117]
	v_mfma_f32_16x16x32_f16 v[102:105], v[164:167], v[220:223], v[102:105]
	v_mfma_f32_16x16x32_f16 v[98:101], v[172:175], v[220:223], v[98:101]
	v_mfma_f32_16x16x32_f16 v[86:89], v[164:167], v[228:231], v[86:89]
	v_mfma_f32_16x16x32_f16 v[82:85], v[172:175], v[228:231], v[82:85]
	v_mfma_f32_16x16x32_f16 v[70:73], v[164:167], v[236:239], v[70:73]
	v_mfma_f32_16x16x32_f16 v[66:69], v[172:175], v[236:239], v[66:69]
	v_mfma_f32_16x16x32_f16 v[118:121], v[168:171], v[216:219], v[118:121]
	v_mfma_f32_16x16x32_f16 v[114:117], v[208:211], v[216:219], v[114:117]
	v_mfma_f32_16x16x32_f16 v[102:105], v[168:171], v[224:227], v[102:105]
	v_mfma_f32_16x16x32_f16 v[98:101], v[208:211], v[224:227], v[98:101]
	v_mfma_f32_16x16x32_f16 v[86:89], v[168:171], v[232:235], v[86:89]
	v_mfma_f32_16x16x32_f16 v[82:85], v[208:211], v[232:235], v[82:85]
	v_mfma_f32_16x16x32_f16 v[70:73], v[168:171], v[240:243], v[70:73]
	v_mfma_f32_16x16x32_f16 v[66:69], v[208:211], v[240:243], v[66:69]
	s_barrier
; #define PG8_STAGE(bufoff, gbase, voff) do { _Pragma("unroll") for (int _i = 0; _i < 2; ++_i) \
;         __builtin_amdgcn_global_load_lds((const unsigned*)((const char*)(gbase) + (voff)[_i]), (LAS unsigned*)(lds + (bufoff) + ldsw + _i * 8192), 16, 0, 0); } while (0)
; #define PG8_LDA(dst, b, h) do { _Pragma("unroll") for (int m = 0; m < 4; ++m) _Pragma("unroll") for (int k = 0; k < 2; ++k) dst[m][k] = *(const LAS h16x8*)(lds + PG8_SA(b, h) + aoff + m * 2048 + k * 1024); } while (0)
; #define PG8_LDB(dst, b, h) do { _Pragma("unroll") for (int n = 0; n < 2; ++n) _Pragma("unroll") for (int k = 0; k < 2; ++k) dst[n][k] = *(const LAS h16x8*)(lds + PG8_SB(b, h) + boff + n * 2048 + k * 1024); } while (0)
; #define PG8_MMA(ai, bj, At, Bt) do { __builtin_amdgcn_s_setprio(1); _Pragma("unroll") for (int m = 0; m < 4; ++m) _Pragma("unroll") for (int n = 0; n < 2; ++n) _Pragma("unroll") for (int k = 0; k < 2; ++k) \
;         acc[ai][bj][m][n] = __builtin_amdgcn_mfma_f32_16x16x32_f16(Bt[n][k], At[m][k], acc[ai][bj][m][n], 0, 0, 0); __builtin_amdgcn_s_setprio(0); } while (0)
; #define PG8_WAIT_V(n) asm volatile("s_waitcnt vmcnt(" #n ")" ::: "memory")
; #define PG8_WAIT_L(n) asm volatile("s_waitcnt lgkmcnt(" #n ")" ::: "memory")
; #define PG8_BAR __builtin_amdgcn_s_barrier()
; #define PG8_SCHED __builtin_amdgcn_sched_barrier(0)
; template <class Epi>
; __device__ __forceinline__ void gemm_phase(LAS unsigned char* lds, const Gemm g, const StaticOrder& S, const Epi& E) {
;     ...
;             PG8_LDA(At, 0, 1); PG8_STAGE(PG8_SB(0, 0), b2, voffB); PG8_STAGE(PG8_SB(0, 1), b2 + hstepB, voffB); PG8_STAGE(PG8_SA(0, 0), a2, voffA);
;             PG8_WAIT_V(8); PG8_WAIT_L(0); PG8_BAR; PG8_MMA(1, 0, At, B0); PG8_MMA(1, 1, At, B1); PG8_BAR; PG8_SCHED;
;             PG8_LDB(B0, 1, 0); PG8_LDB(B1, 1, 1); PG8_SCHED; PG8_LDA(At, 1, 0); PG8_STAGE(PG8_SA(0, 1), a2 + hstepA, voffA);
;             PG8_WAIT_V(8); PG8_WAIT_L(0); PG8_BAR; PG8_MMA(0, 0, At, B0); PG8_MMA(0, 1, At, B1); PG8_BAR; PG8_SCHED;
	s_add_i32 vcc_lo, vcc_lo, s35
	v_lshl_add_u64 v[176:177], s[70:71], 0, v[132:133]
	s_mov_b32 m0, vcc_lo
	ds_read_b128 v[212:215], v206 offset:16384
	ds_read_b128 v[216:219], v206 offset:17408
	ds_read_b128 v[220:223], v206 offset:18432
	ds_read_b128 v[224:227], v206 offset:19456
	ds_read_b128 v[228:231], v206 offset:20480
	ds_read_b128 v[232:235], v206 offset:21504
	ds_read_b128 v[236:239], v206 offset:22528
	ds_read_b128 v[240:243], v206 offset:23552
	global_load_lds_dwordx4 v[176:177], off
	s_add_i32 m0, vcc_lo, 0x2000
	v_lshl_add_u64 v[196:197], s[70:71], 0, v[136:137]
	s_add_u32 s70, s70, s14
	s_addc_u32 s71, s71, 0
	s_add_i32 s69, s69, s35
	global_load_lds_dwordx4 v[196:197], off
	v_lshl_add_u64 v[198:199], s[70:71], 0, v[132:133]
	s_mov_b32 m0, s69
	v_lshl_add_u64 v[244:245], s[70:71], 0, v[136:137]
	global_load_lds_dwordx4 v[198:199], off
	s_add_i32 m0, s69, 0x2000
	v_lshl_add_u64 v[246:247], s[28:29], 0, v[130:131]
	global_load_lds_dwordx4 v[244:245], off
	s_mov_b32 m0, s88
	v_lshl_add_u64 v[248:249], s[28:29], 0, v[134:135]
	global_load_lds_dwordx4 v[246:247], off
	s_mov_b32 m0, s89
	s_nop 0
	global_load_lds_dwordx4 v[248:249], off
	s_waitcnt vmcnt(8)
	s_waitcnt lgkmcnt(0)
	s_barrier
	s_waitcnt lgkmcnt(0)
	v_mfma_f32_16x16x32_f16 v[62:65], v[148:151], v[212:215], v[62:65]
	v_mfma_f32_16x16x32_f16 v[58:61], v[156:159], v[212:215], v[58:61]
	v_mfma_f32_16x16x32_f16 v[46:49], v[148:151], v[220:223], v[46:49]
	v_mfma_f32_16x16x32_f16 v[42:45], v[156:159], v[220:223], v[42:45]
	v_mfma_f32_16x16x32_f16 v[28:31], v[148:151], v[228:231], v[28:31]
	v_mfma_f32_16x16x32_f16 v[24:27], v[156:159], v[228:231], v[24:27]
	v_mfma_f32_16x16x32_f16 v[12:15], v[148:151], v[236:239], v[12:15]
	v_mfma_f32_16x16x32_f16 v[8:11], v[156:159], v[236:239], v[8:11]
	v_mfma_f32_16x16x32_f16 v[62:65], v[152:155], v[216:219], v[62:65]
	v_mfma_f32_16x16x32_f16 v[58:61], v[160:163], v[216:219], v[58:61]
	v_mfma_f32_16x16x32_f16 v[46:49], v[152:155], v[224:227], v[46:49]
	v_mfma_f32_16x16x32_f16 v[42:45], v[160:163], v[224:227], v[42:45]
	v_mfma_f32_16x16x32_f16 v[28:31], v[152:155], v[232:235], v[28:31]
	v_mfma_f32_16x16x32_f16 v[24:27], v[160:163], v[232:235], v[24:27]
	v_mfma_f32_16x16x32_f16 v[12:15], v[152:155], v[240:243], v[12:15]
	v_mfma_f32_16x16x32_f16 v[8:11], v[160:163], v[240:243], v[8:11]
	v_mfma_f32_16x16x32_f16 v[54:57], v[164:167], v[212:215], v[54:57]
	v_mfma_f32_16x16x32_f16 v[50:53], v[172:175], v[212:215], v[50:53]
	v_mfma_f32_16x16x32_f16 v[38:41], v[164:167], v[220:223], v[38:41]
	v_mfma_f32_16x16x32_f16 v[34:37], v[172:175], v[220:223], v[34:37]
	v_mfma_f32_16x16x32_f16 v[20:23], v[164:167], v[228:231], v[20:23]
	v_mfma_f32_16x16x32_f16 v[16:19], v[172:175], v[228:231], v[16:19]
	v_mfma_f32_16x16x32_f16 v[4:7], v[164:167], v[236:239], v[4:7]
	v_mfma_f32_16x16x32_f16 v[0:3], v[172:175], v[236:239], v[0:3]
	v_mfma_f32_16x16x32_f16 v[54:57], v[168:171], v[216:219], v[54:57]
	v_mfma_f32_16x16x32_f16 v[50:53], v[208:211], v[216:219], v[50:53]
	v_mfma_f32_16x16x32_f16 v[38:41], v[168:171], v[224:227], v[38:41]
	v_mfma_f32_16x16x32_f16 v[34:37], v[208:211], v[224:227], v[34:37]
	v_mfma_f32_16x16x32_f16 v[20:23], v[168:171], v[232:235], v[20:23]
	v_mfma_f32_16x16x32_f16 v[16:19], v[208:211], v[232:235], v[16:19]
	v_mfma_f32_16x16x32_f16 v[4:7], v[168:171], v[240:243], v[4:7]
	v_mfma_f32_16x16x32_f16 v[0:3], v[208:211], v[240:243], v[0:3]
	s_barrier
	s_add_i32 s69, 0, 0x18000
	v_add_u32_e32 v32, s69, v178
	s_add_i32 s70, 0, 0x1c000
	ds_read_b128 v[148:151], v32
	ds_read_b128 v[152:155], v32 offset:1024
	ds_read_b128 v[156:159], v32 offset:2048
	ds_read_b128 v[160:163], v32 offset:3072
	v_add_u32_e32 v32, s70, v178
	ds_read_b128 v[164:167], v32
	ds_read_b128 v[168:171], v32 offset:1024
	ds_read_b128 v[172:175], v32 offset:2048
	ds_read_b128 v[208:211], v32 offset:3072
	s_add_u32 s28, s28, s14
	s_addc_u32 s29, s29, 0
	s_mov_b32 m0, s92
	v_lshl_add_u64 v[250:251], s[28:29], 0, v[130:131]
	ds_read_b128 v[212:215], v206 offset:32768
	ds_read_b128 v[216:219], v206 offset:33792
	ds_read_b128 v[220:223], v206 offset:34816
	ds_read_b128 v[224:227], v206 offset:35840
	ds_read_b128 v[228:231], v206 offset:36864
	ds_read_b128 v[232:235], v206 offset:37888
	ds_read_b128 v[236:239], v206 offset:38912
	ds_read_b128 v[240:243], v206 offset:39936
	global_load_lds_dwordx4 v[250:251], off
	v_lshl_add_u64 v[250:251], s[28:29], 0, v[134:135]
	s_mov_b32 m0, s93
	s_nop 0
	global_load_lds_dwordx4 v[250:251], off
	s_waitcnt vmcnt(8)
	s_waitcnt lgkmcnt(0)
	s_barrier
; #define PG8_STAGE(bufoff, gbase, voff) do { _Pragma("unroll") for (int _i = 0; _i < 2; ++_i) \
;         __builtin_amdgcn_global_load_lds((const unsigned*)((const char*)(gbase) + (voff)[_i]), (LAS unsigned*)(lds + (bufoff) + ldsw + _i * 8192), 16, 0, 0); } while (0)
; #define PG8_LDA(dst, b, h) do { _Pragma("unroll") for (int m = 0; m < 4; ++m) _Pragma("unroll") for (int k = 0; k < 2; ++k) dst[m][k] = *(const LAS h16x8*)(lds + PG8_SA(b, h) + aoff + m * 2048 + k * 1024); } while (0)
; #define PG8_MMA(ai, bj, At, Bt) do { __builtin_amdgcn_s_setprio(1); _Pragma("unroll") for (int m = 0; m < 4; ++m) _Pragma("unroll") for (int n = 0; n < 2; ++n) _Pragma("unroll") for (int k = 0; k < 2; ++k) \
;         acc[ai][bj][m][n] = __builtin_amdgcn_mfma_f32_16x16x32_f16(Bt[n][k], At[m][k], acc[ai][bj][m][n], 0, 0, 0); __builtin_amdgcn_s_setprio(0); } while (0)
; #define PG8_WAIT_V(n) asm volatile("s_waitcnt vmcnt(" #n ")" ::: "memory")
; #define PG8_WAIT_L(n) asm volatile("s_waitcnt lgkmcnt(" #n ")" ::: "memory")
; #define PG8_BAR __builtin_amdgcn_s_barrier()
; #define PG8_SCHED __builtin_amdgcn_sched_barrier(0)
; template <class Epi>
; __device__ __forceinline__ void gemm_phase(LAS unsigned char* lds, const Gemm g, const StaticOrder& S, const Epi& E) {
;     ...
;             PG8_WAIT_V(8); PG8_WAIT_L(0); PG8_BAR; PG8_MMA(0, 0, At, B0); PG8_MMA(0, 1, At, B1); PG8_BAR; PG8_SCHED;
;             PG8_LDA(At, 1, 1); PG8_STAGE(PG8_SB(1, 0), b3, voffB); PG8_STAGE(PG8_SB(1, 1), b3 + hstepB, voffB); PG8_STAGE(PG8_SA(1, 0), a3, voffA);
;             PG8_WAIT_V(8); PG8_WAIT_L(0); PG8_BAR; PG8_MMA(1, 0, At, B0); PG8_MMA(1, 1, At, B1); PG8_BAR; PG8_SCHED;
;         }
;         if (wr == 0) PG8_BAR;
	s_waitcnt lgkmcnt(0)
	v_mfma_f32_16x16x32_f16 v[126:129], v[148:151], v[212:215], v[126:129]
	v_mfma_f32_16x16x32_f16 v[122:125], v[156:159], v[212:215], v[122:125]
	v_mfma_f32_16x16x32_f16 v[110:113], v[148:151], v[220:223], v[110:113]
	v_mfma_f32_16x16x32_f16 v[106:109], v[156:159], v[220:223], v[106:109]
	v_mfma_f32_16x16x32_f16 v[94:97], v[148:151], v[228:231], v[94:97]
	v_mfma_f32_16x16x32_f16 v[90:93], v[156:159], v[228:231], v[90:93]
	v_mfma_f32_16x16x32_f16 v[78:81], v[148:151], v[236:239], v[78:81]
	v_mfma_f32_16x16x32_f16 v[74:77], v[156:159], v[236:239], v[74:77]
	v_mfma_f32_16x16x32_f16 v[126:129], v[152:155], v[216:219], v[126:129]
	v_mfma_f32_16x16x32_f16 v[122:125], v[160:163], v[216:219], v[122:125]
	v_mfma_f32_16x16x32_f16 v[110:113], v[152:155], v[224:227], v[110:113]
	v_mfma_f32_16x16x32_f16 v[106:109], v[160:163], v[224:227], v[106:109]
	v_mfma_f32_16x16x32_f16 v[94:97], v[152:155], v[232:235], v[94:97]
	v_mfma_f32_16x16x32_f16 v[90:93], v[160:163], v[232:235], v[90:93]
	v_mfma_f32_16x16x32_f16 v[78:81], v[152:155], v[240:243], v[78:81]
	v_mfma_f32_16x16x32_f16 v[74:77], v[160:163], v[240:243], v[74:77]
	v_mfma_f32_16x16x32_f16 v[118:121], v[164:167], v[212:215], v[118:121]
	v_mfma_f32_16x16x32_f16 v[114:117], v[172:175], v[212:215], v[114:117]
	v_mfma_f32_16x16x32_f16 v[102:105], v[164:167], v[220:223], v[102:105]
	v_mfma_f32_16x16x32_f16 v[98:101], v[172:175], v[220:223], v[98:101]
	v_mfma_f32_16x16x32_f16 v[86:89], v[164:167], v[228:231], v[86:89]
	v_mfma_f32_16x16x32_f16 v[82:85], v[172:175], v[228:231], v[82:85]
	v_mfma_f32_16x16x32_f16 v[70:73], v[164:167], v[236:239], v[70:73]
	v_mfma_f32_16x16x32_f16 v[66:69], v[172:175], v[236:239], v[66:69]
	v_mfma_f32_16x16x32_f16 v[118:121], v[168:171], v[216:219], v[118:121]
	v_mfma_f32_16x16x32_f16 v[114:117], v[208:211], v[216:219], v[114:117]
	v_mfma_f32_16x16x32_f16 v[102:105], v[168:171], v[224:227], v[102:105]
	v_mfma_f32_16x16x32_f16 v[98:101], v[208:211], v[224:227], v[98:101]
	v_mfma_f32_16x16x32_f16 v[86:89], v[168:171], v[232:235], v[86:89]
	v_mfma_f32_16x16x32_f16 v[82:85], v[208:211], v[232:235], v[82:85]
	v_mfma_f32_16x16x32_f16 v[70:73], v[168:171], v[240:243], v[70:73]
	v_mfma_f32_16x16x32_f16 v[66:69], v[208:211], v[240:243], v[66:69]
	s_barrier
	s_add_i32 s28, s69, s35
	v_lshl_add_u64 v[176:177], v[176:177], 0, s[90:91]
	s_mov_b32 m0, s28
	ds_read_b128 v[212:215], v206 offset:49152
	ds_read_b128 v[216:219], v206 offset:50176
	ds_read_b128 v[220:223], v206 offset:51200
	ds_read_b128 v[224:227], v206 offset:52224
	ds_read_b128 v[228:231], v206 offset:53248
	ds_read_b128 v[232:235], v206 offset:54272
	ds_read_b128 v[236:239], v206 offset:55296
	ds_read_b128 v[240:243], v206 offset:56320
	global_load_lds_dwordx4 v[176:177], off
	v_lshl_add_u64 v[176:177], v[196:197], 0, s[90:91]
	s_add_i32 m0, s28, 0x2000
	s_add_i32 s28, s70, s35
	global_load_lds_dwordx4 v[176:177], off
	v_lshl_add_u64 v[176:177], v[198:199], 0, s[90:91]
	s_mov_b32 m0, s28
	s_nop 0
	global_load_lds_dwordx4 v[176:177], off
	v_lshl_add_u64 v[176:177], v[244:245], 0, s[90:91]
	s_add_i32 m0, s28, 0x2000
	s_nop 0
	global_load_lds_dwordx4 v[176:177], off
	v_lshl_add_u64 v[176:177], v[246:247], 0, s[90:91]
	s_mov_b32 m0, s75
	s_nop 0
	global_load_lds_dwordx4 v[176:177], off
	v_lshl_add_u64 v[176:177], v[248:249], 0, s[90:91]
	s_mov_b32 m0, s81
	s_nop 0
	global_load_lds_dwordx4 v[176:177], off
	s_waitcnt vmcnt(8)
	s_waitcnt lgkmcnt(0)
	s_barrier
	s_waitcnt lgkmcnt(0)
	v_mfma_f32_16x16x32_f16 v[62:65], v[148:151], v[212:215], v[62:65]
	v_mfma_f32_16x16x32_f16 v[58:61], v[156:159], v[212:215], v[58:61]
	v_mfma_f32_16x16x32_f16 v[46:49], v[148:151], v[220:223], v[46:49]
	v_mfma_f32_16x16x32_f16 v[42:45], v[156:159], v[220:223], v[42:45]
	v_mfma_f32_16x16x32_f16 v[28:31], v[148:151], v[228:231], v[28:31]
	v_mfma_f32_16x16x32_f16 v[24:27], v[156:159], v[228:231], v[24:27]
	v_mfma_f32_16x16x32_f16 v[12:15], v[148:151], v[236:239], v[12:15]
	v_mfma_f32_16x16x32_f16 v[8:11], v[156:159], v[236:239], v[8:11]
	v_mfma_f32_16x16x32_f16 v[62:65], v[152:155], v[216:219], v[62:65]
	v_mfma_f32_16x16x32_f16 v[58:61], v[160:163], v[216:219], v[58:61]
	v_mfma_f32_16x16x32_f16 v[46:49], v[152:155], v[224:227], v[46:49]
	v_mfma_f32_16x16x32_f16 v[42:45], v[160:163], v[224:227], v[42:45]
	v_mfma_f32_16x16x32_f16 v[28:31], v[152:155], v[232:235], v[28:31]
	v_mfma_f32_16x16x32_f16 v[24:27], v[160:163], v[232:235], v[24:27]
	v_mfma_f32_16x16x32_f16 v[12:15], v[152:155], v[240:243], v[12:15]
	v_mfma_f32_16x16x32_f16 v[8:11], v[160:163], v[240:243], v[8:11]
	v_mfma_f32_16x16x32_f16 v[54:57], v[164:167], v[212:215], v[54:57]
	v_mfma_f32_16x16x32_f16 v[50:53], v[172:175], v[212:215], v[50:53]
	v_mfma_f32_16x16x32_f16 v[38:41], v[164:167], v[220:223], v[38:41]
	v_mfma_f32_16x16x32_f16 v[34:37], v[172:175], v[220:223], v[34:37]
	v_mfma_f32_16x16x32_f16 v[20:23], v[164:167], v[228:231], v[20:23]
	v_mfma_f32_16x16x32_f16 v[16:19], v[172:175], v[228:231], v[16:19]
	v_mfma_f32_16x16x32_f16 v[4:7], v[164:167], v[236:239], v[4:7]
	v_mfma_f32_16x16x32_f16 v[0:3], v[172:175], v[236:239], v[0:3]
	v_mfma_f32_16x16x32_f16 v[54:57], v[168:171], v[216:219], v[54:57]
	v_mfma_f32_16x16x32_f16 v[50:53], v[208:211], v[216:219], v[50:53]
	v_mfma_f32_16x16x32_f16 v[38:41], v[168:171], v[224:227], v[38:41]
	v_mfma_f32_16x16x32_f16 v[34:37], v[208:211], v[224:227], v[34:37]
	v_mfma_f32_16x16x32_f16 v[20:23], v[168:171], v[232:235], v[20:23]
	v_mfma_f32_16x16x32_f16 v[16:19], v[208:211], v[232:235], v[16:19]
	v_mfma_f32_16x16x32_f16 v[4:7], v[168:171], v[240:243], v[4:7]
	v_mfma_f32_16x16x32_f16 v[0:3], v[208:211], v[240:243], v[0:3]
	s_barrier
	s_add_u32 s30, s30, 0x100
	s_addc_u32 s31, s31, 0
	s_add_u32 s26, s26, 0x100
	s_addc_u32 s27, s27, 0
	s_cmp_ge_u32 s68, s80
	s_mov_b32 s28, s68
	s_cbranch_scc0 .LBB0_564
	s_setprio 0
	s_and_b64 vcc, exec, s[20:21]
	s_cbranch_vccz .LBB0_567
	s_barrier

; #define PG8_STAGE(bufoff, gbase, voff) do { _Pragma("unroll") for (int _i = 0; _i < 2; ++_i) \
;         __builtin_amdgcn_global_load_lds((const unsigned*)((const char*)(gbase) + (voff)[_i]), (LAS unsigned*)(lds + (bufoff) + ldsw + _i * 8192), 16, 0, 0); } while (0)
; #define PG8_LDA(dst, b, h) do { _Pragma("unroll") for (int m = 0; m < 4; ++m) _Pragma("unroll") for (int k = 0; k < 2; ++k) dst[m][k] = *(const LAS h16x8*)(lds + PG8_SA(b, h) + aoff + m * 2048 + k * 1024); } while (0)
; #define PG8_LDB(dst, b, h) do { _Pragma("unroll") for (int n = 0; n < 2; ++n) _Pragma("unroll") for (int k = 0; k < 2; ++k) dst[n][k] = *(const LAS h16x8*)(lds + PG8_SB(b, h) + boff + n * 2048 + k * 1024); } while (0)
; #define PG8_MMA(ai, bj, At, Bt) do { __builtin_amdgcn_s_setprio(1); _Pragma("unroll") for (int m = 0; m < 4; ++m) _Pragma("unroll") for (int n = 0; n < 2; ++n) _Pragma("unroll") for (int k = 0; k < 2; ++k) \
;         acc[ai][bj][m][n] = __builtin_amdgcn_mfma_f32_16x16x32_f16(Bt[n][k], At[m][k], acc[ai][bj][m][n], 0, 0, 0); __builtin_amdgcn_s_setprio(0); } while (0)
; #define PG8_WAIT_V(n) asm volatile("s_waitcnt vmcnt(" #n ")" ::: "memory")
; #define PG8_WAIT_L(n) asm volatile("s_waitcnt lgkmcnt(" #n ")" ::: "memory")
; #define PG8_BAR __builtin_amdgcn_s_barrier()
; template <class Epi>
; __device__ __forceinline__ void gemm_phase(LAS unsigned char* lds, const Gemm g, const StaticOrder& S, const Epi& E) {
;     ...
;         for (int t = 0; t < nt; t += 2) {
;             const bool last = (t == nt - 2);
;             const char* a1 = cA + (size_t)(t + 1) * kstep;
;             const char* a2 = last ? nA : cA + (size_t)(t + 2) * kstep; const char* b2 = last ? nB : cB + (size_t)(t + 2) * kstep;
;             const char* a3 = a2 + kstep; const char* b3 = b2 + kstep;
;             PG8_LDB(B0, 0, 0); PG8_LDB(B1, 0, 1); PG8_SCHED; PG8_LDA(At, 0, 0); PG8_STAGE(PG8_SA(1, 1), a1 + hstepA, voffA);
;             PG8_WAIT_V(8); PG8_WAIT_L(0); PG8_BAR; PG8_MMA(0, 0, At, B0); PG8_MMA(0, 1, At, B1); PG8_BAR; PG8_SCHED;
;     ...
; #pragma unroll
;         for (int a = 0; a < 2; ++a)
; #pragma unroll
;             for (int b = 0; b < 2; ++b)
; #pragma unroll
;                 for (int m = 0; m < 4; ++m)
; #pragma unroll
;                     for (int n = 0; n < 2; ++n) acc[a][b][m][n] = (f32x4){0.f, 0.f, 0.f, 0.f};
;         cur = nxt; cA = nA; cB = nB; ++ui;
.LBB0_630:
	s_add_u32 s28, s22, 0x100
	s_addc_u32 s29, s23, 0
	s_add_u32 s22, s26, 0x80
	v_mov_b32_e32 v0, 0
	s_addc_u32 s23, s27, 0
	s_mov_b32 s26, 0
	v_mov_b32_e32 v1, v0
	v_mov_b32_e32 v2, v0
	v_mov_b32_e32 v3, v0
	v_mov_b32_e32 v4, v0
	v_mov_b32_e32 v5, v0
	v_mov_b32_e32 v6, v0
	v_mov_b32_e32 v7, v0
	v_mov_b32_e32 v16, v0
	v_mov_b32_e32 v17, v0
	v_mov_b32_e32 v18, v0
	v_mov_b32_e32 v19, v0
	v_mov_b32_e32 v20, v0
	v_mov_b32_e32 v21, v0
	v_mov_b32_e32 v22, v0
	v_mov_b32_e32 v23, v0
	v_mov_b32_e32 v34, v0
	v_mov_b32_e32 v35, v0
	v_mov_b32_e32 v36, v0
	v_mov_b32_e32 v37, v0
	v_mov_b32_e32 v38, v0
	v_mov_b32_e32 v39, v0
	v_mov_b32_e32 v40, v0
	v_mov_b32_e32 v41, v0
	v_mov_b32_e32 v50, v0
	v_mov_b32_e32 v51, v0
	v_mov_b32_e32 v52, v0
	v_mov_b32_e32 v53, v0
	v_mov_b32_e32 v54, v0
	v_mov_b32_e32 v55, v0
	v_mov_b32_e32 v56, v0
	v_mov_b32_e32 v57, v0
	v_mov_b32_e32 v8, v0
	v_mov_b32_e32 v9, v0
	v_mov_b32_e32 v10, v0
	v_mov_b32_e32 v11, v0
	v_mov_b32_e32 v12, v0
	v_mov_b32_e32 v13, v0
	v_mov_b32_e32 v14, v0
	v_mov_b32_e32 v15, v0
	v_mov_b32_e32 v24, v0
	v_mov_b32_e32 v25, v0
	v_mov_b32_e32 v26, v0
	v_mov_b32_e32 v27, v0
	v_mov_b32_e32 v28, v0
	v_mov_b32_e32 v29, v0
	v_mov_b32_e32 v30, v0
	v_mov_b32_e32 v31, v0
	v_mov_b32_e32 v42, v0
	v_mov_b32_e32 v43, v0
	v_mov_b32_e32 v44, v0
	v_mov_b32_e32 v45, v0
	v_mov_b32_e32 v46, v0
	v_mov_b32_e32 v47, v0
	v_mov_b32_e32 v48, v0
	v_mov_b32_e32 v49, v0
	v_mov_b32_e32 v58, v0
	v_mov_b32_e32 v59, v0
	v_mov_b32_e32 v60, v0
	v_mov_b32_e32 v61, v0
	v_mov_b32_e32 v62, v0
	v_mov_b32_e32 v63, v0
	v_mov_b32_e32 v64, v0
	v_mov_b32_e32 v65, v0
	v_mov_b32_e32 v66, v0
	v_mov_b32_e32 v67, v0
	v_mov_b32_e32 v68, v0
	v_mov_b32_e32 v69, v0
	v_mov_b32_e32 v70, v0
	v_mov_b32_e32 v71, v0
	v_mov_b32_e32 v72, v0
	v_mov_b32_e32 v73, v0
	v_mov_b32_e32 v82, v0
	v_mov_b32_e32 v83, v0
	v_mov_b32_e32 v84, v0
	v_mov_b32_e32 v85, v0
	v_mov_b32_e32 v86, v0
	v_mov_b32_e32 v87, v0
	v_mov_b32_e32 v88, v0
	v_mov_b32_e32 v89, v0
	v_mov_b32_e32 v98, v0
	v_mov_b32_e32 v99, v0
	v_mov_b32_e32 v100, v0
	v_mov_b32_e32 v101, v0
	v_mov_b32_e32 v102, v0
	v_mov_b32_e32 v103, v0
	v_mov_b32_e32 v104, v0
	v_mov_b32_e32 v105, v0
	v_mov_b32_e32 v114, v0
	v_mov_b32_e32 v115, v0
	v_mov_b32_e32 v116, v0
	v_mov_b32_e32 v117, v0
	v_mov_b32_e32 v118, v0
	v_mov_b32_e32 v119, v0
	v_mov_b32_e32 v120, v0
	v_mov_b32_e32 v121, v0
	v_mov_b32_e32 v74, v0
	v_mov_b32_e32 v75, v0
	v_mov_b32_e32 v76, v0
	v_mov_b32_e32 v77, v0
	v_mov_b32_e32 v78, v0
	v_mov_b32_e32 v79, v0
	v_mov_b32_e32 v80, v0
	v_mov_b32_e32 v81, v0
	v_mov_b32_e32 v90, v0
	v_mov_b32_e32 v91, v0
	v_mov_b32_e32 v92, v0
	v_mov_b32_e32 v93, v0
	v_mov_b32_e32 v94, v0
	v_mov_b32_e32 v95, v0
	v_mov_b32_e32 v96, v0
	v_mov_b32_e32 v97, v0
	v_mov_b32_e32 v106, v0
	v_mov_b32_e32 v107, v0
	v_mov_b32_e32 v108, v0
	v_mov_b32_e32 v109, v0
	v_mov_b32_e32 v110, v0
	v_mov_b32_e32 v111, v0
	v_mov_b32_e32 v112, v0
	v_mov_b32_e32 v113, v0
	v_mov_b32_e32 v122, v0
	v_mov_b32_e32 v123, v0
	v_mov_b32_e32 v124, v0
	v_mov_b32_e32 v125, v0
	v_mov_b32_e32 v126, v0
	v_mov_b32_e32 v127, v0
	v_mov_b32_e32 v128, v0
	v_mov_b32_e32 v129, v0
	s_cmp_eq_u64 s[18:19], 0
	s_cbranch_scc0 .Lprio_631
	s_setprio 1
.Lprio_631:
.LBB0_631:
	s_add_i32 s30, s26, 2
	s_add_u32 s31, s22, 0x80
	s_addc_u32 s27, s23, 0
	s_add_i32 vcc_lo, 0, 0x10000
	s_cmp_eq_u32 s76, s26
	s_cselect_b32 s27, s1, s27
	s_cselect_b32 s26, s0, s31
	v_add_u32_e32 v32, vcc_lo, v174
	s_cselect_b32 s69, s21, s29
	s_cselect_b32 s68, s20, s28
	s_add_i32 s31, 0, 0x14000
	ds_read_b128 v[144:147], v32
	ds_read_b128 v[148:151], v32 offset:1024
	ds_read_b128 v[152:155], v32 offset:2048
	ds_read_b128 v[156:159], v32 offset:3072
	v_add_u32_e32 v32, s31, v174
	ds_read_b128 v[160:163], v32
	ds_read_b128 v[164:167], v32 offset:1024
	ds_read_b128 v[168:171], v32 offset:2048
	ds_read_b128 v[204:207], v32 offset:3072
	v_lshl_add_u64 v[172:173], s[22:23], 0, v[142:143]
	s_add_i32 m0, s54, 0xc000
	ds_read_b128 v[208:211], v190
	ds_read_b128 v[212:215], v190 offset:1024
	ds_read_b128 v[216:219], v190 offset:2048
	ds_read_b128 v[220:223], v190 offset:3072
	ds_read_b128 v[224:227], v190 offset:4096
	ds_read_b128 v[228:231], v190 offset:5120
	ds_read_b128 v[232:235], v190 offset:6144
	ds_read_b128 v[236:239], v190 offset:7168
	global_load_lds_dwordx4 v[172:173], off
	v_lshl_add_u64 v[172:173], s[22:23], 0, v[140:141]
	s_add_i32 m0, s54, 0xe000
	s_nop 0
	global_load_lds_dwordx4 v[172:173], off
	s_waitcnt vmcnt(8)
	s_waitcnt lgkmcnt(0)
	s_barrier
	s_waitcnt lgkmcnt(0)
	v_mfma_f32_16x16x32_f16 v[126:129], v[144:147], v[208:211], v[126:129]
	v_mfma_f32_16x16x32_f16 v[122:125], v[152:155], v[208:211], v[122:125]
	v_mfma_f32_16x16x32_f16 v[110:113], v[144:147], v[216:219], v[110:113]
	v_mfma_f32_16x16x32_f16 v[106:109], v[152:155], v[216:219], v[106:109]
	v_mfma_f32_16x16x32_f16 v[94:97], v[144:147], v[224:227], v[94:97]
	v_mfma_f32_16x16x32_f16 v[90:93], v[152:155], v[224:227], v[90:93]
	v_mfma_f32_16x16x32_f16 v[78:81], v[144:147], v[232:235], v[78:81]
	v_mfma_f32_16x16x32_f16 v[74:77], v[152:155], v[232:235], v[74:77]
	v_mfma_f32_16x16x32_f16 v[126:129], v[148:151], v[212:215], v[126:129]
	v_mfma_f32_16x16x32_f16 v[122:125], v[156:159], v[212:215], v[122:125]
	v_mfma_f32_16x16x32_f16 v[110:113], v[148:151], v[220:223], v[110:113]
	v_mfma_f32_16x16x32_f16 v[106:109], v[156:159], v[220:223], v[106:109]
	v_mfma_f32_16x16x32_f16 v[94:97], v[148:151], v[228:231], v[94:97]
	v_mfma_f32_16x16x32_f16 v[90:93], v[156:159], v[228:231], v[90:93]
	v_mfma_f32_16x16x32_f16 v[78:81], v[148:151], v[236:239], v[78:81]
	v_mfma_f32_16x16x32_f16 v[74:77], v[156:159], v[236:239], v[74:77]
	v_mfma_f32_16x16x32_f16 v[118:121], v[160:163], v[208:211], v[118:121]
	v_mfma_f32_16x16x32_f16 v[114:117], v[168:171], v[208:211], v[114:117]
	v_mfma_f32_16x16x32_f16 v[102:105], v[160:163], v[216:219], v[102:105]
	v_mfma_f32_16x16x32_f16 v[98:101], v[168:171], v[216:219], v[98:101]
	v_mfma_f32_16x16x32_f16 v[86:89], v[160:163], v[224:227], v[86:89]
	v_mfma_f32_16x16x32_f16 v[82:85], v[168:171], v[224:227], v[82:85]
	v_mfma_f32_16x16x32_f16 v[70:73], v[160:163], v[232:235], v[70:73]
	v_mfma_f32_16x16x32_f16 v[66:69], v[168:171], v[232:235], v[66:69]
	v_mfma_f32_16x16x32_f16 v[118:121], v[164:167], v[212:215], v[118:121]
	v_mfma_f32_16x16x32_f16 v[114:117], v[204:207], v[212:215], v[114:117]
	v_mfma_f32_16x16x32_f16 v[102:105], v[164:167], v[220:223], v[102:105]
	v_mfma_f32_16x16x32_f16 v[98:101], v[204:207], v[220:223], v[98:101]
	v_mfma_f32_16x16x32_f16 v[86:89], v[164:167], v[228:231], v[86:89]
	v_mfma_f32_16x16x32_f16 v[82:85], v[204:207], v[228:231], v[82:85]
	v_mfma_f32_16x16x32_f16 v[70:73], v[164:167], v[236:239], v[70:73]
	v_mfma_f32_16x16x32_f16 v[66:69], v[204:207], v[236:239], v[66:69]
	s_barrier
; #define PG8_STAGE(bufoff, gbase, voff) do { _Pragma("unroll") for (int _i = 0; _i < 2; ++_i) \
;         __builtin_amdgcn_global_load_lds((const unsigned*)((const char*)(gbase) + (voff)[_i]), (LAS unsigned*)(lds + (bufoff) + ldsw + _i * 8192), 16, 0, 0); } while (0)
; #define PG8_LDA(dst, b, h) do { _Pragma("unroll") for (int m = 0; m < 4; ++m) _Pragma("unroll") for (int k = 0; k < 2; ++k) dst[m][k] = *(const LAS h16x8*)(lds + PG8_SA(b, h) + aoff + m * 2048 + k * 1024); } while (0)
; #define PG8_LDB(dst, b, h) do { _Pragma("unroll") for (int n = 0; n < 2; ++n) _Pragma("unroll") for (int k = 0; k < 2; ++k) dst[n][k] = *(const LAS h16x8*)(lds + PG8_SB(b, h) + boff + n * 2048 + k * 1024); } while (0)
; #define PG8_MMA(ai, bj, At, Bt) do { __builtin_amdgcn_s_setprio(1); _Pragma("unroll") for (int m = 0; m < 4; ++m) _Pragma("unroll") for (int n = 0; n < 2; ++n) _Pragma("unroll") for (int k = 0; k < 2; ++k) \
;         acc[ai][bj][m][n] = __builtin_amdgcn_mfma_f32_16x16x32_f16(Bt[n][k], At[m][k], acc[ai][bj][m][n], 0, 0, 0); __builtin_amdgcn_s_setprio(0); } while (0)
; #define PG8_WAIT_V(n) asm volatile("s_waitcnt vmcnt(" #n ")" ::: "memory")
; #define PG8_WAIT_L(n) asm volatile("s_waitcnt lgkmcnt(" #n ")" ::: "memory")
; #define PG8_BAR __builtin_amdgcn_s_barrier()
; #define PG8_SCHED __builtin_amdgcn_sched_barrier(0)
; template <class Epi>
; __device__ __forceinline__ void gemm_phase(LAS unsigned char* lds, const Gemm g, const StaticOrder& S, const Epi& E) {
;     ...
;             PG8_LDA(At, 0, 1); PG8_STAGE(PG8_SB(0, 0), b2, voffB); PG8_STAGE(PG8_SB(0, 1), b2 + hstepB, voffB); PG8_STAGE(PG8_SA(0, 0), a2, voffA);
;             PG8_WAIT_V(8); PG8_WAIT_L(0); PG8_BAR; PG8_MMA(1, 0, At, B0); PG8_MMA(1, 1, At, B1); PG8_BAR; PG8_SCHED;
;             PG8_LDB(B0, 1, 0); PG8_LDB(B1, 1, 1); PG8_SCHED; PG8_LDA(At, 1, 0); PG8_STAGE(PG8_SA(0, 1), a2 + hstepA, voffA);
;             PG8_WAIT_V(8); PG8_WAIT_L(0); PG8_BAR; PG8_MMA(0, 0, At, B0); PG8_MMA(0, 1, At, B1); PG8_BAR; PG8_SCHED;
	s_add_i32 vcc_lo, vcc_lo, s35
	v_lshl_add_u64 v[172:173], s[68:69], 0, v[132:133]
	s_mov_b32 m0, vcc_lo
	ds_read_b128 v[208:211], v190 offset:16384
	ds_read_b128 v[212:215], v190 offset:17408
	ds_read_b128 v[216:219], v190 offset:18432
	ds_read_b128 v[220:223], v190 offset:19456
	ds_read_b128 v[224:227], v190 offset:20480
	ds_read_b128 v[228:231], v190 offset:21504
	ds_read_b128 v[232:235], v190 offset:22528
	ds_read_b128 v[236:239], v190 offset:23552
	global_load_lds_dwordx4 v[172:173], off
	s_add_i32 m0, vcc_lo, 0x2000
	v_lshl_add_u64 v[196:197], s[68:69], 0, v[136:137]
	s_add_u32 s68, s68, s14
	s_addc_u32 s69, s69, 0
	s_add_i32 s31, s31, s35
	global_load_lds_dwordx4 v[196:197], off
	v_lshl_add_u64 v[198:199], s[68:69], 0, v[132:133]
	s_mov_b32 m0, s31
	v_lshl_add_u64 v[240:241], s[68:69], 0, v[136:137]
	global_load_lds_dwordx4 v[198:199], off
	s_add_i32 m0, s31, 0x2000
	v_lshl_add_u64 v[242:243], s[26:27], 0, v[130:131]
	global_load_lds_dwordx4 v[240:241], off
	s_mov_b32 m0, s54
	v_lshl_add_u64 v[244:245], s[26:27], 0, v[134:135]
	global_load_lds_dwordx4 v[242:243], off
	s_mov_b32 m0, s55
	s_nop 0
	global_load_lds_dwordx4 v[244:245], off
	s_waitcnt vmcnt(8)
	s_waitcnt lgkmcnt(0)
	s_barrier
	s_waitcnt lgkmcnt(0)
	v_mfma_f32_16x16x32_f16 v[62:65], v[144:147], v[208:211], v[62:65]
	v_mfma_f32_16x16x32_f16 v[58:61], v[152:155], v[208:211], v[58:61]
	v_mfma_f32_16x16x32_f16 v[46:49], v[144:147], v[216:219], v[46:49]
	v_mfma_f32_16x16x32_f16 v[42:45], v[152:155], v[216:219], v[42:45]
	v_mfma_f32_16x16x32_f16 v[28:31], v[144:147], v[224:227], v[28:31]
	v_mfma_f32_16x16x32_f16 v[24:27], v[152:155], v[224:227], v[24:27]
	v_mfma_f32_16x16x32_f16 v[12:15], v[144:147], v[232:235], v[12:15]
	v_mfma_f32_16x16x32_f16 v[8:11], v[152:155], v[232:235], v[8:11]
	v_mfma_f32_16x16x32_f16 v[62:65], v[148:151], v[212:215], v[62:65]
	v_mfma_f32_16x16x32_f16 v[58:61], v[156:159], v[212:215], v[58:61]
	v_mfma_f32_16x16x32_f16 v[46:49], v[148:151], v[220:223], v[46:49]
	v_mfma_f32_16x16x32_f16 v[42:45], v[156:159], v[220:223], v[42:45]
	v_mfma_f32_16x16x32_f16 v[28:31], v[148:151], v[228:231], v[28:31]
	v_mfma_f32_16x16x32_f16 v[24:27], v[156:159], v[228:231], v[24:27]
	v_mfma_f32_16x16x32_f16 v[12:15], v[148:151], v[236:239], v[12:15]
	v_mfma_f32_16x16x32_f16 v[8:11], v[156:159], v[236:239], v[8:11]
	v_mfma_f32_16x16x32_f16 v[54:57], v[160:163], v[208:211], v[54:57]
	v_mfma_f32_16x16x32_f16 v[50:53], v[168:171], v[208:211], v[50:53]
	v_mfma_f32_16x16x32_f16 v[38:41], v[160:163], v[216:219], v[38:41]
	v_mfma_f32_16x16x32_f16 v[34:37], v[168:171], v[216:219], v[34:37]
	v_mfma_f32_16x16x32_f16 v[20:23], v[160:163], v[224:227], v[20:23]
	v_mfma_f32_16x16x32_f16 v[16:19], v[168:171], v[224:227], v[16:19]
	v_mfma_f32_16x16x32_f16 v[4:7], v[160:163], v[232:235], v[4:7]
	v_mfma_f32_16x16x32_f16 v[0:3], v[168:171], v[232:235], v[0:3]
	v_mfma_f32_16x16x32_f16 v[54:57], v[164:167], v[212:215], v[54:57]
	v_mfma_f32_16x16x32_f16 v[50:53], v[204:207], v[212:215], v[50:53]
	v_mfma_f32_16x16x32_f16 v[38:41], v[164:167], v[220:223], v[38:41]
	v_mfma_f32_16x16x32_f16 v[34:37], v[204:207], v[220:223], v[34:37]
	v_mfma_f32_16x16x32_f16 v[20:23], v[164:167], v[228:231], v[20:23]
	v_mfma_f32_16x16x32_f16 v[16:19], v[204:207], v[228:231], v[16:19]
	v_mfma_f32_16x16x32_f16 v[4:7], v[164:167], v[236:239], v[4:7]
	v_mfma_f32_16x16x32_f16 v[0:3], v[204:207], v[236:239], v[0:3]
	s_barrier
	s_add_i32 s31, 0, 0x18000
	v_add_u32_e32 v32, s31, v174
	s_add_i32 s68, 0, 0x1c000
	ds_read_b128 v[144:147], v32
	ds_read_b128 v[148:151], v32 offset:1024
	ds_read_b128 v[152:155], v32 offset:2048
	ds_read_b128 v[156:159], v32 offset:3072
	v_add_u32_e32 v32, s68, v174
	ds_read_b128 v[160:163], v32
	ds_read_b128 v[164:167], v32 offset:1024
	ds_read_b128 v[168:171], v32 offset:2048
	ds_read_b128 v[204:207], v32 offset:3072
	s_add_u32 s26, s26, s14
	s_addc_u32 s27, s27, 0
	s_mov_b32 m0, s53
	v_lshl_add_u64 v[246:247], s[26:27], 0, v[130:131]
	ds_read_b128 v[208:211], v190 offset:32768
	ds_read_b128 v[212:215], v190 offset:33792
	ds_read_b128 v[216:219], v190 offset:34816
	ds_read_b128 v[220:223], v190 offset:35840
	ds_read_b128 v[224:227], v190 offset:36864
	ds_read_b128 v[228:231], v190 offset:37888
	ds_read_b128 v[232:235], v190 offset:38912
	ds_read_b128 v[236:239], v190 offset:39936
	global_load_lds_dwordx4 v[246:247], off
	v_lshl_add_u64 v[246:247], s[26:27], 0, v[134:135]
	s_mov_b32 m0, s74
	s_nop 0
	global_load_lds_dwordx4 v[246:247], off
	s_waitcnt vmcnt(8)
	s_waitcnt lgkmcnt(0)
	s_barrier
; #define PG8_STAGE(bufoff, gbase, voff) do { _Pragma("unroll") for (int _i = 0; _i < 2; ++_i) \
;         __builtin_amdgcn_global_load_lds((const unsigned*)((const char*)(gbase) + (voff)[_i]), (LAS unsigned*)(lds + (bufoff) + ldsw + _i * 8192), 16, 0, 0); } while (0)
; #define PG8_LDA(dst, b, h) do { _Pragma("unroll") for (int m = 0; m < 4; ++m) _Pragma("unroll") for (int k = 0; k < 2; ++k) dst[m][k] = *(const LAS h16x8*)(lds + PG8_SA(b, h) + aoff + m * 2048 + k * 1024); } while (0)
; #define PG8_MMA(ai, bj, At, Bt) do { __builtin_amdgcn_s_setprio(1); _Pragma("unroll") for (int m = 0; m < 4; ++m) _Pragma("unroll") for (int n = 0; n < 2; ++n) _Pragma("unroll") for (int k = 0; k < 2; ++k) \
;         acc[ai][bj][m][n] = __builtin_amdgcn_mfma_f32_16x16x32_f16(Bt[n][k], At[m][k], acc[ai][bj][m][n], 0, 0, 0); __builtin_amdgcn_s_setprio(0); } while (0)
; #define PG8_WAIT_V(n) asm volatile("s_waitcnt vmcnt(" #n ")" ::: "memory")
; #define PG8_WAIT_L(n) asm volatile("s_waitcnt lgkmcnt(" #n ")" ::: "memory")
; #define PG8_BAR __builtin_amdgcn_s_barrier()
; #define PG8_SCHED __builtin_amdgcn_sched_barrier(0)
; template <class Epi>
; __device__ __forceinline__ void gemm_phase(LAS unsigned char* lds, const Gemm g, const StaticOrder& S, const Epi& E) {
;     ...
;             PG8_WAIT_V(8); PG8_WAIT_L(0); PG8_BAR; PG8_MMA(0, 0, At, B0); PG8_MMA(0, 1, At, B1); PG8_BAR; PG8_SCHED;
;             PG8_LDA(At, 1, 1); PG8_STAGE(PG8_SB(1, 0), b3, voffB); PG8_STAGE(PG8_SB(1, 1), b3 + hstepB, voffB); PG8_STAGE(PG8_SA(1, 0), a3, voffA);
;             PG8_WAIT_V(8); PG8_WAIT_L(0); PG8_BAR; PG8_MMA(1, 0, At, B0); PG8_MMA(1, 1, At, B1); PG8_BAR; PG8_SCHED;
;         }
;         if (wr == 0) PG8_BAR;
	s_waitcnt lgkmcnt(0)
	v_mfma_f32_16x16x32_f16 v[126:129], v[144:147], v[208:211], v[126:129]
	v_mfma_f32_16x16x32_f16 v[122:125], v[152:155], v[208:211], v[122:125]
	v_mfma_f32_16x16x32_f16 v[110:113], v[144:147], v[216:219], v[110:113]
	v_mfma_f32_16x16x32_f16 v[106:109], v[152:155], v[216:219], v[106:109]
	v_mfma_f32_16x16x32_f16 v[94:97], v[144:147], v[224:227], v[94:97]
	v_mfma_f32_16x16x32_f16 v[90:93], v[152:155], v[224:227], v[90:93]
	v_mfma_f32_16x16x32_f16 v[78:81], v[144:147], v[232:235], v[78:81]
	v_mfma_f32_16x16x32_f16 v[74:77], v[152:155], v[232:235], v[74:77]
	v_mfma_f32_16x16x32_f16 v[126:129], v[148:151], v[212:215], v[126:129]
	v_mfma_f32_16x16x32_f16 v[122:125], v[156:159], v[212:215], v[122:125]
	v_mfma_f32_16x16x32_f16 v[110:113], v[148:151], v[220:223], v[110:113]
	v_mfma_f32_16x16x32_f16 v[106:109], v[156:159], v[220:223], v[106:109]
	v_mfma_f32_16x16x32_f16 v[94:97], v[148:151], v[228:231], v[94:97]
	v_mfma_f32_16x16x32_f16 v[90:93], v[156:159], v[228:231], v[90:93]
	v_mfma_f32_16x16x32_f16 v[78:81], v[148:151], v[236:239], v[78:81]
	v_mfma_f32_16x16x32_f16 v[74:77], v[156:159], v[236:239], v[74:77]
	v_mfma_f32_16x16x32_f16 v[118:121], v[160:163], v[208:211], v[118:121]
	v_mfma_f32_16x16x32_f16 v[114:117], v[168:171], v[208:211], v[114:117]
	v_mfma_f32_16x16x32_f16 v[102:105], v[160:163], v[216:219], v[102:105]
	v_mfma_f32_16x16x32_f16 v[98:101], v[168:171], v[216:219], v[98:101]
	v_mfma_f32_16x16x32_f16 v[86:89], v[160:163], v[224:227], v[86:89]
	v_mfma_f32_16x16x32_f16 v[82:85], v[168:171], v[224:227], v[82:85]
	v_mfma_f32_16x16x32_f16 v[70:73], v[160:163], v[232:235], v[70:73]
	v_mfma_f32_16x16x32_f16 v[66:69], v[168:171], v[232:235], v[66:69]
	v_mfma_f32_16x16x32_f16 v[118:121], v[164:167], v[212:215], v[118:121]
	v_mfma_f32_16x16x32_f16 v[114:117], v[204:207], v[212:215], v[114:117]
	v_mfma_f32_16x16x32_f16 v[102:105], v[164:167], v[220:223], v[102:105]
	v_mfma_f32_16x16x32_f16 v[98:101], v[204:207], v[220:223], v[98:101]
	v_mfma_f32_16x16x32_f16 v[86:89], v[164:167], v[228:231], v[86:89]
	v_mfma_f32_16x16x32_f16 v[82:85], v[204:207], v[228:231], v[82:85]
	v_mfma_f32_16x16x32_f16 v[70:73], v[164:167], v[236:239], v[70:73]
	v_mfma_f32_16x16x32_f16 v[66:69], v[204:207], v[236:239], v[66:69]
	s_barrier
	s_add_i32 s26, s31, s35
	v_lshl_add_u64 v[172:173], v[172:173], 0, s[90:91]
	s_mov_b32 m0, s26
	ds_read_b128 v[208:211], v190 offset:49152
	ds_read_b128 v[212:215], v190 offset:50176
	ds_read_b128 v[216:219], v190 offset:51200
	ds_read_b128 v[220:223], v190 offset:52224
	ds_read_b128 v[224:227], v190 offset:53248
	ds_read_b128 v[228:231], v190 offset:54272
	ds_read_b128 v[232:235], v190 offset:55296
	ds_read_b128 v[236:239], v190 offset:56320
	global_load_lds_dwordx4 v[172:173], off
	v_lshl_add_u64 v[172:173], v[196:197], 0, s[90:91]
	s_add_i32 m0, s26, 0x2000
	s_add_i32 s26, s68, s35
	global_load_lds_dwordx4 v[172:173], off
	v_lshl_add_u64 v[172:173], v[198:199], 0, s[90:91]
	s_mov_b32 m0, s26
	s_nop 0
	global_load_lds_dwordx4 v[172:173], off
	v_lshl_add_u64 v[172:173], v[240:241], 0, s[90:91]
	s_add_i32 m0, s26, 0x2000
	s_nop 0
	global_load_lds_dwordx4 v[172:173], off
	v_lshl_add_u64 v[172:173], v[242:243], 0, s[90:91]
	s_mov_b32 m0, s89
	s_nop 0
	global_load_lds_dwordx4 v[172:173], off
	v_lshl_add_u64 v[172:173], v[244:245], 0, s[90:91]
	s_mov_b32 m0, s92
	s_nop 0
	global_load_lds_dwordx4 v[172:173], off
	s_waitcnt vmcnt(8)
	s_waitcnt lgkmcnt(0)
	s_barrier
	s_waitcnt lgkmcnt(0)
	v_mfma_f32_16x16x32_f16 v[62:65], v[144:147], v[208:211], v[62:65]
	v_mfma_f32_16x16x32_f16 v[58:61], v[152:155], v[208:211], v[58:61]
	v_mfma_f32_16x16x32_f16 v[46:49], v[144:147], v[216:219], v[46:49]
	v_mfma_f32_16x16x32_f16 v[42:45], v[152:155], v[216:219], v[42:45]
	v_mfma_f32_16x16x32_f16 v[28:31], v[144:147], v[224:227], v[28:31]
	v_mfma_f32_16x16x32_f16 v[24:27], v[152:155], v[224:227], v[24:27]
	v_mfma_f32_16x16x32_f16 v[12:15], v[144:147], v[232:235], v[12:15]
	v_mfma_f32_16x16x32_f16 v[8:11], v[152:155], v[232:235], v[8:11]
	v_mfma_f32_16x16x32_f16 v[62:65], v[148:151], v[212:215], v[62:65]
	v_mfma_f32_16x16x32_f16 v[58:61], v[156:159], v[212:215], v[58:61]
	v_mfma_f32_16x16x32_f16 v[46:49], v[148:151], v[220:223], v[46:49]
	v_mfma_f32_16x16x32_f16 v[42:45], v[156:159], v[220:223], v[42:45]
	v_mfma_f32_16x16x32_f16 v[28:31], v[148:151], v[228:231], v[28:31]
	v_mfma_f32_16x16x32_f16 v[24:27], v[156:159], v[228:231], v[24:27]
	v_mfma_f32_16x16x32_f16 v[12:15], v[148:151], v[236:239], v[12:15]
	v_mfma_f32_16x16x32_f16 v[8:11], v[156:159], v[236:239], v[8:11]
	v_mfma_f32_16x16x32_f16 v[54:57], v[160:163], v[208:211], v[54:57]
	v_mfma_f32_16x16x32_f16 v[50:53], v[168:171], v[208:211], v[50:53]
	v_mfma_f32_16x16x32_f16 v[38:41], v[160:163], v[216:219], v[38:41]
	v_mfma_f32_16x16x32_f16 v[34:37], v[168:171], v[216:219], v[34:37]
	v_mfma_f32_16x16x32_f16 v[20:23], v[160:163], v[224:227], v[20:23]
	v_mfma_f32_16x16x32_f16 v[16:19], v[168:171], v[224:227], v[16:19]
	v_mfma_f32_16x16x32_f16 v[4:7], v[160:163], v[232:235], v[4:7]
	v_mfma_f32_16x16x32_f16 v[0:3], v[168:171], v[232:235], v[0:3]
	v_mfma_f32_16x16x32_f16 v[54:57], v[164:167], v[212:215], v[54:57]
	v_mfma_f32_16x16x32_f16 v[50:53], v[204:207], v[212:215], v[50:53]
	v_mfma_f32_16x16x32_f16 v[38:41], v[164:167], v[220:223], v[38:41]
	v_mfma_f32_16x16x32_f16 v[34:37], v[204:207], v[220:223], v[34:37]
	v_mfma_f32_16x16x32_f16 v[20:23], v[164:167], v[228:231], v[20:23]
	v_mfma_f32_16x16x32_f16 v[16:19], v[204:207], v[228:231], v[16:19]
	v_mfma_f32_16x16x32_f16 v[4:7], v[164:167], v[236:239], v[4:7]
	v_mfma_f32_16x16x32_f16 v[0:3], v[204:207], v[236:239], v[0:3]
	s_barrier
	s_add_u32 s28, s28, 0x100
	s_addc_u32 s29, s29, 0
	s_add_u32 s22, s22, 0x100
	s_addc_u32 s23, s23, 0
	s_cmp_ge_u32 s30, s88
	s_mov_b32 s26, s30
	s_cbranch_scc0 .LBB0_631
	s_setprio 0
	s_and_b64 vcc, exec, s[18:19]
	s_cbranch_vccz .LBB0_634
	s_barrier

; #define PG8_STAGE(bufoff, gbase, voff) do { _Pragma("unroll") for (int _i = 0; _i < 2; ++_i) \
;         __builtin_amdgcn_global_load_lds((const unsigned*)((const char*)(gbase) + (voff)[_i]), (LAS unsigned*)(lds + (bufoff) + ldsw + _i * 8192), 16, 0, 0); } while (0)
; #define PG8_LDA(dst, b, h) do { _Pragma("unroll") for (int m = 0; m < 4; ++m) _Pragma("unroll") for (int k = 0; k < 2; ++k) dst[m][k] = *(const LAS h16x8*)(lds + PG8_SA(b, h) + aoff + m * 2048 + k * 1024); } while (0)
; #define PG8_LDB(dst, b, h) do { _Pragma("unroll") for (int n = 0; n < 2; ++n) _Pragma("unroll") for (int k = 0; k < 2; ++k) dst[n][k] = *(const LAS h16x8*)(lds + PG8_SB(b, h) + boff + n * 2048 + k * 1024); } while (0)
; #define PG8_MMA(ai, bj, At, Bt) do { __builtin_amdgcn_s_setprio(1); _Pragma("unroll") for (int m = 0; m < 4; ++m) _Pragma("unroll") for (int n = 0; n < 2; ++n) _Pragma("unroll") for (int k = 0; k < 2; ++k) \
;         acc[ai][bj][m][n] = __builtin_amdgcn_mfma_f32_16x16x32_f16(Bt[n][k], At[m][k], acc[ai][bj][m][n], 0, 0, 0); __builtin_amdgcn_s_setprio(0); } while (0)
; #define PG8_WAIT_V(n) asm volatile("s_waitcnt vmcnt(" #n ")" ::: "memory")
; #define PG8_WAIT_L(n) asm volatile("s_waitcnt lgkmcnt(" #n ")" ::: "memory")
; #define PG8_BAR __builtin_amdgcn_s_barrier()
; template <class Epi>
; __device__ __forceinline__ void gemm_phase(LAS unsigned char* lds, const Gemm g, const StaticOrder& S, const Epi& E) {
;     ...
;         for (int t = 0; t < nt; t += 2) {
;             const bool last = (t == nt - 2);
;             const char* a1 = cA + (size_t)(t + 1) * kstep;
;             const char* a2 = last ? nA : cA + (size_t)(t + 2) * kstep; const char* b2 = last ? nB : cB + (size_t)(t + 2) * kstep;
;             const char* a3 = a2 + kstep; const char* b3 = b2 + kstep;
;             PG8_LDB(B0, 0, 0); PG8_LDB(B1, 0, 1); PG8_SCHED; PG8_LDA(At, 0, 0); PG8_STAGE(PG8_SA(1, 1), a1 + hstepA, voffA);
;             PG8_WAIT_V(8); PG8_WAIT_L(0); PG8_BAR; PG8_MMA(0, 0, At, B0); PG8_MMA(0, 1, At, B1); PG8_BAR; PG8_SCHED;
;     ...
; #pragma unroll
;         for (int a = 0; a < 2; ++a)
; #pragma unroll
;             for (int b = 0; b < 2; ++b)
; #pragma unroll
;                 for (int m = 0; m < 4; ++m)
; #pragma unroll
;                     for (int n = 0; n < 2; ++n) acc[a][b][m][n] = (f32x4){0.f, 0.f, 0.f, 0.f};
;         cur = nxt; cA = nA; cB = nB; ++ui;
.LBB0_698:
	s_add_u32 s75, s20, 0x100
	v_mov_b32_e32 v0, 0
	s_addc_u32 s76, s21, 0
	s_mov_b32 s78, -2
	v_mov_b32_e32 v1, v0
	v_mov_b32_e32 v2, v0
	v_mov_b32_e32 v3, v0
	v_mov_b32_e32 v4, v0
	v_mov_b32_e32 v5, v0
	v_mov_b32_e32 v6, v0
	v_mov_b32_e32 v7, v0
	v_mov_b32_e32 v16, v0
	v_mov_b32_e32 v17, v0
	v_mov_b32_e32 v18, v0
	v_mov_b32_e32 v19, v0
	v_mov_b32_e32 v20, v0
	v_mov_b32_e32 v21, v0
	v_mov_b32_e32 v22, v0
	v_mov_b32_e32 v23, v0
	v_mov_b32_e32 v34, v0
	v_mov_b32_e32 v35, v0
	v_mov_b32_e32 v36, v0
	v_mov_b32_e32 v37, v0
	v_mov_b32_e32 v38, v0
	v_mov_b32_e32 v39, v0
	v_mov_b32_e32 v40, v0
	v_mov_b32_e32 v41, v0
	v_mov_b32_e32 v50, v0
	v_mov_b32_e32 v51, v0
	v_mov_b32_e32 v52, v0
	v_mov_b32_e32 v53, v0
	v_mov_b32_e32 v54, v0
	v_mov_b32_e32 v55, v0
	v_mov_b32_e32 v56, v0
	v_mov_b32_e32 v57, v0
	v_mov_b32_e32 v8, v0
	v_mov_b32_e32 v9, v0
	v_mov_b32_e32 v10, v0
	v_mov_b32_e32 v11, v0
	v_mov_b32_e32 v12, v0
	v_mov_b32_e32 v13, v0
	v_mov_b32_e32 v14, v0
	v_mov_b32_e32 v15, v0
	v_mov_b32_e32 v24, v0
	v_mov_b32_e32 v25, v0
	v_mov_b32_e32 v26, v0
	v_mov_b32_e32 v27, v0
	v_mov_b32_e32 v28, v0
	v_mov_b32_e32 v29, v0
	v_mov_b32_e32 v30, v0
	v_mov_b32_e32 v31, v0
	v_mov_b32_e32 v42, v0
	v_mov_b32_e32 v43, v0
	v_mov_b32_e32 v44, v0
	v_mov_b32_e32 v45, v0
	v_mov_b32_e32 v46, v0
	v_mov_b32_e32 v47, v0
	v_mov_b32_e32 v48, v0
	v_mov_b32_e32 v49, v0
	v_mov_b32_e32 v58, v0
	v_mov_b32_e32 v59, v0
	v_mov_b32_e32 v60, v0
	v_mov_b32_e32 v61, v0
	v_mov_b32_e32 v62, v0
	v_mov_b32_e32 v63, v0
	v_mov_b32_e32 v64, v0
	v_mov_b32_e32 v65, v0
	v_mov_b32_e32 v66, v0
	v_mov_b32_e32 v67, v0
	v_mov_b32_e32 v68, v0
	v_mov_b32_e32 v69, v0
	v_mov_b32_e32 v70, v0
	v_mov_b32_e32 v71, v0
	v_mov_b32_e32 v72, v0
	v_mov_b32_e32 v73, v0
	v_mov_b32_e32 v82, v0
	v_mov_b32_e32 v83, v0
	v_mov_b32_e32 v84, v0
	v_mov_b32_e32 v85, v0
	v_mov_b32_e32 v86, v0
	v_mov_b32_e32 v87, v0
	v_mov_b32_e32 v88, v0
	v_mov_b32_e32 v89, v0
	v_mov_b32_e32 v98, v0
	v_mov_b32_e32 v99, v0
	v_mov_b32_e32 v100, v0
	v_mov_b32_e32 v101, v0
	v_mov_b32_e32 v102, v0
	v_mov_b32_e32 v103, v0
	v_mov_b32_e32 v104, v0
	v_mov_b32_e32 v105, v0
	v_mov_b32_e32 v114, v0
	v_mov_b32_e32 v115, v0
	v_mov_b32_e32 v116, v0
	v_mov_b32_e32 v117, v0
	v_mov_b32_e32 v118, v0
	v_mov_b32_e32 v119, v0
	v_mov_b32_e32 v120, v0
	v_mov_b32_e32 v121, v0
	v_mov_b32_e32 v74, v0
	v_mov_b32_e32 v75, v0
	v_mov_b32_e32 v76, v0
	v_mov_b32_e32 v77, v0
	v_mov_b32_e32 v78, v0
	v_mov_b32_e32 v79, v0
	v_mov_b32_e32 v80, v0
	v_mov_b32_e32 v81, v0
	v_mov_b32_e32 v90, v0
	v_mov_b32_e32 v91, v0
	v_mov_b32_e32 v92, v0
	v_mov_b32_e32 v93, v0
	v_mov_b32_e32 v94, v0
	v_mov_b32_e32 v95, v0
	v_mov_b32_e32 v96, v0
	v_mov_b32_e32 v97, v0
	v_mov_b32_e32 v106, v0
	v_mov_b32_e32 v107, v0
	v_mov_b32_e32 v108, v0
	v_mov_b32_e32 v109, v0
	v_mov_b32_e32 v110, v0
	v_mov_b32_e32 v111, v0
	v_mov_b32_e32 v112, v0
	v_mov_b32_e32 v113, v0
	v_mov_b32_e32 v122, v0
	v_mov_b32_e32 v123, v0
	v_mov_b32_e32 v124, v0
	v_mov_b32_e32 v125, v0
	v_mov_b32_e32 v126, v0
	v_mov_b32_e32 v127, v0
	v_mov_b32_e32 v128, v0
	v_mov_b32_e32 v129, v0
	s_cmp_eq_u64 s[14:15], 0
	s_cbranch_scc0 .Lprio_699
	s_setprio 1
.Lprio_699:
.LBB0_699:
	s_add_u32 s20, s18, 0x100
	s_addc_u32 s21, s19, 0
	s_add_i32 s79, 0, 0x10000
	s_cmp_eq_u32 s78, 40
	s_cselect_b32 s27, s1, s21
	s_cselect_b32 s26, s0, s20
	v_add_u32_e32 v32, s79, v172
	s_cselect_b32 s23, s17, s76
	s_cselect_b32 s22, s16, s75
	s_add_i32 s80, 0, 0x14000
	ds_read_b128 v[144:147], v32
	ds_read_b128 v[148:151], v32 offset:1024
	ds_read_b128 v[152:155], v32 offset:2048
	ds_read_b128 v[156:159], v32 offset:3072
	v_add_u32_e32 v32, s80, v172
	ds_read_b128 v[160:163], v32
	ds_read_b128 v[164:167], v32 offset:1024
	ds_read_b128 v[168:171], v32 offset:2048
	ds_read_b128 v[204:207], v32 offset:3072
	v_lshl_add_u64 v[190:191], s[18:19], 0, v[142:143]
	s_add_i32 m0, s28, 0xc000
	ds_read_b128 v[208:211], v179
	ds_read_b128 v[212:215], v179 offset:1024
	ds_read_b128 v[216:219], v179 offset:2048
	ds_read_b128 v[220:223], v179 offset:3072
	ds_read_b128 v[224:227], v179 offset:4096
	ds_read_b128 v[228:231], v179 offset:5120
	ds_read_b128 v[232:235], v179 offset:6144
	ds_read_b128 v[236:239], v179 offset:7168
	global_load_lds_dwordx4 v[190:191], off
	v_lshl_add_u64 v[190:191], s[18:19], 0, v[140:141]
	s_add_i32 m0, s28, 0xe000
	s_nop 0
	global_load_lds_dwordx4 v[190:191], off
	s_waitcnt vmcnt(8)
	s_waitcnt lgkmcnt(0)
	s_barrier
	s_waitcnt lgkmcnt(0)
	v_mfma_f32_16x16x32_f16 v[126:129], v[144:147], v[208:211], v[126:129]
	v_mfma_f32_16x16x32_f16 v[122:125], v[152:155], v[208:211], v[122:125]
	v_mfma_f32_16x16x32_f16 v[110:113], v[144:147], v[216:219], v[110:113]
	v_mfma_f32_16x16x32_f16 v[106:109], v[152:155], v[216:219], v[106:109]
	v_mfma_f32_16x16x32_f16 v[94:97], v[144:147], v[224:227], v[94:97]
	v_mfma_f32_16x16x32_f16 v[90:93], v[152:155], v[224:227], v[90:93]
	v_mfma_f32_16x16x32_f16 v[78:81], v[144:147], v[232:235], v[78:81]
	v_mfma_f32_16x16x32_f16 v[74:77], v[152:155], v[232:235], v[74:77]
	v_mfma_f32_16x16x32_f16 v[126:129], v[148:151], v[212:215], v[126:129]
	v_mfma_f32_16x16x32_f16 v[122:125], v[156:159], v[212:215], v[122:125]
	v_mfma_f32_16x16x32_f16 v[110:113], v[148:151], v[220:223], v[110:113]
	v_mfma_f32_16x16x32_f16 v[106:109], v[156:159], v[220:223], v[106:109]
	v_mfma_f32_16x16x32_f16 v[94:97], v[148:151], v[228:231], v[94:97]
	v_mfma_f32_16x16x32_f16 v[90:93], v[156:159], v[228:231], v[90:93]
	v_mfma_f32_16x16x32_f16 v[78:81], v[148:151], v[236:239], v[78:81]
	v_mfma_f32_16x16x32_f16 v[74:77], v[156:159], v[236:239], v[74:77]
	v_mfma_f32_16x16x32_f16 v[118:121], v[160:163], v[208:211], v[118:121]
	v_mfma_f32_16x16x32_f16 v[114:117], v[168:171], v[208:211], v[114:117]
	v_mfma_f32_16x16x32_f16 v[102:105], v[160:163], v[216:219], v[102:105]
	v_mfma_f32_16x16x32_f16 v[98:101], v[168:171], v[216:219], v[98:101]
	v_mfma_f32_16x16x32_f16 v[86:89], v[160:163], v[224:227], v[86:89]
	v_mfma_f32_16x16x32_f16 v[82:85], v[168:171], v[224:227], v[82:85]
	v_mfma_f32_16x16x32_f16 v[70:73], v[160:163], v[232:235], v[70:73]
	v_mfma_f32_16x16x32_f16 v[66:69], v[168:171], v[232:235], v[66:69]
	v_mfma_f32_16x16x32_f16 v[118:121], v[164:167], v[212:215], v[118:121]
	v_mfma_f32_16x16x32_f16 v[114:117], v[204:207], v[212:215], v[114:117]
	v_mfma_f32_16x16x32_f16 v[102:105], v[164:167], v[220:223], v[102:105]
	v_mfma_f32_16x16x32_f16 v[98:101], v[204:207], v[220:223], v[98:101]
	v_mfma_f32_16x16x32_f16 v[86:89], v[164:167], v[228:231], v[86:89]
	v_mfma_f32_16x16x32_f16 v[82:85], v[204:207], v[228:231], v[82:85]
	v_mfma_f32_16x16x32_f16 v[70:73], v[164:167], v[236:239], v[70:73]
	v_mfma_f32_16x16x32_f16 v[66:69], v[204:207], v[236:239], v[66:69]
	s_barrier
; #define PG8_STAGE(bufoff, gbase, voff) do { _Pragma("unroll") for (int _i = 0; _i < 2; ++_i) \
;         __builtin_amdgcn_global_load_lds((const unsigned*)((const char*)(gbase) + (voff)[_i]), (LAS unsigned*)(lds + (bufoff) + ldsw + _i * 8192), 16, 0, 0); } while (0)
; #define PG8_LDA(dst, b, h) do { _Pragma("unroll") for (int m = 0; m < 4; ++m) _Pragma("unroll") for (int k = 0; k < 2; ++k) dst[m][k] = *(const LAS h16x8*)(lds + PG8_SA(b, h) + aoff + m * 2048 + k * 1024); } while (0)
; #define PG8_LDB(dst, b, h) do { _Pragma("unroll") for (int n = 0; n < 2; ++n) _Pragma("unroll") for (int k = 0; k < 2; ++k) dst[n][k] = *(const LAS h16x8*)(lds + PG8_SB(b, h) + boff + n * 2048 + k * 1024); } while (0)
; #define PG8_MMA(ai, bj, At, Bt) do { __builtin_amdgcn_s_setprio(1); _Pragma("unroll") for (int m = 0; m < 4; ++m) _Pragma("unroll") for (int n = 0; n < 2; ++n) _Pragma("unroll") for (int k = 0; k < 2; ++k) \
;         acc[ai][bj][m][n] = __builtin_amdgcn_mfma_f32_16x16x32_f16(Bt[n][k], At[m][k], acc[ai][bj][m][n], 0, 0, 0); __builtin_amdgcn_s_setprio(0); } while (0)
; #define PG8_WAIT_V(n) asm volatile("s_waitcnt vmcnt(" #n ")" ::: "memory")
; #define PG8_WAIT_L(n) asm volatile("s_waitcnt lgkmcnt(" #n ")" ::: "memory")
; #define PG8_BAR __builtin_amdgcn_s_barrier()
; #define PG8_SCHED __builtin_amdgcn_sched_barrier(0)
; template <class Epi>
; __device__ __forceinline__ void gemm_phase(LAS unsigned char* lds, const Gemm g, const StaticOrder& S, const Epi& E) {
;     ...
;             PG8_LDA(At, 0, 1); PG8_STAGE(PG8_SB(0, 0), b2, voffB); PG8_STAGE(PG8_SB(0, 1), b2 + hstepB, voffB); PG8_STAGE(PG8_SA(0, 0), a2, voffA);
;             PG8_WAIT_V(8); PG8_WAIT_L(0); PG8_BAR; PG8_MMA(1, 0, At, B0); PG8_MMA(1, 1, At, B1); PG8_BAR; PG8_SCHED;
;             PG8_LDB(B0, 1, 0); PG8_LDB(B1, 1, 1); PG8_SCHED; PG8_LDA(At, 1, 0); PG8_STAGE(PG8_SA(0, 1), a2 + hstepA, voffA);
;             PG8_WAIT_V(8); PG8_WAIT_L(0); PG8_BAR; PG8_MMA(0, 0, At, B0); PG8_MMA(0, 1, At, B1); PG8_BAR; PG8_SCHED;
	s_add_i32 s18, s79, s3
	v_lshl_add_u64 v[190:191], s[22:23], 0, v[132:133]
	s_mov_b32 m0, s18
	ds_read_b128 v[208:211], v179 offset:16384
	ds_read_b128 v[212:215], v179 offset:17408
	ds_read_b128 v[216:219], v179 offset:18432
	ds_read_b128 v[220:223], v179 offset:19456
	ds_read_b128 v[224:227], v179 offset:20480
	ds_read_b128 v[228:231], v179 offset:21504
	ds_read_b128 v[232:235], v179 offset:22528
	ds_read_b128 v[236:239], v179 offset:23552
	global_load_lds_dwordx4 v[190:191], off
	s_add_i32 m0, s18, 0x2000
	s_add_u32 s18, s22, 0xb0000
	v_lshl_add_u64 v[196:197], s[22:23], 0, v[136:137]
	s_addc_u32 s19, s23, 0
	s_add_i32 s79, s80, s3
	global_load_lds_dwordx4 v[196:197], off
	v_lshl_add_u64 v[198:199], s[18:19], 0, v[132:133]
	s_mov_b32 m0, s79
	v_lshl_add_u64 v[240:241], s[26:27], 0, v[134:135]
	global_load_lds_dwordx4 v[198:199], off
	v_lshl_add_u64 v[198:199], s[18:19], 0, v[136:137]
	s_add_i32 m0, s79, 0x2000
	s_nop 0
	global_load_lds_dwordx4 v[198:199], off
	v_lshl_add_u64 v[198:199], s[26:27], 0, v[130:131]
	s_mov_b32 m0, s28
	s_nop 0
	global_load_lds_dwordx4 v[198:199], off
	s_mov_b32 m0, s29
	s_nop 0
	global_load_lds_dwordx4 v[240:241], off
	s_waitcnt vmcnt(8)
	s_waitcnt lgkmcnt(0)
	s_barrier
	s_waitcnt lgkmcnt(0)
	v_mfma_f32_16x16x32_f16 v[62:65], v[144:147], v[208:211], v[62:65]
	v_mfma_f32_16x16x32_f16 v[58:61], v[152:155], v[208:211], v[58:61]
	v_mfma_f32_16x16x32_f16 v[46:49], v[144:147], v[216:219], v[46:49]
	v_mfma_f32_16x16x32_f16 v[42:45], v[152:155], v[216:219], v[42:45]
	v_mfma_f32_16x16x32_f16 v[28:31], v[144:147], v[224:227], v[28:31]
	v_mfma_f32_16x16x32_f16 v[24:27], v[152:155], v[224:227], v[24:27]
	v_mfma_f32_16x16x32_f16 v[12:15], v[144:147], v[232:235], v[12:15]
	v_mfma_f32_16x16x32_f16 v[8:11], v[152:155], v[232:235], v[8:11]
	v_mfma_f32_16x16x32_f16 v[62:65], v[148:151], v[212:215], v[62:65]
	v_mfma_f32_16x16x32_f16 v[58:61], v[156:159], v[212:215], v[58:61]
	v_mfma_f32_16x16x32_f16 v[46:49], v[148:151], v[220:223], v[46:49]
	v_mfma_f32_16x16x32_f16 v[42:45], v[156:159], v[220:223], v[42:45]
	v_mfma_f32_16x16x32_f16 v[28:31], v[148:151], v[228:231], v[28:31]
	v_mfma_f32_16x16x32_f16 v[24:27], v[156:159], v[228:231], v[24:27]
	v_mfma_f32_16x16x32_f16 v[12:15], v[148:151], v[236:239], v[12:15]
	v_mfma_f32_16x16x32_f16 v[8:11], v[156:159], v[236:239], v[8:11]
	v_mfma_f32_16x16x32_f16 v[54:57], v[160:163], v[208:211], v[54:57]
	v_mfma_f32_16x16x32_f16 v[50:53], v[168:171], v[208:211], v[50:53]
	v_mfma_f32_16x16x32_f16 v[38:41], v[160:163], v[216:219], v[38:41]
	v_mfma_f32_16x16x32_f16 v[34:37], v[168:171], v[216:219], v[34:37]
	v_mfma_f32_16x16x32_f16 v[20:23], v[160:163], v[224:227], v[20:23]
	v_mfma_f32_16x16x32_f16 v[16:19], v[168:171], v[224:227], v[16:19]
	v_mfma_f32_16x16x32_f16 v[4:7], v[160:163], v[232:235], v[4:7]
	v_mfma_f32_16x16x32_f16 v[0:3], v[168:171], v[232:235], v[0:3]
	v_mfma_f32_16x16x32_f16 v[54:57], v[164:167], v[212:215], v[54:57]
	v_mfma_f32_16x16x32_f16 v[50:53], v[204:207], v[212:215], v[50:53]
	v_mfma_f32_16x16x32_f16 v[38:41], v[164:167], v[220:223], v[38:41]
	v_mfma_f32_16x16x32_f16 v[34:37], v[204:207], v[220:223], v[34:37]
	v_mfma_f32_16x16x32_f16 v[20:23], v[164:167], v[228:231], v[20:23]
	v_mfma_f32_16x16x32_f16 v[16:19], v[204:207], v[228:231], v[16:19]
	v_mfma_f32_16x16x32_f16 v[4:7], v[164:167], v[236:239], v[4:7]
	v_mfma_f32_16x16x32_f16 v[0:3], v[204:207], v[236:239], v[0:3]
	s_barrier
	s_add_i32 s79, 0, 0x18000
	v_add_u32_e32 v32, s79, v172
	s_add_i32 s80, 0, 0x1c000
	ds_read_b128 v[144:147], v32
	ds_read_b128 v[148:151], v32 offset:1024
	ds_read_b128 v[152:155], v32 offset:2048
	ds_read_b128 v[156:159], v32 offset:3072
	v_add_u32_e32 v32, s80, v172
	ds_read_b128 v[160:163], v32
	ds_read_b128 v[164:167], v32 offset:1024
	ds_read_b128 v[168:171], v32 offset:2048
	ds_read_b128 v[204:207], v32 offset:3072
	s_add_u32 s18, s26, 0xb0000
	s_addc_u32 s19, s27, 0
	s_mov_b32 m0, s30
	v_lshl_add_u64 v[242:243], s[18:19], 0, v[130:131]
	ds_read_b128 v[208:211], v179 offset:32768
	ds_read_b128 v[212:215], v179 offset:33792
	ds_read_b128 v[216:219], v179 offset:34816
	ds_read_b128 v[220:223], v179 offset:35840
	ds_read_b128 v[224:227], v179 offset:36864
	ds_read_b128 v[228:231], v179 offset:37888
	ds_read_b128 v[232:235], v179 offset:38912
	ds_read_b128 v[236:239], v179 offset:39936
	global_load_lds_dwordx4 v[242:243], off
	v_lshl_add_u64 v[242:243], s[18:19], 0, v[134:135]
	s_mov_b32 m0, s31
	s_nop 0
	global_load_lds_dwordx4 v[242:243], off
	s_waitcnt vmcnt(8)
	s_waitcnt lgkmcnt(0)
	s_barrier
; #define PG8_STAGE(bufoff, gbase, voff) do { _Pragma("unroll") for (int _i = 0; _i < 2; ++_i) \
;         __builtin_amdgcn_global_load_lds((const unsigned*)((const char*)(gbase) + (voff)[_i]), (LAS unsigned*)(lds + (bufoff) + ldsw + _i * 8192), 16, 0, 0); } while (0)
; #define PG8_LDA(dst, b, h) do { _Pragma("unroll") for (int m = 0; m < 4; ++m) _Pragma("unroll") for (int k = 0; k < 2; ++k) dst[m][k] = *(const LAS h16x8*)(lds + PG8_SA(b, h) + aoff + m * 2048 + k * 1024); } while (0)
; #define PG8_MMA(ai, bj, At, Bt) do { __builtin_amdgcn_s_setprio(1); _Pragma("unroll") for (int m = 0; m < 4; ++m) _Pragma("unroll") for (int n = 0; n < 2; ++n) _Pragma("unroll") for (int k = 0; k < 2; ++k) \
;         acc[ai][bj][m][n] = __builtin_amdgcn_mfma_f32_16x16x32_f16(Bt[n][k], At[m][k], acc[ai][bj][m][n], 0, 0, 0); __builtin_amdgcn_s_setprio(0); } while (0)
; #define PG8_WAIT_V(n) asm volatile("s_waitcnt vmcnt(" #n ")" ::: "memory")
; #define PG8_WAIT_L(n) asm volatile("s_waitcnt lgkmcnt(" #n ")" ::: "memory")
; #define PG8_BAR __builtin_amdgcn_s_barrier()
; #define PG8_SCHED __builtin_amdgcn_sched_barrier(0)
; template <class Epi>
; __device__ __forceinline__ void gemm_phase(LAS unsigned char* lds, const Gemm g, const StaticOrder& S, const Epi& E) {
;     ...
;             PG8_WAIT_V(8); PG8_WAIT_L(0); PG8_BAR; PG8_MMA(0, 0, At, B0); PG8_MMA(0, 1, At, B1); PG8_BAR; PG8_SCHED;
;             PG8_LDA(At, 1, 1); PG8_STAGE(PG8_SB(1, 0), b3, voffB); PG8_STAGE(PG8_SB(1, 1), b3 + hstepB, voffB); PG8_STAGE(PG8_SA(1, 0), a3, voffA);
;             PG8_WAIT_V(8); PG8_WAIT_L(0); PG8_BAR; PG8_MMA(1, 0, At, B0); PG8_MMA(1, 1, At, B1); PG8_BAR; PG8_SCHED;
;         }
;         if (wr == 0) PG8_BAR;
	s_waitcnt lgkmcnt(0)
	v_mfma_f32_16x16x32_f16 v[126:129], v[144:147], v[208:211], v[126:129]
	v_mfma_f32_16x16x32_f16 v[122:125], v[152:155], v[208:211], v[122:125]
	v_mfma_f32_16x16x32_f16 v[110:113], v[144:147], v[216:219], v[110:113]
	v_mfma_f32_16x16x32_f16 v[106:109], v[152:155], v[216:219], v[106:109]
	v_mfma_f32_16x16x32_f16 v[94:97], v[144:147], v[224:227], v[94:97]
	v_mfma_f32_16x16x32_f16 v[90:93], v[152:155], v[224:227], v[90:93]
	v_mfma_f32_16x16x32_f16 v[78:81], v[144:147], v[232:235], v[78:81]
	v_mfma_f32_16x16x32_f16 v[74:77], v[152:155], v[232:235], v[74:77]
	v_mfma_f32_16x16x32_f16 v[126:129], v[148:151], v[212:215], v[126:129]
	v_mfma_f32_16x16x32_f16 v[122:125], v[156:159], v[212:215], v[122:125]
	v_mfma_f32_16x16x32_f16 v[110:113], v[148:151], v[220:223], v[110:113]
	v_mfma_f32_16x16x32_f16 v[106:109], v[156:159], v[220:223], v[106:109]
	v_mfma_f32_16x16x32_f16 v[94:97], v[148:151], v[228:231], v[94:97]
	v_mfma_f32_16x16x32_f16 v[90:93], v[156:159], v[228:231], v[90:93]
	v_mfma_f32_16x16x32_f16 v[78:81], v[148:151], v[236:239], v[78:81]
	v_mfma_f32_16x16x32_f16 v[74:77], v[156:159], v[236:239], v[74:77]
	v_mfma_f32_16x16x32_f16 v[118:121], v[160:163], v[208:211], v[118:121]
	v_mfma_f32_16x16x32_f16 v[114:117], v[168:171], v[208:211], v[114:117]
	v_mfma_f32_16x16x32_f16 v[102:105], v[160:163], v[216:219], v[102:105]
	v_mfma_f32_16x16x32_f16 v[98:101], v[168:171], v[216:219], v[98:101]
	v_mfma_f32_16x16x32_f16 v[86:89], v[160:163], v[224:227], v[86:89]
	v_mfma_f32_16x16x32_f16 v[82:85], v[168:171], v[224:227], v[82:85]
	v_mfma_f32_16x16x32_f16 v[70:73], v[160:163], v[232:235], v[70:73]
	v_mfma_f32_16x16x32_f16 v[66:69], v[168:171], v[232:235], v[66:69]
	v_mfma_f32_16x16x32_f16 v[118:121], v[164:167], v[212:215], v[118:121]
	v_mfma_f32_16x16x32_f16 v[114:117], v[204:207], v[212:215], v[114:117]
	v_mfma_f32_16x16x32_f16 v[102:105], v[164:167], v[220:223], v[102:105]
	v_mfma_f32_16x16x32_f16 v[98:101], v[204:207], v[220:223], v[98:101]
	v_mfma_f32_16x16x32_f16 v[86:89], v[164:167], v[228:231], v[86:89]
	v_mfma_f32_16x16x32_f16 v[82:85], v[204:207], v[228:231], v[82:85]
	v_mfma_f32_16x16x32_f16 v[70:73], v[164:167], v[236:239], v[70:73]
	v_mfma_f32_16x16x32_f16 v[66:69], v[204:207], v[236:239], v[66:69]
	s_barrier
	s_add_i32 s18, s79, s3
	v_lshl_add_u64 v[190:191], v[190:191], 0, s[90:91]
	s_mov_b32 m0, s18
	ds_read_b128 v[208:211], v179 offset:49152
	ds_read_b128 v[212:215], v179 offset:50176
	ds_read_b128 v[216:219], v179 offset:51200
	ds_read_b128 v[220:223], v179 offset:52224
	ds_read_b128 v[224:227], v179 offset:53248
	ds_read_b128 v[228:231], v179 offset:54272
	ds_read_b128 v[232:235], v179 offset:55296
	ds_read_b128 v[236:239], v179 offset:56320
	global_load_lds_dwordx4 v[190:191], off
	s_add_i32 m0, s18, 0x2000
	s_add_u32 s18, s22, 0xb0080
	v_lshl_add_u64 v[190:191], v[196:197], 0, s[90:91]
	s_addc_u32 s19, s23, 0
	s_add_i32 s22, s80, s3
	global_load_lds_dwordx4 v[190:191], off
	v_lshl_add_u64 v[190:191], s[18:19], 0, v[132:133]
	s_mov_b32 m0, s22
	s_nop 0
	global_load_lds_dwordx4 v[190:191], off
	v_lshl_add_u64 v[190:191], s[18:19], 0, v[136:137]
	s_add_i32 m0, s22, 0x2000
	s_nop 0
	global_load_lds_dwordx4 v[190:191], off
	v_lshl_add_u64 v[190:191], v[198:199], 0, s[90:91]
	s_mov_b32 m0, s55
	s_nop 0
	global_load_lds_dwordx4 v[190:191], off
	v_lshl_add_u64 v[190:191], v[240:241], 0, s[90:91]
	s_mov_b32 m0, s68
	s_nop 0
	global_load_lds_dwordx4 v[190:191], off
	s_waitcnt vmcnt(8)
	s_waitcnt lgkmcnt(0)
	s_barrier
	s_waitcnt lgkmcnt(0)
	v_mfma_f32_16x16x32_f16 v[62:65], v[144:147], v[208:211], v[62:65]
	v_mfma_f32_16x16x32_f16 v[58:61], v[152:155], v[208:211], v[58:61]
	v_mfma_f32_16x16x32_f16 v[46:49], v[144:147], v[216:219], v[46:49]
	v_mfma_f32_16x16x32_f16 v[42:45], v[152:155], v[216:219], v[42:45]
	v_mfma_f32_16x16x32_f16 v[28:31], v[144:147], v[224:227], v[28:31]
	v_mfma_f32_16x16x32_f16 v[24:27], v[152:155], v[224:227], v[24:27]
	v_mfma_f32_16x16x32_f16 v[12:15], v[144:147], v[232:235], v[12:15]
	v_mfma_f32_16x16x32_f16 v[8:11], v[152:155], v[232:235], v[8:11]
	v_mfma_f32_16x16x32_f16 v[62:65], v[148:151], v[212:215], v[62:65]
	v_mfma_f32_16x16x32_f16 v[58:61], v[156:159], v[212:215], v[58:61]
	v_mfma_f32_16x16x32_f16 v[46:49], v[148:151], v[220:223], v[46:49]
	v_mfma_f32_16x16x32_f16 v[42:45], v[156:159], v[220:223], v[42:45]
	v_mfma_f32_16x16x32_f16 v[28:31], v[148:151], v[228:231], v[28:31]
	v_mfma_f32_16x16x32_f16 v[24:27], v[156:159], v[228:231], v[24:27]
	v_mfma_f32_16x16x32_f16 v[12:15], v[148:151], v[236:239], v[12:15]
	v_mfma_f32_16x16x32_f16 v[8:11], v[156:159], v[236:239], v[8:11]
	v_mfma_f32_16x16x32_f16 v[54:57], v[160:163], v[208:211], v[54:57]
	v_mfma_f32_16x16x32_f16 v[50:53], v[168:171], v[208:211], v[50:53]
	v_mfma_f32_16x16x32_f16 v[38:41], v[160:163], v[216:219], v[38:41]
	v_mfma_f32_16x16x32_f16 v[34:37], v[168:171], v[216:219], v[34:37]
	v_mfma_f32_16x16x32_f16 v[20:23], v[160:163], v[224:227], v[20:23]
	v_mfma_f32_16x16x32_f16 v[16:19], v[168:171], v[224:227], v[16:19]
	v_mfma_f32_16x16x32_f16 v[4:7], v[160:163], v[232:235], v[4:7]
	v_mfma_f32_16x16x32_f16 v[0:3], v[168:171], v[232:235], v[0:3]
	v_mfma_f32_16x16x32_f16 v[54:57], v[164:167], v[212:215], v[54:57]
	v_mfma_f32_16x16x32_f16 v[50:53], v[204:207], v[212:215], v[50:53]
	v_mfma_f32_16x16x32_f16 v[38:41], v[164:167], v[220:223], v[38:41]
	v_mfma_f32_16x16x32_f16 v[34:37], v[204:207], v[220:223], v[34:37]
	v_mfma_f32_16x16x32_f16 v[20:23], v[164:167], v[228:231], v[20:23]
	v_mfma_f32_16x16x32_f16 v[16:19], v[204:207], v[228:231], v[16:19]
	v_mfma_f32_16x16x32_f16 v[4:7], v[164:167], v[236:239], v[4:7]
	v_mfma_f32_16x16x32_f16 v[0:3], v[204:207], v[236:239], v[0:3]
	s_barrier
	s_add_i32 s78, s78, 2
	s_add_u32 s75, s75, 0x100
	s_addc_u32 s76, s76, 0
	s_cmp_gt_u32 s78, 41
	s_mov_b64 s[18:19], s[20:21]
	s_cbranch_scc0 .LBB0_699
	s_setprio 0
	s_and_b64 vcc, exec, s[14:15]
	s_cbranch_vccz .LBB0_702
	s_barrier

; #define PG8_STAGE(bufoff, gbase, voff) do { _Pragma("unroll") for (int _i = 0; _i < 2; ++_i) \
;         __builtin_amdgcn_global_load_lds((const unsigned*)((const char*)(gbase) + (voff)[_i]), (LAS unsigned*)(lds + (bufoff) + ldsw + _i * 8192), 16, 0, 0); } while (0)
; #define PG8_LDA(dst, b, h) do { _Pragma("unroll") for (int m = 0; m < 4; ++m) _Pragma("unroll") for (int k = 0; k < 2; ++k) dst[m][k] = *(const LAS h16x8*)(lds + PG8_SA(b, h) + aoff + m * 2048 + k * 1024); } while (0)
; #define PG8_LDB(dst, b, h) do { _Pragma("unroll") for (int n = 0; n < 2; ++n) _Pragma("unroll") for (int k = 0; k < 2; ++k) dst[n][k] = *(const LAS h16x8*)(lds + PG8_SB(b, h) + boff + n * 2048 + k * 1024); } while (0)
; #define PG8_MMA(ai, bj, At, Bt) do { __builtin_amdgcn_s_setprio(1); _Pragma("unroll") for (int m = 0; m < 4; ++m) _Pragma("unroll") for (int n = 0; n < 2; ++n) _Pragma("unroll") for (int k = 0; k < 2; ++k) \
;         acc[ai][bj][m][n] = __builtin_amdgcn_mfma_f32_16x16x32_f16(Bt[n][k], At[m][k], acc[ai][bj][m][n], 0, 0, 0); __builtin_amdgcn_s_setprio(0); } while (0)
; #define PG8_BAR __builtin_amdgcn_s_barrier()
; template <class Epi>
; __device__ __forceinline__ void gemm_phase(LAS unsigned char* lds, const Gemm g, const StaticOrder& S, const Epi& E) {
;     ...
;         const char* nA = has_next ? (const char*)g.A + (size_t)nxt.pm * tstepA : cA; const char* nB = has_next ? (const char*)g.Bt + (size_t)nxt.pn * tstepB : cB;
;         for (int t = 0; t < nt; t += 2) {
;             const bool last = (t == nt - 2);
;             const char* a1 = cA + (size_t)(t + 1) * kstep;
;             const char* a2 = last ? nA : cA + (size_t)(t + 2) * kstep; const char* b2 = last ? nB : cB + (size_t)(t + 2) * kstep;
;             const char* a3 = a2 + kstep; const char* b3 = b2 + kstep;
;             PG8_LDB(B0, 0, 0); PG8_LDB(B1, 0, 1); PG8_SCHED; PG8_LDA(At, 0, 0); PG8_STAGE(PG8_SA(1, 1), a1 + hstepA, voffA);
;             PG8_WAIT_V(8); PG8_WAIT_L(0); PG8_BAR; PG8_MMA(0, 0, At, B0); PG8_MMA(0, 1, At, B1); PG8_BAR; PG8_SCHED;
;     ...
; #pragma unroll
;         for (int a = 0; a < 2; ++a)
; #pragma unroll
;             for (int b = 0; b < 2; ++b)
; #pragma unroll
;                 for (int m = 0; m < 4; ++m)
; #pragma unroll
;                     for (int n = 0; n < 2; ++n) acc[a][b][m][n] = (f32x4){0.f, 0.f, 0.f, 0.f};
;         cur = nxt; cA = nA; cB = nB; ++ui;
.LBB0_752:
	s_ashr_i32 s11, s10, 31
	s_lshl_b64 s[12:13], s[10:11], 19
	s_add_u32 s12, s84, s12
	s_addc_u32 s13, s85, s13
	s_and_b64 s[14:15], s[4:5], exec
	s_cselect_b32 s11, s13, s21
	s_cselect_b32 s68, s12, s20
	s_ashr_i32 s9, s8, 31
	s_lshl_b64 s[14:15], s[8:9], 19
	s_add_u32 s14, s24, s14
	s_addc_u32 s15, s26, s15
	s_and_b64 s[22:23], s[4:5], exec
	s_cselect_b32 s9, s15, s19
	s_cselect_b32 s69, s14, s18
	s_add_u32 s70, s18, 0x100
	s_addc_u32 s71, s19, 0
	s_add_u32 s18, s20, 0x40080
	v_mov_b32_e32 v0, 0
	s_addc_u32 s19, s21, 0
	s_mov_b32 s72, -2
	v_mov_b32_e32 v1, v0
	v_mov_b32_e32 v2, v0
	v_mov_b32_e32 v3, v0
	v_mov_b32_e32 v8, v0
	v_mov_b32_e32 v9, v0
	v_mov_b32_e32 v10, v0
	v_mov_b32_e32 v11, v0
	v_mov_b32_e32 v16, v0
	v_mov_b32_e32 v17, v0
	v_mov_b32_e32 v18, v0
	v_mov_b32_e32 v19, v0
	v_mov_b32_e32 v24, v0
	v_mov_b32_e32 v25, v0
	v_mov_b32_e32 v26, v0
	v_mov_b32_e32 v27, v0
	v_mov_b32_e32 v34, v0
	v_mov_b32_e32 v35, v0
	v_mov_b32_e32 v36, v0
	v_mov_b32_e32 v37, v0
	v_mov_b32_e32 v42, v0
	v_mov_b32_e32 v43, v0
	v_mov_b32_e32 v44, v0
	v_mov_b32_e32 v45, v0
	v_mov_b32_e32 v50, v0
	v_mov_b32_e32 v51, v0
	v_mov_b32_e32 v52, v0
	v_mov_b32_e32 v53, v0
	v_mov_b32_e32 v58, v0
	v_mov_b32_e32 v59, v0
	v_mov_b32_e32 v60, v0
	v_mov_b32_e32 v61, v0
	v_mov_b32_e32 v4, v0
	v_mov_b32_e32 v5, v0
	v_mov_b32_e32 v6, v0
	v_mov_b32_e32 v7, v0
	v_mov_b32_e32 v12, v0
	v_mov_b32_e32 v13, v0
	v_mov_b32_e32 v14, v0
	v_mov_b32_e32 v15, v0
	v_mov_b32_e32 v20, v0
	v_mov_b32_e32 v21, v0
	v_mov_b32_e32 v22, v0
	v_mov_b32_e32 v23, v0
	v_mov_b32_e32 v28, v0
	v_mov_b32_e32 v29, v0
	v_mov_b32_e32 v30, v0
	v_mov_b32_e32 v31, v0
	v_mov_b32_e32 v38, v0
	v_mov_b32_e32 v39, v0
	v_mov_b32_e32 v40, v0
	v_mov_b32_e32 v41, v0
	v_mov_b32_e32 v46, v0
	v_mov_b32_e32 v47, v0
	v_mov_b32_e32 v48, v0
	v_mov_b32_e32 v49, v0
	v_mov_b32_e32 v54, v0
	v_mov_b32_e32 v55, v0
	v_mov_b32_e32 v56, v0
	v_mov_b32_e32 v57, v0
	v_mov_b32_e32 v62, v0
	v_mov_b32_e32 v63, v0
	v_mov_b32_e32 v64, v0
	v_mov_b32_e32 v65, v0
	v_mov_b32_e32 v66, v0
	v_mov_b32_e32 v67, v0
	v_mov_b32_e32 v68, v0
	v_mov_b32_e32 v69, v0
	v_mov_b32_e32 v74, v0
	v_mov_b32_e32 v75, v0
	v_mov_b32_e32 v76, v0
	v_mov_b32_e32 v77, v0
	v_mov_b32_e32 v82, v0
	v_mov_b32_e32 v83, v0
	v_mov_b32_e32 v84, v0
	v_mov_b32_e32 v85, v0
	v_mov_b32_e32 v90, v0
	v_mov_b32_e32 v91, v0
	v_mov_b32_e32 v92, v0
	v_mov_b32_e32 v93, v0
	v_mov_b32_e32 v98, v0
	v_mov_b32_e32 v99, v0
	v_mov_b32_e32 v100, v0
	v_mov_b32_e32 v101, v0
	v_mov_b32_e32 v106, v0
	v_mov_b32_e32 v107, v0
	v_mov_b32_e32 v108, v0
	v_mov_b32_e32 v109, v0
	v_mov_b32_e32 v114, v0
	v_mov_b32_e32 v115, v0
	v_mov_b32_e32 v116, v0
	v_mov_b32_e32 v117, v0
	v_mov_b32_e32 v122, v0
	v_mov_b32_e32 v123, v0
	v_mov_b32_e32 v124, v0
	v_mov_b32_e32 v125, v0
	v_mov_b32_e32 v70, v0
	v_mov_b32_e32 v71, v0
	v_mov_b32_e32 v72, v0
	v_mov_b32_e32 v73, v0
	v_mov_b32_e32 v78, v0
	v_mov_b32_e32 v79, v0
	v_mov_b32_e32 v80, v0
	v_mov_b32_e32 v81, v0
	v_mov_b32_e32 v86, v0
	v_mov_b32_e32 v87, v0
	v_mov_b32_e32 v88, v0
	v_mov_b32_e32 v89, v0
	v_mov_b32_e32 v94, v0
	v_mov_b32_e32 v95, v0
	v_mov_b32_e32 v96, v0
	v_mov_b32_e32 v97, v0
	v_mov_b32_e32 v102, v0
	v_mov_b32_e32 v103, v0
	v_mov_b32_e32 v104, v0
	v_mov_b32_e32 v105, v0
	v_mov_b32_e32 v110, v0
	v_mov_b32_e32 v111, v0
	v_mov_b32_e32 v112, v0
	v_mov_b32_e32 v113, v0
	v_mov_b32_e32 v118, v0
	v_mov_b32_e32 v119, v0
	v_mov_b32_e32 v120, v0
	v_mov_b32_e32 v121, v0
	v_mov_b32_e32 v126, v0
	v_mov_b32_e32 v127, v0
	v_mov_b32_e32 v128, v0
	v_mov_b32_e32 v129, v0
	s_cmp_eq_u64 s[6:7], 0
	s_cbranch_scc0 .Lprio_753
	s_setprio 1
.Lprio_753:
.LBB0_753:
	s_add_u32 s20, s18, 0xfffc0080
	s_addc_u32 s21, s19, -1
	s_add_i32 s73, 0, 0x10000
	s_cmp_eq_u32 s72, 12
	s_cselect_b32 s23, s11, s21
	s_cselect_b32 s22, s68, s20
	v_add_u32_e32 v32, s73, v143
	s_cselect_b32 s21, s9, s71
	s_cselect_b32 s20, s69, s70
	s_add_i32 s75, 0, 0x14000
	ds_read_b128 v[146:149], v32
	ds_read_b128 v[150:153], v32 offset:1024
	ds_read_b128 v[154:157], v32 offset:2048
	ds_read_b128 v[158:161], v32 offset:3072
	v_add_u32_e32 v32, s75, v143
	ds_read_b128 v[162:165], v32
	ds_read_b128 v[166:169], v32 offset:1024
	ds_read_b128 v[170:173], v32 offset:2048
	ds_read_b128 v[174:177], v32 offset:3072
	v_lshl_add_u64 v[190:191], s[18:19], 0, v[140:141]
	s_add_i32 m0, s28, 0xc000
	ds_read_b128 v[178:181], v145
	ds_read_b128 v[204:207], v145 offset:1024
	ds_read_b128 v[208:211], v145 offset:2048
	ds_read_b128 v[212:215], v145 offset:3072
	ds_read_b128 v[216:219], v145 offset:4096
	ds_read_b128 v[220:223], v145 offset:5120
	ds_read_b128 v[224:227], v145 offset:6144
	ds_read_b128 v[228:231], v145 offset:7168
	global_load_lds_dwordx4 v[190:191], off
	v_lshl_add_u64 v[190:191], s[18:19], 0, v[138:139]
	s_add_i32 m0, s28, 0xe000
	s_nop 0
	global_load_lds_dwordx4 v[190:191], off
	s_waitcnt vmcnt(8)
	s_waitcnt lgkmcnt(0)
	s_barrier
; #define PG8_STAGE(bufoff, gbase, voff) do { _Pragma("unroll") for (int _i = 0; _i < 2; ++_i) \
;         __builtin_amdgcn_global_load_lds((const unsigned*)((const char*)(gbase) + (voff)[_i]), (LAS unsigned*)(lds + (bufoff) + ldsw + _i * 8192), 16, 0, 0); } while (0)
; #define PG8_LDA(dst, b, h) do { _Pragma("unroll") for (int m = 0; m < 4; ++m) _Pragma("unroll") for (int k = 0; k < 2; ++k) dst[m][k] = *(const LAS h16x8*)(lds + PG8_SA(b, h) + aoff + m * 2048 + k * 1024); } while (0)
; #define PG8_MMA(ai, bj, At, Bt) do { __builtin_amdgcn_s_setprio(1); _Pragma("unroll") for (int m = 0; m < 4; ++m) _Pragma("unroll") for (int n = 0; n < 2; ++n) _Pragma("unroll") for (int k = 0; k < 2; ++k) \
;         acc[ai][bj][m][n] = __builtin_amdgcn_mfma_f32_16x16x32_f16(Bt[n][k], At[m][k], acc[ai][bj][m][n], 0, 0, 0); __builtin_amdgcn_s_setprio(0); } while (0)
; #define PG8_WAIT_V(n) asm volatile("s_waitcnt vmcnt(" #n ")" ::: "memory")
; #define PG8_WAIT_L(n) asm volatile("s_waitcnt lgkmcnt(" #n ")" ::: "memory")
; #define PG8_BAR __builtin_amdgcn_s_barrier()
; #define PG8_SCHED __builtin_amdgcn_sched_barrier(0)
; template <class Epi>
; __device__ __forceinline__ void gemm_phase(LAS unsigned char* lds, const Gemm g, const StaticOrder& S, const Epi& E) {
;     ...
;             PG8_WAIT_V(8); PG8_WAIT_L(0); PG8_BAR; PG8_MMA(0, 0, At, B0); PG8_MMA(0, 1, At, B1); PG8_BAR; PG8_SCHED;
;             PG8_LDA(At, 0, 1); PG8_STAGE(PG8_SB(0, 0), b2, voffB); PG8_STAGE(PG8_SB(0, 1), b2 + hstepB, voffB); PG8_STAGE(PG8_SA(0, 0), a2, voffA);
;             PG8_WAIT_V(8); PG8_WAIT_L(0); PG8_BAR; PG8_MMA(1, 0, At, B0); PG8_MMA(1, 1, At, B1); PG8_BAR; PG8_SCHED;
	s_waitcnt lgkmcnt(0)
	v_mfma_f32_16x16x32_f16 v[126:129], v[146:149], v[178:181], v[126:129]
	v_mfma_f32_16x16x32_f16 v[118:121], v[154:157], v[178:181], v[118:121]
	v_mfma_f32_16x16x32_f16 v[110:113], v[146:149], v[208:211], v[110:113]
	v_mfma_f32_16x16x32_f16 v[102:105], v[154:157], v[208:211], v[102:105]
	v_mfma_f32_16x16x32_f16 v[94:97], v[146:149], v[216:219], v[94:97]
	v_mfma_f32_16x16x32_f16 v[86:89], v[154:157], v[216:219], v[86:89]
	v_mfma_f32_16x16x32_f16 v[78:81], v[146:149], v[224:227], v[78:81]
	v_mfma_f32_16x16x32_f16 v[70:73], v[154:157], v[224:227], v[70:73]
	v_mfma_f32_16x16x32_f16 v[126:129], v[150:153], v[204:207], v[126:129]
	v_mfma_f32_16x16x32_f16 v[118:121], v[158:161], v[204:207], v[118:121]
	v_mfma_f32_16x16x32_f16 v[110:113], v[150:153], v[212:215], v[110:113]
	v_mfma_f32_16x16x32_f16 v[102:105], v[158:161], v[212:215], v[102:105]
	v_mfma_f32_16x16x32_f16 v[94:97], v[150:153], v[220:223], v[94:97]
	v_mfma_f32_16x16x32_f16 v[86:89], v[158:161], v[220:223], v[86:89]
	v_mfma_f32_16x16x32_f16 v[78:81], v[150:153], v[228:231], v[78:81]
	v_mfma_f32_16x16x32_f16 v[70:73], v[158:161], v[228:231], v[70:73]
	v_mfma_f32_16x16x32_f16 v[122:125], v[162:165], v[178:181], v[122:125]
	v_mfma_f32_16x16x32_f16 v[114:117], v[170:173], v[178:181], v[114:117]
	v_mfma_f32_16x16x32_f16 v[106:109], v[162:165], v[208:211], v[106:109]
	v_mfma_f32_16x16x32_f16 v[98:101], v[170:173], v[208:211], v[98:101]
	v_mfma_f32_16x16x32_f16 v[90:93], v[162:165], v[216:219], v[90:93]
	v_mfma_f32_16x16x32_f16 v[82:85], v[170:173], v[216:219], v[82:85]
	v_mfma_f32_16x16x32_f16 v[74:77], v[162:165], v[224:227], v[74:77]
	v_mfma_f32_16x16x32_f16 v[66:69], v[170:173], v[224:227], v[66:69]
	v_mfma_f32_16x16x32_f16 v[122:125], v[166:169], v[204:207], v[122:125]
	v_mfma_f32_16x16x32_f16 v[114:117], v[174:177], v[204:207], v[114:117]
	v_mfma_f32_16x16x32_f16 v[106:109], v[166:169], v[212:215], v[106:109]
	v_mfma_f32_16x16x32_f16 v[98:101], v[174:177], v[212:215], v[98:101]
	v_mfma_f32_16x16x32_f16 v[90:93], v[166:169], v[220:223], v[90:93]
	v_mfma_f32_16x16x32_f16 v[82:85], v[174:177], v[220:223], v[82:85]
	v_mfma_f32_16x16x32_f16 v[74:77], v[166:169], v[228:231], v[74:77]
	v_mfma_f32_16x16x32_f16 v[66:69], v[174:177], v[228:231], v[66:69]
	s_barrier
	s_add_i32 s73, s73, s3
	v_lshl_add_u64 v[190:191], s[20:21], 0, v[134:135]
	s_mov_b32 m0, s73
	ds_read_b128 v[178:181], v145 offset:16384
	ds_read_b128 v[204:207], v145 offset:17408
	ds_read_b128 v[208:211], v145 offset:18432
	ds_read_b128 v[212:215], v145 offset:19456
	ds_read_b128 v[216:219], v145 offset:20480
	ds_read_b128 v[220:223], v145 offset:21504
	ds_read_b128 v[224:227], v145 offset:22528
	ds_read_b128 v[228:231], v145 offset:23552
	global_load_lds_dwordx4 v[190:191], off
	s_add_i32 m0, s73, 0x2000
	s_add_u32 s76, s20, 0x40000
	v_lshl_add_u64 v[196:197], s[20:21], 0, v[130:131]
	s_addc_u32 s77, s21, 0
	s_add_i32 s73, s75, s3
	global_load_lds_dwordx4 v[196:197], off
	v_lshl_add_u64 v[198:199], s[76:77], 0, v[134:135]
	s_mov_b32 m0, s73
	v_lshl_add_u64 v[232:233], s[22:23], 0, v[132:133]
	global_load_lds_dwordx4 v[198:199], off
	v_lshl_add_u64 v[198:199], s[76:77], 0, v[130:131]
	s_add_i32 m0, s73, 0x2000
	s_nop 0
	global_load_lds_dwordx4 v[198:199], off
	v_lshl_add_u64 v[198:199], s[22:23], 0, v[136:137]
	s_mov_b32 m0, s28
	s_nop 0
	global_load_lds_dwordx4 v[198:199], off
	s_mov_b32 m0, s29
	s_nop 0
	global_load_lds_dwordx4 v[232:233], off
	s_waitcnt vmcnt(8)
	s_waitcnt lgkmcnt(0)
	s_barrier
	s_waitcnt lgkmcnt(0)
	v_mfma_f32_16x16x32_f16 v[62:65], v[146:149], v[178:181], v[62:65]
	v_mfma_f32_16x16x32_f16 v[54:57], v[154:157], v[178:181], v[54:57]
	v_mfma_f32_16x16x32_f16 v[46:49], v[146:149], v[208:211], v[46:49]
	v_mfma_f32_16x16x32_f16 v[38:41], v[154:157], v[208:211], v[38:41]
	v_mfma_f32_16x16x32_f16 v[28:31], v[146:149], v[216:219], v[28:31]
	v_mfma_f32_16x16x32_f16 v[20:23], v[154:157], v[216:219], v[20:23]
	v_mfma_f32_16x16x32_f16 v[12:15], v[146:149], v[224:227], v[12:15]
	v_mfma_f32_16x16x32_f16 v[4:7], v[154:157], v[224:227], v[4:7]
	v_mfma_f32_16x16x32_f16 v[62:65], v[150:153], v[204:207], v[62:65]
	v_mfma_f32_16x16x32_f16 v[54:57], v[158:161], v[204:207], v[54:57]
	v_mfma_f32_16x16x32_f16 v[46:49], v[150:153], v[212:215], v[46:49]
	v_mfma_f32_16x16x32_f16 v[38:41], v[158:161], v[212:215], v[38:41]
	v_mfma_f32_16x16x32_f16 v[28:31], v[150:153], v[220:223], v[28:31]
	v_mfma_f32_16x16x32_f16 v[20:23], v[158:161], v[220:223], v[20:23]
	v_mfma_f32_16x16x32_f16 v[12:15], v[150:153], v[228:231], v[12:15]
	v_mfma_f32_16x16x32_f16 v[4:7], v[158:161], v[228:231], v[4:7]
	v_mfma_f32_16x16x32_f16 v[58:61], v[162:165], v[178:181], v[58:61]
	v_mfma_f32_16x16x32_f16 v[50:53], v[170:173], v[178:181], v[50:53]
	v_mfma_f32_16x16x32_f16 v[42:45], v[162:165], v[208:211], v[42:45]
	v_mfma_f32_16x16x32_f16 v[34:37], v[170:173], v[208:211], v[34:37]
	v_mfma_f32_16x16x32_f16 v[24:27], v[162:165], v[216:219], v[24:27]
	v_mfma_f32_16x16x32_f16 v[16:19], v[170:173], v[216:219], v[16:19]
	v_mfma_f32_16x16x32_f16 v[8:11], v[162:165], v[224:227], v[8:11]
	v_mfma_f32_16x16x32_f16 v[0:3], v[170:173], v[224:227], v[0:3]
	v_mfma_f32_16x16x32_f16 v[58:61], v[166:169], v[204:207], v[58:61]
	v_mfma_f32_16x16x32_f16 v[50:53], v[174:177], v[204:207], v[50:53]
	v_mfma_f32_16x16x32_f16 v[42:45], v[166:169], v[212:215], v[42:45]
	v_mfma_f32_16x16x32_f16 v[34:37], v[174:177], v[212:215], v[34:37]
	v_mfma_f32_16x16x32_f16 v[24:27], v[166:169], v[220:223], v[24:27]
	v_mfma_f32_16x16x32_f16 v[16:19], v[174:177], v[220:223], v[16:19]
	v_mfma_f32_16x16x32_f16 v[8:11], v[166:169], v[228:231], v[8:11]
	v_mfma_f32_16x16x32_f16 v[0:3], v[174:177], v[228:231], v[0:3]
	s_barrier
; #define PG8_STAGE(bufoff, gbase, voff) do { _Pragma("unroll") for (int _i = 0; _i < 2; ++_i) \
;         __builtin_amdgcn_global_load_lds((const unsigned*)((const char*)(gbase) + (voff)[_i]), (LAS unsigned*)(lds + (bufoff) + ldsw + _i * 8192), 16, 0, 0); } while (0)
; #define PG8_LDA(dst, b, h) do { _Pragma("unroll") for (int m = 0; m < 4; ++m) _Pragma("unroll") for (int k = 0; k < 2; ++k) dst[m][k] = *(const LAS h16x8*)(lds + PG8_SA(b, h) + aoff + m * 2048 + k * 1024); } while (0)
; #define PG8_LDB(dst, b, h) do { _Pragma("unroll") for (int n = 0; n < 2; ++n) _Pragma("unroll") for (int k = 0; k < 2; ++k) dst[n][k] = *(const LAS h16x8*)(lds + PG8_SB(b, h) + boff + n * 2048 + k * 1024); } while (0)
; #define PG8_MMA(ai, bj, At, Bt) do { __builtin_amdgcn_s_setprio(1); _Pragma("unroll") for (int m = 0; m < 4; ++m) _Pragma("unroll") for (int n = 0; n < 2; ++n) _Pragma("unroll") for (int k = 0; k < 2; ++k) \
;         acc[ai][bj][m][n] = __builtin_amdgcn_mfma_f32_16x16x32_f16(Bt[n][k], At[m][k], acc[ai][bj][m][n], 0, 0, 0); __builtin_amdgcn_s_setprio(0); } while (0)
; #define PG8_WAIT_V(n) asm volatile("s_waitcnt vmcnt(" #n ")" ::: "memory")
; #define PG8_WAIT_L(n) asm volatile("s_waitcnt lgkmcnt(" #n ")" ::: "memory")
; #define PG8_BAR __builtin_amdgcn_s_barrier()
; #define PG8_SCHED __builtin_amdgcn_sched_barrier(0)
; template <class Epi>
; __device__ __forceinline__ void gemm_phase(LAS unsigned char* lds, const Gemm g, const StaticOrder& S, const Epi& E) {
;     ...
;             PG8_LDB(B0, 1, 0); PG8_LDB(B1, 1, 1); PG8_SCHED; PG8_LDA(At, 1, 0); PG8_STAGE(PG8_SA(0, 1), a2 + hstepA, voffA);
;             PG8_WAIT_V(8); PG8_WAIT_L(0); PG8_BAR; PG8_MMA(0, 0, At, B0); PG8_MMA(0, 1, At, B1); PG8_BAR; PG8_SCHED;
	s_add_i32 s73, 0, 0x18000
	v_add_u32_e32 v32, s73, v143
	s_add_i32 s75, 0, 0x1c000
	ds_read_b128 v[146:149], v32
	ds_read_b128 v[150:153], v32 offset:1024
	ds_read_b128 v[154:157], v32 offset:2048
	ds_read_b128 v[158:161], v32 offset:3072
	v_add_u32_e32 v32, s75, v143
	ds_read_b128 v[162:165], v32
	ds_read_b128 v[166:169], v32 offset:1024
	ds_read_b128 v[170:173], v32 offset:2048
	ds_read_b128 v[174:177], v32 offset:3072
	s_add_u32 s22, s22, 0x40000
	s_addc_u32 s23, s23, 0
	s_mov_b32 m0, s30
	v_lshl_add_u64 v[234:235], s[22:23], 0, v[136:137]
	ds_read_b128 v[178:181], v145 offset:32768
	ds_read_b128 v[204:207], v145 offset:33792
	ds_read_b128 v[208:211], v145 offset:34816
	ds_read_b128 v[212:215], v145 offset:35840
	ds_read_b128 v[216:219], v145 offset:36864
	ds_read_b128 v[220:223], v145 offset:37888
	ds_read_b128 v[224:227], v145 offset:38912
	ds_read_b128 v[228:231], v145 offset:39936
	global_load_lds_dwordx4 v[234:235], off
	v_lshl_add_u64 v[234:235], s[22:23], 0, v[132:133]
	s_mov_b32 m0, s31
	s_nop 0
	global_load_lds_dwordx4 v[234:235], off
	s_waitcnt vmcnt(8)
	s_waitcnt lgkmcnt(0)
	s_barrier
	s_waitcnt lgkmcnt(0)
	v_mfma_f32_16x16x32_f16 v[126:129], v[146:149], v[178:181], v[126:129]
	v_mfma_f32_16x16x32_f16 v[118:121], v[154:157], v[178:181], v[118:121]
	v_mfma_f32_16x16x32_f16 v[110:113], v[146:149], v[208:211], v[110:113]
	v_mfma_f32_16x16x32_f16 v[102:105], v[154:157], v[208:211], v[102:105]
	v_mfma_f32_16x16x32_f16 v[94:97], v[146:149], v[216:219], v[94:97]
	v_mfma_f32_16x16x32_f16 v[86:89], v[154:157], v[216:219], v[86:89]
	v_mfma_f32_16x16x32_f16 v[78:81], v[146:149], v[224:227], v[78:81]
	v_mfma_f32_16x16x32_f16 v[70:73], v[154:157], v[224:227], v[70:73]
	v_mfma_f32_16x16x32_f16 v[126:129], v[150:153], v[204:207], v[126:129]
	v_mfma_f32_16x16x32_f16 v[118:121], v[158:161], v[204:207], v[118:121]
	v_mfma_f32_16x16x32_f16 v[110:113], v[150:153], v[212:215], v[110:113]
	v_mfma_f32_16x16x32_f16 v[102:105], v[158:161], v[212:215], v[102:105]
	v_mfma_f32_16x16x32_f16 v[94:97], v[150:153], v[220:223], v[94:97]
	v_mfma_f32_16x16x32_f16 v[86:89], v[158:161], v[220:223], v[86:89]
	v_mfma_f32_16x16x32_f16 v[78:81], v[150:153], v[228:231], v[78:81]
	v_mfma_f32_16x16x32_f16 v[70:73], v[158:161], v[228:231], v[70:73]
	v_mfma_f32_16x16x32_f16 v[122:125], v[162:165], v[178:181], v[122:125]
	v_mfma_f32_16x16x32_f16 v[114:117], v[170:173], v[178:181], v[114:117]
	v_mfma_f32_16x16x32_f16 v[106:109], v[162:165], v[208:211], v[106:109]
	v_mfma_f32_16x16x32_f16 v[98:101], v[170:173], v[208:211], v[98:101]
	v_mfma_f32_16x16x32_f16 v[90:93], v[162:165], v[216:219], v[90:93]
	v_mfma_f32_16x16x32_f16 v[82:85], v[170:173], v[216:219], v[82:85]
	v_mfma_f32_16x16x32_f16 v[74:77], v[162:165], v[224:227], v[74:77]
	v_mfma_f32_16x16x32_f16 v[66:69], v[170:173], v[224:227], v[66:69]
	v_mfma_f32_16x16x32_f16 v[122:125], v[166:169], v[204:207], v[122:125]
	v_mfma_f32_16x16x32_f16 v[114:117], v[174:177], v[204:207], v[114:117]
	v_mfma_f32_16x16x32_f16 v[106:109], v[166:169], v[212:215], v[106:109]
	v_mfma_f32_16x16x32_f16 v[98:101], v[174:177], v[212:215], v[98:101]
	v_mfma_f32_16x16x32_f16 v[90:93], v[166:169], v[220:223], v[90:93]
	v_mfma_f32_16x16x32_f16 v[82:85], v[174:177], v[220:223], v[82:85]
	v_mfma_f32_16x16x32_f16 v[74:77], v[166:169], v[228:231], v[74:77]
	v_mfma_f32_16x16x32_f16 v[66:69], v[174:177], v[228:231], v[66:69]
	s_barrier
; #define PG8_STAGE(bufoff, gbase, voff) do { _Pragma("unroll") for (int _i = 0; _i < 2; ++_i) \
;         __builtin_amdgcn_global_load_lds((const unsigned*)((const char*)(gbase) + (voff)[_i]), (LAS unsigned*)(lds + (bufoff) + ldsw + _i * 8192), 16, 0, 0); } while (0)
; #define PG8_LDA(dst, b, h) do { _Pragma("unroll") for (int m = 0; m < 4; ++m) _Pragma("unroll") for (int k = 0; k < 2; ++k) dst[m][k] = *(const LAS h16x8*)(lds + PG8_SA(b, h) + aoff + m * 2048 + k * 1024); } while (0)
; #define PG8_MMA(ai, bj, At, Bt) do { __builtin_amdgcn_s_setprio(1); _Pragma("unroll") for (int m = 0; m < 4; ++m) _Pragma("unroll") for (int n = 0; n < 2; ++n) _Pragma("unroll") for (int k = 0; k < 2; ++k) \
;         acc[ai][bj][m][n] = __builtin_amdgcn_mfma_f32_16x16x32_f16(Bt[n][k], At[m][k], acc[ai][bj][m][n], 0, 0, 0); __builtin_amdgcn_s_setprio(0); } while (0)
; #define PG8_WAIT_V(n) asm volatile("s_waitcnt vmcnt(" #n ")" ::: "memory")
; #define PG8_WAIT_L(n) asm volatile("s_waitcnt lgkmcnt(" #n ")" ::: "memory")
; #define PG8_BAR __builtin_amdgcn_s_barrier()
; #define PG8_SCHED __builtin_amdgcn_sched_barrier(0)
; template <class Epi>
; __device__ __forceinline__ void gemm_phase(LAS unsigned char* lds, const Gemm g, const StaticOrder& S, const Epi& E) {
;     ...
;             PG8_LDA(At, 1, 1); PG8_STAGE(PG8_SB(1, 0), b3, voffB); PG8_STAGE(PG8_SB(1, 1), b3 + hstepB, voffB); PG8_STAGE(PG8_SA(1, 0), a3, voffA);
;             PG8_WAIT_V(8); PG8_WAIT_L(0); PG8_BAR; PG8_MMA(1, 0, At, B0); PG8_MMA(1, 1, At, B1); PG8_BAR; PG8_SCHED;
;         }
;         if (wr == 0) PG8_BAR;
	s_add_i32 s22, s73, s3
	v_lshl_add_u64 v[190:191], v[190:191], 0, s[90:91]
	s_mov_b32 m0, s22
	ds_read_b128 v[178:181], v145 offset:49152
	ds_read_b128 v[204:207], v145 offset:50176
	ds_read_b128 v[208:211], v145 offset:51200
	ds_read_b128 v[212:215], v145 offset:52224
	ds_read_b128 v[216:219], v145 offset:53248
	ds_read_b128 v[220:223], v145 offset:54272
	ds_read_b128 v[224:227], v145 offset:55296
	ds_read_b128 v[228:231], v145 offset:56320
	global_load_lds_dwordx4 v[190:191], off
	s_add_i32 m0, s22, 0x2000
	s_add_u32 s20, s20, 0x40080
	v_lshl_add_u64 v[190:191], v[196:197], 0, s[90:91]
	s_addc_u32 s21, s21, 0
	s_add_i32 s22, s75, s3
	global_load_lds_dwordx4 v[190:191], off
	v_lshl_add_u64 v[190:191], s[20:21], 0, v[134:135]
	s_mov_b32 m0, s22
	s_nop 0
	global_load_lds_dwordx4 v[190:191], off
	v_lshl_add_u64 v[190:191], s[20:21], 0, v[130:131]
	s_add_i32 m0, s22, 0x2000
	s_nop 0
	global_load_lds_dwordx4 v[190:191], off
	v_lshl_add_u64 v[190:191], v[198:199], 0, s[90:91]
	s_mov_b32 m0, s35
	s_nop 0
	global_load_lds_dwordx4 v[190:191], off
	v_lshl_add_u64 v[190:191], v[232:233], 0, s[90:91]
	s_mov_b32 m0, s54
	s_nop 0
	global_load_lds_dwordx4 v[190:191], off
	s_waitcnt vmcnt(8)
	s_waitcnt lgkmcnt(0)
	s_barrier
	s_waitcnt lgkmcnt(0)
	v_mfma_f32_16x16x32_f16 v[62:65], v[146:149], v[178:181], v[62:65]
	v_mfma_f32_16x16x32_f16 v[54:57], v[154:157], v[178:181], v[54:57]
	v_mfma_f32_16x16x32_f16 v[46:49], v[146:149], v[208:211], v[46:49]
	v_mfma_f32_16x16x32_f16 v[38:41], v[154:157], v[208:211], v[38:41]
	v_mfma_f32_16x16x32_f16 v[28:31], v[146:149], v[216:219], v[28:31]
	v_mfma_f32_16x16x32_f16 v[20:23], v[154:157], v[216:219], v[20:23]
	v_mfma_f32_16x16x32_f16 v[12:15], v[146:149], v[224:227], v[12:15]
	v_mfma_f32_16x16x32_f16 v[4:7], v[154:157], v[224:227], v[4:7]
	v_mfma_f32_16x16x32_f16 v[62:65], v[150:153], v[204:207], v[62:65]
	v_mfma_f32_16x16x32_f16 v[54:57], v[158:161], v[204:207], v[54:57]
	v_mfma_f32_16x16x32_f16 v[46:49], v[150:153], v[212:215], v[46:49]
	v_mfma_f32_16x16x32_f16 v[38:41], v[158:161], v[212:215], v[38:41]
	v_mfma_f32_16x16x32_f16 v[28:31], v[150:153], v[220:223], v[28:31]
	v_mfma_f32_16x16x32_f16 v[20:23], v[158:161], v[220:223], v[20:23]
	v_mfma_f32_16x16x32_f16 v[12:15], v[150:153], v[228:231], v[12:15]
	v_mfma_f32_16x16x32_f16 v[4:7], v[158:161], v[228:231], v[4:7]
	v_mfma_f32_16x16x32_f16 v[58:61], v[162:165], v[178:181], v[58:61]
	v_mfma_f32_16x16x32_f16 v[50:53], v[170:173], v[178:181], v[50:53]
	v_mfma_f32_16x16x32_f16 v[42:45], v[162:165], v[208:211], v[42:45]
	v_mfma_f32_16x16x32_f16 v[34:37], v[170:173], v[208:211], v[34:37]
	v_mfma_f32_16x16x32_f16 v[24:27], v[162:165], v[216:219], v[24:27]
	v_mfma_f32_16x16x32_f16 v[16:19], v[170:173], v[216:219], v[16:19]
	v_mfma_f32_16x16x32_f16 v[8:11], v[162:165], v[224:227], v[8:11]
	v_mfma_f32_16x16x32_f16 v[0:3], v[170:173], v[224:227], v[0:3]
	v_mfma_f32_16x16x32_f16 v[58:61], v[166:169], v[204:207], v[58:61]
	v_mfma_f32_16x16x32_f16 v[50:53], v[174:177], v[204:207], v[50:53]
	v_mfma_f32_16x16x32_f16 v[42:45], v[166:169], v[212:215], v[42:45]
	v_mfma_f32_16x16x32_f16 v[34:37], v[174:177], v[212:215], v[34:37]
	v_mfma_f32_16x16x32_f16 v[24:27], v[166:169], v[220:223], v[24:27]
	v_mfma_f32_16x16x32_f16 v[16:19], v[174:177], v[220:223], v[16:19]
	v_mfma_f32_16x16x32_f16 v[8:11], v[166:169], v[228:231], v[8:11]
	v_mfma_f32_16x16x32_f16 v[0:3], v[174:177], v[228:231], v[0:3]
	s_barrier
	s_add_i32 s72, s72, 2
	s_add_u32 s70, s70, 0x100
	s_addc_u32 s71, s71, 0
	s_add_u32 s18, s18, 0x100
	s_addc_u32 s19, s19, 0
	s_cmp_gt_u32 s72, 13
	s_cbranch_scc0 .LBB0_753
	s_setprio 0
	s_and_b64 vcc, exec, s[6:7]
	s_cbranch_vccz .LBB0_756
	s_barrier

; #define PG8_STAGE(bufoff, gbase, voff) do { _Pragma("unroll") for (int _i = 0; _i < 2; ++_i) \
;         __builtin_amdgcn_global_load_lds((const unsigned*)((const char*)(gbase) + (voff)[_i]), (LAS unsigned*)(lds + (bufoff) + ldsw + _i * 8192), 16, 0, 0); } while (0)
; #define PG8_LDA(dst, b, h) do { _Pragma("unroll") for (int m = 0; m < 4; ++m) _Pragma("unroll") for (int k = 0; k < 2; ++k) dst[m][k] = *(const LAS h16x8*)(lds + PG8_SA(b, h) + aoff + m * 2048 + k * 1024); } while (0)
; #define PG8_LDB(dst, b, h) do { _Pragma("unroll") for (int n = 0; n < 2; ++n) _Pragma("unroll") for (int k = 0; k < 2; ++k) dst[n][k] = *(const LAS h16x8*)(lds + PG8_SB(b, h) + boff + n * 2048 + k * 1024); } while (0)
; #define PG8_MMA(ai, bj, At, Bt) do { __builtin_amdgcn_s_setprio(1); _Pragma("unroll") for (int m = 0; m < 4; ++m) _Pragma("unroll") for (int n = 0; n < 2; ++n) _Pragma("unroll") for (int k = 0; k < 2; ++k) \
;         acc[ai][bj][m][n] = __builtin_amdgcn_mfma_f32_16x16x32_f16(Bt[n][k], At[m][k], acc[ai][bj][m][n], 0, 0, 0); __builtin_amdgcn_s_setprio(0); } while (0)
; #define PG8_WAIT_V(n) asm volatile("s_waitcnt vmcnt(" #n ")" ::: "memory")
; template <class Epi>
; __device__ __forceinline__ void gemm_phase(LAS unsigned char* lds, const Gemm g, const StaticOrder& S, const Epi& E) {
;     ...
; #pragma unroll
;     for (int a = 0; a < 2; ++a)
; #pragma unroll
;         for (int b = 0; b < 2; ++b)
; #pragma unroll
;             for (int m = 0; m < 4; ++m)
; #pragma unroll
;                 for (int n = 0; n < 2; ++n) acc[a][b][m][n] = (f32x4){0.f, 0.f, 0.f, 0.f};
;     ...
;         const bool has_next = S.next(ui + 1, nxt);
;         const char* nA = has_next ? (const char*)g.A + (size_t)nxt.pm * tstepA : cA; const char* nB = has_next ? (const char*)g.Bt + (size_t)nxt.pn * tstepB : cB;
;         for (int t = 0; t < nt; t += 2) {
;             const bool last = (t == nt - 2);
;             const char* a1 = cA + (size_t)(t + 1) * kstep;
;             const char* a2 = last ? nA : cA + (size_t)(t + 2) * kstep; const char* b2 = last ? nB : cB + (size_t)(t + 2) * kstep;
;             const char* a3 = a2 + kstep; const char* b3 = b2 + kstep;
;             PG8_LDB(B0, 0, 0); PG8_LDB(B1, 0, 1); PG8_SCHED; PG8_LDA(At, 0, 0); PG8_STAGE(PG8_SA(1, 1), a1 + hstepA, voffA);
;             PG8_WAIT_V(8); PG8_WAIT_L(0); PG8_BAR; PG8_MMA(0, 0, At, B0); PG8_MMA(0, 1, At, B1); PG8_BAR; PG8_SCHED;
.LBB0_915:
	s_ashr_i32 s19, s18, 31
	s_lshl_b64 s[20:21], s[18:19], 19
	s_add_u32 s20, s84, s20
	s_addc_u32 s21, s85, s21
	s_and_b64 s[22:23], s[6:7], exec
	s_cselect_b32 s19, s21, s31
	s_cselect_b32 s27, s20, s30
	s_ashr_i32 s17, s16, 31
	s_lshl_b64 s[22:23], s[16:17], 19
	s_add_u32 s22, s35, s22
	s_addc_u32 s23, s3, s23
	s_and_b64 s[68:69], s[6:7], exec
	s_cselect_b32 s17, s23, s29
	s_cselect_b32 s94, s22, s28
	s_add_u32 s95, s28, 0x100
	s_addc_u32 s96, s29, 0
	s_add_u32 s28, s30, 0x40080
	v_mov_b32_e32 v0, 0
	s_addc_u32 s29, s31, 0
	s_mov_b32 s97, -2
	v_mov_b32_e32 v1, v0
	v_mov_b32_e32 v2, v0
	v_mov_b32_e32 v3, v0
	v_mov_b32_e32 v4, v0
	v_mov_b32_e32 v5, v0
	v_mov_b32_e32 v6, v0
	v_mov_b32_e32 v7, v0
	v_mov_b32_e32 v16, v0
	v_mov_b32_e32 v17, v0
	v_mov_b32_e32 v18, v0
	v_mov_b32_e32 v19, v0
	v_mov_b32_e32 v20, v0
	v_mov_b32_e32 v21, v0
	v_mov_b32_e32 v22, v0
	v_mov_b32_e32 v23, v0
	v_mov_b32_e32 v34, v0
	v_mov_b32_e32 v35, v0
	v_mov_b32_e32 v36, v0
	v_mov_b32_e32 v37, v0
	v_mov_b32_e32 v38, v0
	v_mov_b32_e32 v39, v0
	v_mov_b32_e32 v40, v0
	v_mov_b32_e32 v41, v0
	v_mov_b32_e32 v50, v0
	v_mov_b32_e32 v51, v0
	v_mov_b32_e32 v52, v0
	v_mov_b32_e32 v53, v0
	v_mov_b32_e32 v54, v0
	v_mov_b32_e32 v55, v0
	v_mov_b32_e32 v56, v0
	v_mov_b32_e32 v57, v0
	v_mov_b32_e32 v8, v0
	v_mov_b32_e32 v9, v0
	v_mov_b32_e32 v10, v0
	v_mov_b32_e32 v11, v0
	v_mov_b32_e32 v12, v0
	v_mov_b32_e32 v13, v0
	v_mov_b32_e32 v14, v0
	v_mov_b32_e32 v15, v0
	v_mov_b32_e32 v24, v0
	v_mov_b32_e32 v25, v0
	v_mov_b32_e32 v26, v0
	v_mov_b32_e32 v27, v0
	v_mov_b32_e32 v28, v0
	v_mov_b32_e32 v29, v0
	v_mov_b32_e32 v30, v0
	v_mov_b32_e32 v31, v0
	v_mov_b32_e32 v42, v0
	v_mov_b32_e32 v43, v0
	v_mov_b32_e32 v44, v0
	v_mov_b32_e32 v45, v0
	v_mov_b32_e32 v46, v0
	v_mov_b32_e32 v47, v0
	v_mov_b32_e32 v48, v0
	v_mov_b32_e32 v49, v0
	v_mov_b32_e32 v58, v0
	v_mov_b32_e32 v59, v0
	v_mov_b32_e32 v60, v0
	v_mov_b32_e32 v61, v0
	v_mov_b32_e32 v62, v0
	v_mov_b32_e32 v63, v0
	v_mov_b32_e32 v64, v0
	v_mov_b32_e32 v65, v0
	v_mov_b32_e32 v66, v0
	v_mov_b32_e32 v67, v0
	v_mov_b32_e32 v68, v0
	v_mov_b32_e32 v69, v0
	v_mov_b32_e32 v70, v0
	v_mov_b32_e32 v71, v0
	v_mov_b32_e32 v72, v0
	v_mov_b32_e32 v73, v0
	v_mov_b32_e32 v82, v0
	v_mov_b32_e32 v83, v0
	v_mov_b32_e32 v84, v0
	v_mov_b32_e32 v85, v0
	v_mov_b32_e32 v86, v0
	v_mov_b32_e32 v87, v0
	v_mov_b32_e32 v88, v0
	v_mov_b32_e32 v89, v0
	v_mov_b32_e32 v98, v0
	v_mov_b32_e32 v99, v0
	v_mov_b32_e32 v100, v0
	v_mov_b32_e32 v101, v0
	v_mov_b32_e32 v102, v0
	v_mov_b32_e32 v103, v0
	v_mov_b32_e32 v104, v0
	v_mov_b32_e32 v105, v0
	v_mov_b32_e32 v114, v0
	v_mov_b32_e32 v115, v0
	v_mov_b32_e32 v116, v0
	v_mov_b32_e32 v117, v0
	v_mov_b32_e32 v118, v0
	v_mov_b32_e32 v119, v0
	v_mov_b32_e32 v120, v0
	v_mov_b32_e32 v121, v0
	v_mov_b32_e32 v74, v0
	v_mov_b32_e32 v75, v0
	v_mov_b32_e32 v76, v0
	v_mov_b32_e32 v77, v0
	v_mov_b32_e32 v78, v0
	v_mov_b32_e32 v79, v0
	v_mov_b32_e32 v80, v0
	v_mov_b32_e32 v81, v0
	v_mov_b32_e32 v90, v0
	v_mov_b32_e32 v91, v0
	v_mov_b32_e32 v92, v0
	v_mov_b32_e32 v93, v0
	v_mov_b32_e32 v94, v0
	v_mov_b32_e32 v95, v0
	v_mov_b32_e32 v96, v0
	v_mov_b32_e32 v97, v0
	v_mov_b32_e32 v106, v0
	v_mov_b32_e32 v107, v0
	v_mov_b32_e32 v108, v0
	v_mov_b32_e32 v109, v0
	v_mov_b32_e32 v110, v0
	v_mov_b32_e32 v111, v0
	v_mov_b32_e32 v112, v0
	v_mov_b32_e32 v113, v0
	v_mov_b32_e32 v122, v0
	v_mov_b32_e32 v123, v0
	v_mov_b32_e32 v124, v0
	v_mov_b32_e32 v125, v0
	v_mov_b32_e32 v126, v0
	v_mov_b32_e32 v127, v0
	v_mov_b32_e32 v128, v0
	v_mov_b32_e32 v129, v0
	s_cmp_eq_u64 s[10:11], 0
	s_cbranch_scc0 .Lprio_916
	s_setprio 1
.Lprio_916:
.LBB0_916:
	s_add_u32 s30, s28, 0xfffc0080
	s_addc_u32 s31, s29, -1
	s_add_i32 vcc_lo, 0, 0x10000
	s_cmp_eq_u32 s97, 12
	s_cselect_b32 s69, s19, s31
	s_cselect_b32 s68, s27, s30
	v_add_u32_e32 v32, vcc_lo, v147
	s_cselect_b32 s31, s17, s96
	s_cselect_b32 s30, s94, s95
	s_add_i32 s0, 0, 0x14000
	ds_read_b128 v[152:155], v32
	ds_read_b128 v[156:159], v32 offset:1024
	ds_read_b128 v[160:163], v32 offset:2048
	ds_read_b128 v[164:167], v32 offset:3072
	v_add_u32_e32 v32, s0, v147
	ds_read_b128 v[168:171], v32
	ds_read_b128 v[172:175], v32 offset:1024
	ds_read_b128 v[176:179], v32 offset:2048
	ds_read_b128 v[204:207], v32 offset:3072
	v_lshl_add_u64 v[144:145], s[28:29], 0, v[142:143]
	s_add_i32 m0, s73, 0xc000
	ds_read_b128 v[208:211], v150
	ds_read_b128 v[212:215], v150 offset:1024
	ds_read_b128 v[216:219], v150 offset:2048
	ds_read_b128 v[220:223], v150 offset:3072
	ds_read_b128 v[224:227], v150 offset:4096
	ds_read_b128 v[228:231], v150 offset:5120
	ds_read_b128 v[232:235], v150 offset:6144
	ds_read_b128 v[236:239], v150 offset:7168
	global_load_lds_dwordx4 v[144:145], off
	v_lshl_add_u64 v[144:145], s[28:29], 0, v[140:141]
	s_add_i32 m0, s73, 0xe000
	s_nop 0
	global_load_lds_dwordx4 v[144:145], off
	s_waitcnt vmcnt(8)
	s_waitcnt lgkmcnt(0)
	s_barrier
; #define PG8_STAGE(bufoff, gbase, voff) do { _Pragma("unroll") for (int _i = 0; _i < 2; ++_i) \
;         __builtin_amdgcn_global_load_lds((const unsigned*)((const char*)(gbase) + (voff)[_i]), (LAS unsigned*)(lds + (bufoff) + ldsw + _i * 8192), 16, 0, 0); } while (0)
; #define PG8_LDA(dst, b, h) do { _Pragma("unroll") for (int m = 0; m < 4; ++m) _Pragma("unroll") for (int k = 0; k < 2; ++k) dst[m][k] = *(const LAS h16x8*)(lds + PG8_SA(b, h) + aoff + m * 2048 + k * 1024); } while (0)
; #define PG8_MMA(ai, bj, At, Bt) do { __builtin_amdgcn_s_setprio(1); _Pragma("unroll") for (int m = 0; m < 4; ++m) _Pragma("unroll") for (int n = 0; n < 2; ++n) _Pragma("unroll") for (int k = 0; k < 2; ++k) \
;         acc[ai][bj][m][n] = __builtin_amdgcn_mfma_f32_16x16x32_f16(Bt[n][k], At[m][k], acc[ai][bj][m][n], 0, 0, 0); __builtin_amdgcn_s_setprio(0); } while (0)
; #define PG8_WAIT_V(n) asm volatile("s_waitcnt vmcnt(" #n ")" ::: "memory")
; #define PG8_WAIT_L(n) asm volatile("s_waitcnt lgkmcnt(" #n ")" ::: "memory")
; #define PG8_BAR __builtin_amdgcn_s_barrier()
; #define PG8_SCHED __builtin_amdgcn_sched_barrier(0)
; template <class Epi>
; __device__ __forceinline__ void gemm_phase(LAS unsigned char* lds, const Gemm g, const StaticOrder& S, const Epi& E) {
;     ...
;             PG8_WAIT_V(8); PG8_WAIT_L(0); PG8_BAR; PG8_MMA(0, 0, At, B0); PG8_MMA(0, 1, At, B1); PG8_BAR; PG8_SCHED;
;             PG8_LDA(At, 0, 1); PG8_STAGE(PG8_SB(0, 0), b2, voffB); PG8_STAGE(PG8_SB(0, 1), b2 + hstepB, voffB); PG8_STAGE(PG8_SA(0, 0), a2, voffA);
;             PG8_WAIT_V(8); PG8_WAIT_L(0); PG8_BAR; PG8_MMA(1, 0, At, B0); PG8_MMA(1, 1, At, B1); PG8_BAR; PG8_SCHED;
	s_waitcnt lgkmcnt(0)
	v_mfma_f32_16x16x32_f16 v[126:129], v[152:155], v[208:211], v[126:129]
	v_mfma_f32_16x16x32_f16 v[122:125], v[160:163], v[208:211], v[122:125]
	v_mfma_f32_16x16x32_f16 v[110:113], v[152:155], v[216:219], v[110:113]
	v_mfma_f32_16x16x32_f16 v[106:109], v[160:163], v[216:219], v[106:109]
	v_mfma_f32_16x16x32_f16 v[94:97], v[152:155], v[224:227], v[94:97]
	v_mfma_f32_16x16x32_f16 v[90:93], v[160:163], v[224:227], v[90:93]
	v_mfma_f32_16x16x32_f16 v[78:81], v[152:155], v[232:235], v[78:81]
	v_mfma_f32_16x16x32_f16 v[74:77], v[160:163], v[232:235], v[74:77]
	v_mfma_f32_16x16x32_f16 v[126:129], v[156:159], v[212:215], v[126:129]
	v_mfma_f32_16x16x32_f16 v[122:125], v[164:167], v[212:215], v[122:125]
	v_mfma_f32_16x16x32_f16 v[110:113], v[156:159], v[220:223], v[110:113]
	v_mfma_f32_16x16x32_f16 v[106:109], v[164:167], v[220:223], v[106:109]
	v_mfma_f32_16x16x32_f16 v[94:97], v[156:159], v[228:231], v[94:97]
	v_mfma_f32_16x16x32_f16 v[90:93], v[164:167], v[228:231], v[90:93]
	v_mfma_f32_16x16x32_f16 v[78:81], v[156:159], v[236:239], v[78:81]
	v_mfma_f32_16x16x32_f16 v[74:77], v[164:167], v[236:239], v[74:77]
	v_mfma_f32_16x16x32_f16 v[118:121], v[168:171], v[208:211], v[118:121]
	v_mfma_f32_16x16x32_f16 v[114:117], v[176:179], v[208:211], v[114:117]
	v_mfma_f32_16x16x32_f16 v[102:105], v[168:171], v[216:219], v[102:105]
	v_mfma_f32_16x16x32_f16 v[98:101], v[176:179], v[216:219], v[98:101]
	v_mfma_f32_16x16x32_f16 v[86:89], v[168:171], v[224:227], v[86:89]
	v_mfma_f32_16x16x32_f16 v[82:85], v[176:179], v[224:227], v[82:85]
	v_mfma_f32_16x16x32_f16 v[70:73], v[168:171], v[232:235], v[70:73]
	v_mfma_f32_16x16x32_f16 v[66:69], v[176:179], v[232:235], v[66:69]
	v_mfma_f32_16x16x32_f16 v[118:121], v[172:175], v[212:215], v[118:121]
	v_mfma_f32_16x16x32_f16 v[114:117], v[204:207], v[212:215], v[114:117]
	v_mfma_f32_16x16x32_f16 v[102:105], v[172:175], v[220:223], v[102:105]
	v_mfma_f32_16x16x32_f16 v[98:101], v[204:207], v[220:223], v[98:101]
	v_mfma_f32_16x16x32_f16 v[86:89], v[172:175], v[228:231], v[86:89]
	v_mfma_f32_16x16x32_f16 v[82:85], v[204:207], v[228:231], v[82:85]
	v_mfma_f32_16x16x32_f16 v[70:73], v[172:175], v[236:239], v[70:73]
	v_mfma_f32_16x16x32_f16 v[66:69], v[204:207], v[236:239], v[66:69]
	s_barrier
	s_add_i32 s1, vcc_lo, s54
	v_lshl_add_u64 v[144:145], s[30:31], 0, v[134:135]
	s_mov_b32 m0, s1
	ds_read_b128 v[208:211], v150 offset:16384
	ds_read_b128 v[212:215], v150 offset:17408
	ds_read_b128 v[216:219], v150 offset:18432
	ds_read_b128 v[220:223], v150 offset:19456
	ds_read_b128 v[224:227], v150 offset:20480
	ds_read_b128 v[228:231], v150 offset:21504
	ds_read_b128 v[232:235], v150 offset:22528
	ds_read_b128 v[236:239], v150 offset:23552
	global_load_lds_dwordx4 v[144:145], off
	s_add_i32 m0, s1, 0x2000
	s_add_u32 vcc_lo, s30, 0x40000
	v_lshl_add_u64 v[180:181], s[30:31], 0, v[130:131]
	s_addc_u32 vcc_hi, s31, 0
	s_add_i32 s0, s0, s54
	global_load_lds_dwordx4 v[180:181], off
	v_lshl_add_u64 v[190:191], vcc, 0, v[134:135]
	s_mov_b32 m0, s0
	v_lshl_add_u64 v[196:197], s[68:69], 0, v[132:133]
	global_load_lds_dwordx4 v[190:191], off
	v_lshl_add_u64 v[190:191], vcc, 0, v[130:131]
	s_add_i32 m0, s0, 0x2000
	s_nop 0
	global_load_lds_dwordx4 v[190:191], off
	v_lshl_add_u64 v[190:191], s[68:69], 0, v[136:137]
	s_mov_b32 m0, s73
	s_nop 0
	global_load_lds_dwordx4 v[190:191], off
	s_mov_b32 m0, s75
	s_nop 0
	global_load_lds_dwordx4 v[196:197], off
	s_waitcnt vmcnt(8)
	s_waitcnt lgkmcnt(0)
	s_barrier
	s_waitcnt lgkmcnt(0)
	v_mfma_f32_16x16x32_f16 v[62:65], v[152:155], v[208:211], v[62:65]
	v_mfma_f32_16x16x32_f16 v[58:61], v[160:163], v[208:211], v[58:61]
	v_mfma_f32_16x16x32_f16 v[46:49], v[152:155], v[216:219], v[46:49]
	v_mfma_f32_16x16x32_f16 v[42:45], v[160:163], v[216:219], v[42:45]
	v_mfma_f32_16x16x32_f16 v[28:31], v[152:155], v[224:227], v[28:31]
	v_mfma_f32_16x16x32_f16 v[24:27], v[160:163], v[224:227], v[24:27]
	v_mfma_f32_16x16x32_f16 v[12:15], v[152:155], v[232:235], v[12:15]
	v_mfma_f32_16x16x32_f16 v[8:11], v[160:163], v[232:235], v[8:11]
	v_mfma_f32_16x16x32_f16 v[62:65], v[156:159], v[212:215], v[62:65]
	v_mfma_f32_16x16x32_f16 v[58:61], v[164:167], v[212:215], v[58:61]
	v_mfma_f32_16x16x32_f16 v[46:49], v[156:159], v[220:223], v[46:49]
	v_mfma_f32_16x16x32_f16 v[42:45], v[164:167], v[220:223], v[42:45]
	v_mfma_f32_16x16x32_f16 v[28:31], v[156:159], v[228:231], v[28:31]
	v_mfma_f32_16x16x32_f16 v[24:27], v[164:167], v[228:231], v[24:27]
	v_mfma_f32_16x16x32_f16 v[12:15], v[156:159], v[236:239], v[12:15]
	v_mfma_f32_16x16x32_f16 v[8:11], v[164:167], v[236:239], v[8:11]
	v_mfma_f32_16x16x32_f16 v[54:57], v[168:171], v[208:211], v[54:57]
	v_mfma_f32_16x16x32_f16 v[50:53], v[176:179], v[208:211], v[50:53]
	v_mfma_f32_16x16x32_f16 v[38:41], v[168:171], v[216:219], v[38:41]
	v_mfma_f32_16x16x32_f16 v[34:37], v[176:179], v[216:219], v[34:37]
	v_mfma_f32_16x16x32_f16 v[20:23], v[168:171], v[224:227], v[20:23]
	v_mfma_f32_16x16x32_f16 v[16:19], v[176:179], v[224:227], v[16:19]
	v_mfma_f32_16x16x32_f16 v[4:7], v[168:171], v[232:235], v[4:7]
	v_mfma_f32_16x16x32_f16 v[0:3], v[176:179], v[232:235], v[0:3]
	v_mfma_f32_16x16x32_f16 v[54:57], v[172:175], v[212:215], v[54:57]
	v_mfma_f32_16x16x32_f16 v[50:53], v[204:207], v[212:215], v[50:53]
	v_mfma_f32_16x16x32_f16 v[38:41], v[172:175], v[220:223], v[38:41]
	v_mfma_f32_16x16x32_f16 v[34:37], v[204:207], v[220:223], v[34:37]
	v_mfma_f32_16x16x32_f16 v[20:23], v[172:175], v[228:231], v[20:23]
	v_mfma_f32_16x16x32_f16 v[16:19], v[204:207], v[228:231], v[16:19]
	v_mfma_f32_16x16x32_f16 v[4:7], v[172:175], v[236:239], v[4:7]
	v_mfma_f32_16x16x32_f16 v[0:3], v[204:207], v[236:239], v[0:3]
	s_barrier
; #define PG8_STAGE(bufoff, gbase, voff) do { _Pragma("unroll") for (int _i = 0; _i < 2; ++_i) \
;         __builtin_amdgcn_global_load_lds((const unsigned*)((const char*)(gbase) + (voff)[_i]), (LAS unsigned*)(lds + (bufoff) + ldsw + _i * 8192), 16, 0, 0); } while (0)
; #define PG8_LDA(dst, b, h) do { _Pragma("unroll") for (int m = 0; m < 4; ++m) _Pragma("unroll") for (int k = 0; k < 2; ++k) dst[m][k] = *(const LAS h16x8*)(lds + PG8_SA(b, h) + aoff + m * 2048 + k * 1024); } while (0)
; #define PG8_LDB(dst, b, h) do { _Pragma("unroll") for (int n = 0; n < 2; ++n) _Pragma("unroll") for (int k = 0; k < 2; ++k) dst[n][k] = *(const LAS h16x8*)(lds + PG8_SB(b, h) + boff + n * 2048 + k * 1024); } while (0)
; #define PG8_MMA(ai, bj, At, Bt) do { __builtin_amdgcn_s_setprio(1); _Pragma("unroll") for (int m = 0; m < 4; ++m) _Pragma("unroll") for (int n = 0; n < 2; ++n) _Pragma("unroll") for (int k = 0; k < 2; ++k) \
;         acc[ai][bj][m][n] = __builtin_amdgcn_mfma_f32_16x16x32_f16(Bt[n][k], At[m][k], acc[ai][bj][m][n], 0, 0, 0); __builtin_amdgcn_s_setprio(0); } while (0)
; #define PG8_WAIT_V(n) asm volatile("s_waitcnt vmcnt(" #n ")" ::: "memory")
; #define PG8_WAIT_L(n) asm volatile("s_waitcnt lgkmcnt(" #n ")" ::: "memory")
; #define PG8_BAR __builtin_amdgcn_s_barrier()
; #define PG8_SCHED __builtin_amdgcn_sched_barrier(0)
; template <class Epi>
; __device__ __forceinline__ void gemm_phase(LAS unsigned char* lds, const Gemm g, const StaticOrder& S, const Epi& E) {
;     ...
;             PG8_LDB(B0, 1, 0); PG8_LDB(B1, 1, 1); PG8_SCHED; PG8_LDA(At, 1, 0); PG8_STAGE(PG8_SA(0, 1), a2 + hstepA, voffA);
;             PG8_WAIT_V(8); PG8_WAIT_L(0); PG8_BAR; PG8_MMA(0, 0, At, B0); PG8_MMA(0, 1, At, B1); PG8_BAR; PG8_SCHED;
;             PG8_LDA(At, 1, 1); PG8_STAGE(PG8_SB(1, 0), b3, voffB); PG8_STAGE(PG8_SB(1, 1), b3 + hstepB, voffB); PG8_STAGE(PG8_SA(1, 0), a3, voffA);
;             PG8_WAIT_V(8); PG8_WAIT_L(0); PG8_BAR; PG8_MMA(1, 0, At, B0); PG8_MMA(1, 1, At, B1); PG8_BAR; PG8_SCHED;
;         }
;         if (wr == 0) PG8_BAR;
	s_add_i32 s0, 0, 0x18000
	v_add_u32_e32 v32, s0, v147
	s_add_i32 s1, 0, 0x1c000
	ds_read_b128 v[152:155], v32
	ds_read_b128 v[156:159], v32 offset:1024
	ds_read_b128 v[160:163], v32 offset:2048
	ds_read_b128 v[164:167], v32 offset:3072
	v_add_u32_e32 v32, s1, v147
	ds_read_b128 v[168:171], v32
	ds_read_b128 v[172:175], v32 offset:1024
	ds_read_b128 v[176:179], v32 offset:2048
	ds_read_b128 v[204:207], v32 offset:3072
	s_add_u32 s68, s68, 0x40000
	s_addc_u32 s69, s69, 0
	s_mov_b32 m0, s76
	v_lshl_add_u64 v[198:199], s[68:69], 0, v[136:137]
	ds_read_b128 v[208:211], v150 offset:32768
	ds_read_b128 v[212:215], v150 offset:33792
	ds_read_b128 v[216:219], v150 offset:34816
	ds_read_b128 v[220:223], v150 offset:35840
	ds_read_b128 v[224:227], v150 offset:36864
	ds_read_b128 v[228:231], v150 offset:37888
	ds_read_b128 v[232:235], v150 offset:38912
	ds_read_b128 v[236:239], v150 offset:39936
	global_load_lds_dwordx4 v[198:199], off
	v_lshl_add_u64 v[198:199], s[68:69], 0, v[132:133]
	s_mov_b32 m0, s77
	s_nop 0
	global_load_lds_dwordx4 v[198:199], off
	s_waitcnt vmcnt(8)
	s_waitcnt lgkmcnt(0)
	s_barrier
	s_waitcnt lgkmcnt(0)
	v_mfma_f32_16x16x32_f16 v[126:129], v[152:155], v[208:211], v[126:129]
	v_mfma_f32_16x16x32_f16 v[122:125], v[160:163], v[208:211], v[122:125]
	v_mfma_f32_16x16x32_f16 v[110:113], v[152:155], v[216:219], v[110:113]
	v_mfma_f32_16x16x32_f16 v[106:109], v[160:163], v[216:219], v[106:109]
	v_mfma_f32_16x16x32_f16 v[94:97], v[152:155], v[224:227], v[94:97]
	v_mfma_f32_16x16x32_f16 v[90:93], v[160:163], v[224:227], v[90:93]
	v_mfma_f32_16x16x32_f16 v[78:81], v[152:155], v[232:235], v[78:81]
	v_mfma_f32_16x16x32_f16 v[74:77], v[160:163], v[232:235], v[74:77]
	v_mfma_f32_16x16x32_f16 v[126:129], v[156:159], v[212:215], v[126:129]
	v_mfma_f32_16x16x32_f16 v[122:125], v[164:167], v[212:215], v[122:125]
	v_mfma_f32_16x16x32_f16 v[110:113], v[156:159], v[220:223], v[110:113]
	v_mfma_f32_16x16x32_f16 v[106:109], v[164:167], v[220:223], v[106:109]
	v_mfma_f32_16x16x32_f16 v[94:97], v[156:159], v[228:231], v[94:97]
	v_mfma_f32_16x16x32_f16 v[90:93], v[164:167], v[228:231], v[90:93]
	v_mfma_f32_16x16x32_f16 v[78:81], v[156:159], v[236:239], v[78:81]
	v_mfma_f32_16x16x32_f16 v[74:77], v[164:167], v[236:239], v[74:77]
	v_mfma_f32_16x16x32_f16 v[118:121], v[168:171], v[208:211], v[118:121]
	v_mfma_f32_16x16x32_f16 v[114:117], v[176:179], v[208:211], v[114:117]
	v_mfma_f32_16x16x32_f16 v[102:105], v[168:171], v[216:219], v[102:105]
	v_mfma_f32_16x16x32_f16 v[98:101], v[176:179], v[216:219], v[98:101]
	v_mfma_f32_16x16x32_f16 v[86:89], v[168:171], v[224:227], v[86:89]
	v_mfma_f32_16x16x32_f16 v[82:85], v[176:179], v[224:227], v[82:85]
	v_mfma_f32_16x16x32_f16 v[70:73], v[168:171], v[232:235], v[70:73]
	v_mfma_f32_16x16x32_f16 v[66:69], v[176:179], v[232:235], v[66:69]
	v_mfma_f32_16x16x32_f16 v[118:121], v[172:175], v[212:215], v[118:121]
	v_mfma_f32_16x16x32_f16 v[114:117], v[204:207], v[212:215], v[114:117]
	v_mfma_f32_16x16x32_f16 v[102:105], v[172:175], v[220:223], v[102:105]
	v_mfma_f32_16x16x32_f16 v[98:101], v[204:207], v[220:223], v[98:101]
	v_mfma_f32_16x16x32_f16 v[86:89], v[172:175], v[228:231], v[86:89]
	v_mfma_f32_16x16x32_f16 v[82:85], v[204:207], v[228:231], v[82:85]
	v_mfma_f32_16x16x32_f16 v[70:73], v[172:175], v[236:239], v[70:73]
	v_mfma_f32_16x16x32_f16 v[66:69], v[204:207], v[236:239], v[66:69]
	s_barrier
	s_add_i32 s0, s0, s54
	v_lshl_add_u64 v[144:145], v[144:145], 0, s[90:91]
	s_mov_b32 m0, s0
	ds_read_b128 v[208:211], v150 offset:49152
	ds_read_b128 v[212:215], v150 offset:50176
	ds_read_b128 v[216:219], v150 offset:51200
	ds_read_b128 v[220:223], v150 offset:52224
	ds_read_b128 v[224:227], v150 offset:53248
	ds_read_b128 v[228:231], v150 offset:54272
	ds_read_b128 v[232:235], v150 offset:55296
	ds_read_b128 v[236:239], v150 offset:56320
	global_load_lds_dwordx4 v[144:145], off
	s_add_i32 m0, s0, 0x2000
	s_add_u32 s30, s30, 0x40080
	v_lshl_add_u64 v[144:145], v[180:181], 0, s[90:91]
	s_addc_u32 s31, s31, 0
	s_add_i32 s0, s1, s54
	global_load_lds_dwordx4 v[144:145], off
	v_lshl_add_u64 v[144:145], s[30:31], 0, v[134:135]
	s_mov_b32 m0, s0
	s_nop 0
	global_load_lds_dwordx4 v[144:145], off
	v_lshl_add_u64 v[144:145], s[30:31], 0, v[130:131]
	s_add_i32 m0, s0, 0x2000
	s_nop 0
	global_load_lds_dwordx4 v[144:145], off
	v_lshl_add_u64 v[144:145], v[190:191], 0, s[90:91]
	s_mov_b32 m0, s81
	s_nop 0
	global_load_lds_dwordx4 v[144:145], off
	v_lshl_add_u64 v[144:145], v[196:197], 0, s[90:91]
	s_mov_b32 m0, s88
	s_nop 0
	global_load_lds_dwordx4 v[144:145], off
	s_waitcnt vmcnt(8)
	s_waitcnt lgkmcnt(0)
	s_barrier
	s_waitcnt lgkmcnt(0)
	v_mfma_f32_16x16x32_f16 v[62:65], v[152:155], v[208:211], v[62:65]
	v_mfma_f32_16x16x32_f16 v[58:61], v[160:163], v[208:211], v[58:61]
	v_mfma_f32_16x16x32_f16 v[46:49], v[152:155], v[216:219], v[46:49]
	v_mfma_f32_16x16x32_f16 v[42:45], v[160:163], v[216:219], v[42:45]
	v_mfma_f32_16x16x32_f16 v[28:31], v[152:155], v[224:227], v[28:31]
	v_mfma_f32_16x16x32_f16 v[24:27], v[160:163], v[224:227], v[24:27]
	v_mfma_f32_16x16x32_f16 v[12:15], v[152:155], v[232:235], v[12:15]
	v_mfma_f32_16x16x32_f16 v[8:11], v[160:163], v[232:235], v[8:11]
	v_mfma_f32_16x16x32_f16 v[62:65], v[156:159], v[212:215], v[62:65]
	v_mfma_f32_16x16x32_f16 v[58:61], v[164:167], v[212:215], v[58:61]
	v_mfma_f32_16x16x32_f16 v[46:49], v[156:159], v[220:223], v[46:49]
	v_mfma_f32_16x16x32_f16 v[42:45], v[164:167], v[220:223], v[42:45]
	v_mfma_f32_16x16x32_f16 v[28:31], v[156:159], v[228:231], v[28:31]
	v_mfma_f32_16x16x32_f16 v[24:27], v[164:167], v[228:231], v[24:27]
	v_mfma_f32_16x16x32_f16 v[12:15], v[156:159], v[236:239], v[12:15]
	v_mfma_f32_16x16x32_f16 v[8:11], v[164:167], v[236:239], v[8:11]
	v_mfma_f32_16x16x32_f16 v[54:57], v[168:171], v[208:211], v[54:57]
	v_mfma_f32_16x16x32_f16 v[50:53], v[176:179], v[208:211], v[50:53]
	v_mfma_f32_16x16x32_f16 v[38:41], v[168:171], v[216:219], v[38:41]
	v_mfma_f32_16x16x32_f16 v[34:37], v[176:179], v[216:219], v[34:37]
	v_mfma_f32_16x16x32_f16 v[20:23], v[168:171], v[224:227], v[20:23]
	v_mfma_f32_16x16x32_f16 v[16:19], v[176:179], v[224:227], v[16:19]
	v_mfma_f32_16x16x32_f16 v[4:7], v[168:171], v[232:235], v[4:7]
	v_mfma_f32_16x16x32_f16 v[0:3], v[176:179], v[232:235], v[0:3]
	v_mfma_f32_16x16x32_f16 v[54:57], v[172:175], v[212:215], v[54:57]
	v_mfma_f32_16x16x32_f16 v[50:53], v[204:207], v[212:215], v[50:53]
	v_mfma_f32_16x16x32_f16 v[38:41], v[172:175], v[220:223], v[38:41]
	v_mfma_f32_16x16x32_f16 v[34:37], v[204:207], v[220:223], v[34:37]
	v_mfma_f32_16x16x32_f16 v[20:23], v[172:175], v[228:231], v[20:23]
	v_mfma_f32_16x16x32_f16 v[16:19], v[204:207], v[228:231], v[16:19]
	v_mfma_f32_16x16x32_f16 v[4:7], v[172:175], v[236:239], v[4:7]
	v_mfma_f32_16x16x32_f16 v[0:3], v[204:207], v[236:239], v[0:3]
	s_barrier
	s_add_i32 s97, s97, 2
	s_add_u32 s95, s95, 0x100
	s_addc_u32 s96, s96, 0
	s_add_u32 s28, s28, 0x100
	s_addc_u32 s29, s29, 0
	s_cmp_gt_u32 s97, 13
	s_cbranch_scc0 .LBB0_916
	s_setprio 0
	s_and_b64 vcc, exec, s[10:11]
	s_cbranch_vccz .LBB0_919
	s_barrier
